# attention A and C steady loops: K/V LDS-DMA source addresses via SGPR base pairs + 32-bit lane offset (SALU adds) instead of five 64-bit VALU pointer adds per two steps; rest as v74
# speedup vs baseline: 1.0052x; 1.0052x over previous
; __device__ __forceinline__ int fresh_tid() { int t = threadIdx.x; asm volatile("" : "+v"(t)); return t; }
; #define WAIT_BAR(N) asm volatile("s_waitcnt vmcnt(" #N ") lgkmcnt(0)\n\ts_barrier":::"memory")
;   #define DMA_K(t,slot) glds16(ksrc+(long)(t)*KVBLK*PK,(unsigned)__builtin_amdgcn_readfirstlane(kdst+(slot)))
;   #define CMASK(P0,P1,t) do{}while(0)
; template<int THRL,bool FIXREF,bool HALFK> __device__ __forceinline__ void attn_unit(float mref,long rowbase,int q0,const bf16*Qh,int PQ,const bf16*__restrict__ Kh_,int PK,const bf16*__restrict__ Vh_,int PV,bf16*Oh,int PO,const bf16*Gh,int PG,u32x4(&okeep)[4],int omode,float lam,float oml,const float ...
;   const int tid=fresh_tid(),lane=tid&63,r32=lane&31,hi=lane>>5; const int wid=__builtin_amdgcn_readfirstlane(tid>>6);
;   const bf16*Qw=Qh+(rowbase+q0+wid*QBLK)*PQ;
;   const bf16*Kh=Kh_+rowbase*PK,*Vh=Vh_+rowbase*PV;
;   const unsigned lds0=(unsigned)(uintptr_t)shm;
;   float*wsf=(float*)(shm+LDS_WS)+wid*64;
;   const bf16*ksrc=Kh+(long)lane*PK+wid*8;
;   const bf16*vsrc=Vh+(long)(16*(wid&3)+(lane>>2))*PV+(wid>>2)*32+(lane&3)*8;
;   const unsigned kdst=lds0+LDS_K+wid*1024, vdst=lds0+LDS_V+wid*1024;
;     ...
;   const int vb0=(int)(lds0+LDS_V)+((lane>>4)&1)*32+(lane&3)*8+(4*hi+((lane&15)>>2))*64;
;   const char*Kbase=shm+LDS_K; bf16x8 kf[8];
;   const lds_cptr shm3=(lds_cptr)shm; const lds_cptr kp0=shm3+LDS_K+hi*1024+r32*16; const lds_cptr vp0=shm3+LDS_V+((lane>>4)&1)*32+(lane&3)*8+(4*hi+((lane&15)>>2))*64;
;   constexpr int NT=SEQ/KVBLK;
;   if(Gh){ const bf16*Gw=Gh+(rowbase+q0+wid*QBLK)*PG;
;     #pragma unroll
;     for(int i=0;i<4;++i) glds16(Gw+(long)(i*8+(lane>>3))*PG+(lane&7)*8,(unsigned)__builtin_amdgcn_readfirstlane(lds0+LDS_GST+wid*4096+i*1024)); }
;   DMA_K(0,0);DMA_V(0,0);DMA_K(1,SLOTB);
;   bf16x8 qr[4];
;   #pragma unroll
;   for(int d0=0;d0<4;++d0)qr[d0]=*reinterpret_cast<const bf16x8*>(&Qw[(long)r32*PQ+d0*16+hi*8]);
;   float mhat=0.f,l_reg=0.f;f32x16 o[2];o[0]=f32x16{};o[1]=f32x16{};f32x16 negm=f32x16{};
;   if constexpr(FIXREF){ mhat=mref; _Pragma("unroll") for(int r=0;r<16;++r)negm[r]=-mref; }
;   asm volatile("":"+v"(negm));
;     ...
;   bool resc=false;
;     ...
;   f32x16 pA0,pA1,pB0,pB1;
;   int sl_prev=0,sl_cur=0,sl_next=SLOTB;
;     ...
;   DMA_K(2,2*SLOTB);
;   WAIT_BAR(3);
;   qkt<HALFK?2:4>(pA0,pA1,Kbase,qr,negm,r32,hi);asm volatile("s_nop 15\n\ts_nop 7":"+v"(pA0),"+v"(pA1));CMASK(pA0,pA1,0);
.LBB0_450:
	s_bfe_u32 s16, s58, 0x20004
	s_lshl_b32 s59, s16, 6
	s_and_b32 s67, s59, 0x80
	s_ashr_i32 s42, s58, 6
	s_lshl_b32 s16, s16, 7
	s_add_u32 s46, s2, s16
	s_addc_u32 s47, s3, 0
	s_lshl_b32 s17, s58, 2
	s_and_b32 s17, s17, 0x80
	s_add_u32 s60, s14, s17
	s_addc_u32 s61, s15, 0
	s_add_u32 s62, s20, s17
	s_addc_u32 s63, s28, 0
	s_add_u32 s65, s34, s16
	v_mov_b32_e32 v104, v218
	s_addc_u32 s66, s35, 0
	s_ashr_i32 s43, s42, 31
	s_lshl_b32 s40, s58, 8
	s_lshl_b64 s[16:17], s[42:43], 12
	v_readfirstlane_b32 s64, v104
	s_and_b32 s40, s40, 0xf00
	s_ashr_i32 s73, s64, 6
	s_or_b32 s16, s16, s40
	s_lshl_b32 s40, s73, 5
	s_ashr_i32 s41, s40, 31
	s_add_u32 s16, s16, s40
	s_addc_u32 s17, s17, s41
	s_lshl_b64 s[40:41], s[16:17], 9
	s_add_u32 s48, s46, s40
	s_addc_u32 s49, s47, s41
	s_lshl_b64 s[40:41], s[42:43], 20
	s_add_u32 s46, s60, s40
	s_addc_u32 s47, s61, s41
	s_mul_i32 s69, s42, 0x1e00000
	s_mul_hi_i32 s68, s42, 0x1e00000
	s_add_u32 s60, s62, s69
	v_and_b32_e32 v205, 63, v104
	s_addc_u32 s61, s63, s68
	s_lshl_b32 s42, s73, 3
	v_lshlrev_b32_e32 v0, 8, v205
	s_ashr_i32 s43, s42, 31
	v_lshl_add_u64 v[18:19], s[46:47], 0, v[0:1]
	s_lshl_b64 s[42:43], s[42:43], 1
	v_lshl_add_u64 v[210:211], v[18:19], 0, s[42:43]
	s_lshl_b32 s46, s73, 4
	v_bfe_u32 v18, v104, 2, 4
	v_and_or_b32 v18, s46, 48, v18
	s_ashr_i32 s46, s64, 3
	s_andn2_b32 s46, s46, 31
	s_ashr_i32 s47, s46, 31
	s_lshl_b64 s[46:47], s[46:47], 1
	s_lshl_b32 s63, s73, 10
	v_mul_u32_u24_e32 v18, 0xf00, v18
	s_cmp_lg_u32 0, -1
	v_lshlrev_b32_e32 v102, 1, v18
	v_mov_b32_e32 v103, v1
	s_cselect_b32 s75, 0, 0
	v_lshl_add_u64 v[18:19], s[60:61], 0, v[102:103]
	v_lshlrev_b32_e32 v22, 3, v104
	s_add_i32 s62, s63, s75
	s_mul_i32 s60, s17, 0x1e00
	s_mul_hi_u32 s70, s16, 0x1e00
	v_and_b32_e32 v229, 24, v22
	s_add_i32 s61, s62, 0x6000
	s_add_i32 s60, s70, s60
	s_mul_i32 s70, s16, 0x1e00
	v_lshl_add_u64 v[18:19], v[18:19], 0, s[46:47]
	v_lshlrev_b32_e32 v20, 1, v229
	v_mov_b32_e32 v21, v1
	s_add_u32 s70, s65, s70
	v_bfe_u32 v203, v104, 3, 3
	v_and_b32_e32 v206, 56, v22
	v_lshl_add_u64 v[208:209], v[18:19], 0, v[20:21]
	s_addc_u32 s71, s66, s60
	v_lshlrev_b32_e32 v18, 1, v206
	v_mov_b32_e32 v19, v1
	s_lshl_b32 s60, s73, 12
	v_mul_u32_u24_e32 v20, 0xf00, v203
	v_lshl_add_u64 v[18:19], s[70:71], 0, v[18:19]
	v_lshlrev_b32_e32 v20, 1, v20
	s_add_i32 s65, s75, s60
	v_lshl_add_u64 v[18:19], v[18:19], 0, v[20:21]
	s_add_i32 s66, s65, 0x14800
	s_mov_b32 s70, m0
	s_mov_b32 m0, s66
	s_nop 0
	global_load_lds_dwordx4 v[18:19], off
	s_mov_b32 m0, s70
	v_lshl_add_u64 v[20:21], v[18:19], 0, s[30:31]
	s_add_i32 s66, s65, 0x14c00
	s_mov_b32 s70, m0
	s_mov_b32 m0, s66
	s_nop 0
	global_load_lds_dwordx4 v[20:21], off
	s_mov_b32 m0, s70
	v_lshl_add_u64 v[20:21], v[18:19], 0, s[56:57]
	s_add_i32 s66, s65, 0x15000
	s_mov_b32 s70, m0
	s_mov_b32 m0, s66
	s_nop 0
	global_load_lds_dwordx4 v[20:21], off
	s_mov_b32 m0, s70
	v_lshl_add_u64 v[18:19], v[18:19], 0, s[8:9]
	s_add_i32 s65, s65, 0x15400
	s_mov_b32 s66, m0
	s_mov_b32 m0, s65
	s_nop 0
	global_load_lds_dwordx4 v[18:19], off
	s_mov_b32 m0, s66
	s_mov_b32 s65, m0
	s_mov_b32 m0, s62
	s_nop 0
	global_load_lds_dwordx4 v[210:211], off
	s_mov_b32 m0, s65
	s_mov_b64 s[70:71], 0x4000
	v_and_b32_e32 v216, 31, v104
	s_mov_b32 s65, m0
	s_mov_b32 m0, s61
	s_nop 0
	global_load_lds_dwordx4 v[208:209], off
	s_mov_b32 m0, s65
	v_lshl_add_u64 v[18:19], v[210:211], 0, s[70:71]
	v_bfe_u32 v217, v104, 5, 1
	s_add_i32 s65, s62, 0x2000
	s_mov_b32 s66, m0
	s_mov_b32 m0, s65
	s_nop 0
	global_load_lds_dwordx4 v[18:19], off
	s_mov_b32 m0, s66
	v_lshlrev_b32_e32 v18, 9, v216
	v_lshl_or_b32 v18, v217, 4, v18
	global_load_dwordx4 v[174:177], v18, s[48:49]
	global_load_dwordx4 v[170:173], v18, s[48:49] offset:32
	global_load_dwordx4 v[162:165], v18, s[48:49] offset:64
	global_load_dwordx4 v[154:157], v18, s[48:49] offset:96
	v_mov_b64_e32 v[64:65], v[16:17]
	v_lshlrev_b32_e32 v18, 10, v217
	v_lshlrev_b32_e32 v19, 4, v216
	v_mov_b64_e32 v[62:63], v[14:15]
	v_mov_b64_e32 v[60:61], v[12:13]
	v_mov_b64_e32 v[58:59], v[10:11]
	v_mov_b64_e32 v[56:57], v[8:9]
	v_mov_b64_e32 v[54:55], v[6:7]
	v_mov_b64_e32 v[52:53], v[4:5]
	v_mov_b64_e32 v[50:51], v[2:3]
	v_add3_u32 v228, 0, v18, v19
	v_lshl_add_u64 v[18:19], v[210:211], 0, s[10:11]
	s_add_i32 s48, s62, 0x4000
	s_mov_b32 s49, m0
	s_mov_b32 m0, s48
	s_nop 0
	global_load_lds_dwordx4 v[18:19], off
	s_mov_b32 m0, s49
	s_waitcnt vmcnt(3) lgkmcnt(0)
	s_barrier
	ds_read_b128 v[18:21], v228
	ds_read_b128 v[66:69], v228 offset:512
	s_or_b32 s69, s69, s67
	s_waitcnt vmcnt(3) lgkmcnt(1)
	v_mfma_f32_32x32x16_bf16 v[34:49], v[18:21], v[174:177], v[50:65]
	v_mov_b32_e32 v232, 0
	s_mov_b32 s48, -1
	s_mov_b32 s66, 0
	s_movk_i32 s65, 0x2000
	s_movk_i32 s49, 0x4000
	s_waitcnt lgkmcnt(0)
	v_mfma_f32_32x32x16_bf16 v[18:33], v[66:69], v[174:177], v[50:65]
	ds_read_b128 v[66:69], v228 offset:2048
	ds_read_b128 v[70:73], v228 offset:2560
	s_waitcnt vmcnt(2) lgkmcnt(1)
	v_mfma_f32_32x32x16_bf16 v[34:49], v[66:69], v[170:173], v[34:49]
	s_waitcnt lgkmcnt(0)
	v_mfma_f32_32x32x16_bf16 v[18:33], v[70:73], v[170:173], v[18:33]
	ds_read_b128 v[66:69], v228 offset:4096
	ds_read_b128 v[70:73], v228 offset:4608
	s_waitcnt vmcnt(1) lgkmcnt(1)
	v_mfma_f32_32x32x16_bf16 v[34:49], v[66:69], v[162:165], v[34:49]
	ds_read_b128 v[66:69], v228 offset:6144
	s_waitcnt lgkmcnt(1)
	v_mfma_f32_32x32x16_bf16 v[18:33], v[70:73], v[162:165], v[18:33]
	ds_read_b128 v[70:73], v228 offset:6656
	s_waitcnt vmcnt(0) lgkmcnt(1)
	v_mfma_f32_32x32x16_bf16 v[34:49], v[66:69], v[154:157], v[34:49]
	v_lshlrev_b32_e32 v66, 1, v104
	v_lshlrev_b32_e32 v67, 4, v104
	v_and_b32_e32 v231, 32, v66
	v_and_b32_e32 v66, 0xc0, v67
	v_lshl_or_b32 v230, v217, 8, v66
	v_add_u32_e32 v66, 0, v231
	v_add3_u32 v227, v66, v229, v230
	s_waitcnt lgkmcnt(0)
	v_mfma_f32_32x32x16_bf16 v[18:33], v[70:73], v[154:157], v[18:33]
	s_nop 15
	s_nop 7
	s_waitcnt vmcnt(0) lgkmcnt(0)
	s_barrier
; #define WAIT_BAR(N) asm volatile("s_waitcnt vmcnt(" #N ") lgkmcnt(0)\n\ts_barrier":::"memory")
; __device__ __forceinline__ void kload2(bf16x8*kf,lds_cptr kp,int j){ kf[2*j]=*(const __attribute__((address_space(3))) bf16x8*)(kp+j*2048); kf[2*j+1]=*(const __attribute__((address_space(3))) bf16x8*)(kp+j*2048+512); }
;   #define DMA_K(t,slot) glds16(ksrc+(long)(t)*KVBLK*PK,(unsigned)__builtin_amdgcn_readfirstlane(kdst+(slot)))
;   #define DMA_V(t,slot) glds16(vsrc+(long)(t)*KVBLK*PV,(unsigned)__builtin_amdgcn_readfirstlane(vdst+(slot)))
;   #define ROT() do{sl_prev=sl_cur;sl_cur=sl_next;sl_next=(sl_next==(NSLOT-1)*SLOTB)?0:sl_next+SLOTB;}while(0)
; template<int THRL,bool FIXREF,bool HALFK> __device__ __forceinline__ void attn_unit(float mref,long rowbase,int q0,const bf16*Qh,int PQ,const bf16*__restrict__ Kh_,int PK,const bf16*__restrict__ Vh_,int PV,bf16*Oh,int PO,const bf16*Gh,int PG,u32x4(&okeep)[4],int omode,float lam,float oml,const float ...
;     ...
;   START(pA0,pA1);
;   _Pragma("unroll") for(int r=0;r<16;++r)pA1[r]=__builtin_amdgcn_exp2f(pA1[r]);
;   WAIT_BAR(0);
;   DMA_K(3,0);DMA_V(1,SLOTB);
;   ROT();
;   if constexpr(HALFK){ kload2(kf,kp0+sl_cur,0); kload2(kf,kp0+sl_cur,1); } else kload8(kf,kp0+sl_cur);
;   WAIT_BAR(2);
	s_nop 2
	v_exp_f32_e32 v82, v34
	v_exp_f32_e32 v83, v35
	s_nop 6
	v_exp_f32_e32 v66, v18
	v_exp_f32_e32 v67, v19
	v_lshl_add_u64 v[18:19], v[210:211], 0, s[12:13]
	s_mov_b32 s70, m0
	s_mov_b32 m0, s62
	s_nop 0
	global_load_lds_dwordx4 v[18:19], off
	s_mov_b32 m0, s70
	v_lshl_add_u64 v[18:19], v[208:209], 0, s[22:23]
	s_add_i32 s70, s62, 0x8000
	s_mov_b32 s71, m0
	s_mov_b32 m0, s70
	s_nop 0
	global_load_lds_dwordx4 v[18:19], off
	s_mov_b32 m0, s71
	ds_read_b128 v[98:101], v228 offset:8192
	ds_read_b128 v[182:185], v228 offset:8704
	ds_read_b128 v[186:189], v228 offset:10240
	ds_read_b128 v[178:181], v228 offset:10752
	ds_read_b128 v[142:145], v228 offset:12288
	ds_read_b128 v[138:141], v228 offset:12800
	ds_read_b128 v[134:137], v228 offset:14336
	ds_read_b128 v[130:133], v228 offset:14848
	s_add_u32 s46, s46, s69
	s_addc_u32 s47, s47, s68
	s_add_u32 s42, s50, s42
	s_addc_u32 s43, s51, s43
	s_add_u32 s42, s42, s67
	v_exp_f32_e32 v84, v36
	v_exp_f32_e32 v85, v37
	v_exp_f32_e32 v86, v38
	v_exp_f32_e32 v87, v39
	v_exp_f32_e32 v88, v40
	v_exp_f32_e32 v89, v41
	v_exp_f32_e32 v90, v42
	v_exp_f32_e32 v91, v43
	v_exp_f32_e32 v92, v44
	v_exp_f32_e32 v93, v45
	v_exp_f32_e32 v94, v46
	v_exp_f32_e32 v95, v47
	v_exp_f32_e32 v96, v48
	v_exp_f32_e32 v97, v49
	v_exp_f32_e32 v68, v20
	v_exp_f32_e32 v69, v21
	v_exp_f32_e32 v70, v22
	v_exp_f32_e32 v71, v23
	v_exp_f32_e32 v72, v24
	v_exp_f32_e32 v73, v25
	v_exp_f32_e32 v74, v26
	v_exp_f32_e32 v75, v27
	v_exp_f32_e32 v76, v28
	v_exp_f32_e32 v77, v29
	v_exp_f32_e32 v78, v30
	v_exp_f32_e32 v79, v31
	v_exp_f32_e32 v80, v32
	v_exp_f32_e32 v81, v33
	v_and_b32_e32 v18, 3, v104
	s_addc_u32 s43, s43, 0
	s_waitcnt vmcnt(2) lgkmcnt(0)
	s_barrier
	v_lshl_or_b32 v18, v18, 4, s46
	s_add_u32 s40, s42, s40
	v_subrev_u32_e32 v18, s46, v18
	s_addc_u32 s41, s43, s41
	v_add_u32_e32 v212, v18, v102
	s_add_u32 s82, s0, s46
	s_addc_u32 s83, s1, s47
	v_mov_b32_e32 v214, v0
	s_mov_b32 s80, s40
	s_mov_b32 s81, s41
	v_mov_b32_e32 v18, 0
	v_mov_b32_e32 v19, v232
	v_mov_b32_e32 v20, v232
	v_mov_b32_e32 v21, v232
	v_mov_b32_e32 v22, v232
	v_mov_b32_e32 v23, v232
	v_mov_b32_e32 v24, v232
	v_mov_b32_e32 v25, v232
	v_mov_b32_e32 v26, v232
	v_mov_b32_e32 v27, v232
	v_mov_b32_e32 v28, v232
	v_mov_b32_e32 v29, v232
	v_mov_b32_e32 v30, v232
	v_mov_b32_e32 v31, v232
	v_mov_b32_e32 v32, v232
	v_mov_b32_e32 v33, v232
	v_mov_b32_e32 v34, 0
	v_mov_b32_e32 v35, v232
	v_mov_b32_e32 v36, v232
	v_mov_b32_e32 v37, v232
	v_mov_b32_e32 v38, v232
	v_mov_b32_e32 v39, v232
	v_mov_b32_e32 v40, v232
	v_mov_b32_e32 v41, v232
	v_mov_b32_e32 v42, v232
	v_mov_b32_e32 v43, v232
	v_mov_b32_e32 v44, v232
	v_mov_b32_e32 v45, v232
	v_mov_b32_e32 v46, v232
	v_mov_b32_e32 v47, v232
	v_mov_b32_e32 v48, v232
	v_mov_b32_e32 v49, v232
.LBB0_451:
	v_add_u32_e32 v0, s66, v227
	ds_read_b64_tr_b16 v[234:235], v0 offset:24576
	ds_read_b64_tr_b16 v[236:237], v0 offset:25088
	v_add_f32_e32 v102, v82, v83
	v_add_f32_e32 v102, v84, v102
	v_add_f32_e32 v102, v85, v102
	v_add_f32_e32 v102, v86, v102
	v_add_f32_e32 v102, v87, v102
	v_cvt_pk_bf16_f32 v166, v82, v83
	v_cvt_pk_bf16_f32 v167, v84, v85
	s_waitcnt lgkmcnt(9)
	v_mfma_f32_32x32x16_bf16 v[114:129], v[98:101], v[174:177], v[50:65]
	ds_read_b64_tr_b16 v[82:83], v0 offset:28672
	ds_read_b64_tr_b16 v[84:85], v0 offset:29184
	v_add_f32_e32 v98, v88, v102
	v_add_f32_e32 v98, v89, v98
	v_add_f32_e32 v98, v90, v98
	v_add_f32_e32 v146, v91, v98
	s_waitcnt lgkmcnt(10)
	v_mfma_f32_32x32x16_bf16 v[98:113], v[182:185], v[174:177], v[50:65]
	v_cvt_pk_bf16_f32 v168, v86, v87
	v_cvt_pk_bf16_f32 v169, v88, v89
	ds_read_b64_tr_b16 v[86:87], v0 offset:25600
	ds_read_b64_tr_b16 v[88:89], v0 offset:26112
	v_add_f32_e32 v146, v92, v146
	v_add_f32_e32 v146, v93, v146
	v_add_f32_e32 v146, v94, v146
	v_add_f32_e32 v146, v95, v146
	v_cvt_pk_bf16_f32 v158, v90, v91
	v_cvt_pk_bf16_f32 v159, v92, v93
	s_waitcnt lgkmcnt(11)
	v_mfma_f32_32x32x16_bf16 v[114:129], v[186:189], v[170:173], v[114:129]
	ds_read_b64_tr_b16 v[90:91], v0 offset:29696
	ds_read_b64_tr_b16 v[92:93], v0 offset:30208
	s_waitcnt lgkmcnt(12)
	v_mfma_f32_32x32x16_bf16 v[98:113], v[178:181], v[170:173], v[98:113]
	v_add_f32_e32 v146, v96, v146
	v_add_f32_e32 v146, v97, v146
	v_add_f32_e32 v146, v66, v146
	v_add_f32_e32 v146, v67, v146
	v_cvt_pk_bf16_f32 v160, v94, v95
	v_cvt_pk_bf16_f32 v161, v96, v97
	ds_read_b64_tr_b16 v[94:95], v0 offset:26624
	ds_read_b64_tr_b16 v[96:97], v0 offset:27136
	s_waitcnt lgkmcnt(13)
	v_mfma_f32_32x32x16_bf16 v[114:129], v[142:145], v[162:165], v[114:129]
	v_add_f32_e32 v142, v68, v146
	v_add_f32_e32 v142, v69, v142
	v_add_f32_e32 v142, v70, v142
	v_add_f32_e32 v142, v71, v142
	v_cvt_pk_bf16_f32 v150, v66, v67
	v_cvt_pk_bf16_f32 v151, v68, v69
	ds_read_b64_tr_b16 v[66:67], v0 offset:30720
	ds_read_b64_tr_b16 v[68:69], v0 offset:31232
	s_waitcnt lgkmcnt(14)
	v_mfma_f32_32x32x16_bf16 v[98:113], v[138:141], v[162:165], v[98:113]
	v_add_f32_e32 v138, v72, v142
	v_add_f32_e32 v138, v73, v138
	v_add_f32_e32 v138, v74, v138
	v_add_f32_e32 v138, v75, v138
	v_cvt_pk_bf16_f32 v152, v70, v71
	v_cvt_pk_bf16_f32 v153, v72, v73
	ds_read_b64_tr_b16 v[70:71], v0 offset:27648
	ds_read_b64_tr_b16 v[72:73], v0 offset:28160
	s_waitcnt lgkmcnt(14)
; #define WAIT_BAR(N) asm volatile("s_waitcnt vmcnt(" #N ") lgkmcnt(0)\n\ts_barrier":::"memory")
;   #define RESC() do{ if(!FIXREF&&resc){ asm volatile("s_waitcnt lgkmcnt(0)":::"memory"); \
;       _Pragma("unroll") for(int d_=0;d_<2;++d_) _Pragma("unroll") for(int r=0;r<16;++r)o[d_][r]*=wsf[crow(r,hi)]; } }while(0)
;   #define ROT() do{sl_prev=sl_cur;sl_cur=sl_next;sl_next=(sl_next==(NSLOT-1)*SLOTB)?0:sl_next+SLOTB;}while(0)
; template<int THRL,bool FIXREF,bool HALFK> __device__ __forceinline__ void attn_unit(float mref,long rowbase,int q0,const bf16*Qh,int PQ,const bf16*__restrict__ Kh_,int PK,const bf16*__restrict__ Vh_,int PV,bf16*Oh,int PO,const bf16*Gh,int PG,u32x4(&okeep)[4],int omode,float lam,float oml,const float ...
;     ...
;   int t=1;
;     ...
;   for(;t+5<NT;t+=2){
;     STEP(pB0,pB1,pA0,pA1,t,true,true,true);     WAIT_BAR(2); RESC(); ROT();
;     STEP(pA0,pA1,pB0,pB1,t+1,true,true,true);   WAIT_BAR(2); RESC(); ROT();
	v_mfma_f32_32x32x16_bf16 v[114:129], v[134:137], v[154:157], v[114:129]
	v_add_f32_e32 v134, v76, v138
	v_add_f32_e32 v134, v77, v134
	v_add_f32_e32 v134, v78, v134
	v_add_f32_e32 v134, v79, v134
	v_cvt_pk_bf16_f32 v146, v74, v75
	v_cvt_pk_bf16_f32 v147, v76, v77
	ds_read_b64_tr_b16 v[74:75], v0 offset:31744
	ds_read_b64_tr_b16 v[76:77], v0 offset:32256
	v_mfma_f32_32x32x16_bf16 v[98:113], v[130:133], v[154:157], v[98:113]
	v_add_f32_e32 v0, v80, v134
	v_add_f32_e32 v0, v81, v0
	v_cvt_pk_bf16_f32 v148, v78, v79
	v_cvt_pk_bf16_f32 v149, v80, v81
	s_add_u32 s84, s80, s12
	s_addc_u32 s85, s81, s13
	s_add_i32 s40, s65, s62
	s_mov_b32 s41, m0
	s_mov_b32 m0, s40
	s_nop 0
	global_load_lds_dwordx4 v214, s[84:85]
	s_mov_b32 m0, s41
	s_add_u32 s84, s82, s22
	s_addc_u32 s85, s83, s23
	s_add_i32 s40, s49, s61
	s_mov_b32 s41, m0
	s_mov_b32 m0, s40
	s_nop 0
	global_load_lds_dwordx4 v212, s[84:85]
	s_mov_b32 m0, s41
	v_add_f32_e32 v0, v232, v0
	s_waitcnt lgkmcnt(14)
	v_mfma_f32_32x32x16_bf16 v[18:33], v[166:169], v[234:237], v[18:33]
	v_exp_f32_e32 v114, v114
	v_exp_f32_e32 v115, v115
	v_exp_f32_e32 v116, v116
	v_exp_f32_e32 v117, v117
	s_waitcnt lgkmcnt(12)
	v_mfma_f32_32x32x16_bf16 v[34:49], v[166:169], v[82:85], v[34:49]
	v_exp_f32_e32 v118, v118
	v_exp_f32_e32 v119, v119
	v_exp_f32_e32 v120, v120
	v_exp_f32_e32 v121, v121
	v_add_u32_e32 v82, s49, v228
	ds_read_b128 v[78:81], v82
	ds_read_b128 v[134:137], v82 offset:512
	s_waitcnt lgkmcnt(12)
	v_mfma_f32_32x32x16_bf16 v[18:33], v[158:161], v[86:89], v[18:33]
	v_exp_f32_e32 v122, v122
	v_exp_f32_e32 v123, v123
	v_exp_f32_e32 v124, v124
	v_exp_f32_e32 v125, v125
	ds_read_b128 v[138:141], v82 offset:2048
	ds_read_b128 v[142:145], v82 offset:2560
	s_waitcnt lgkmcnt(12)
	v_mfma_f32_32x32x16_bf16 v[34:49], v[158:161], v[90:93], v[34:49]
	v_exp_f32_e32 v126, v126
	v_exp_f32_e32 v127, v127
	v_exp_f32_e32 v128, v128
	v_exp_f32_e32 v129, v129
	ds_read_b128 v[178:181], v82 offset:4096
	ds_read_b128 v[182:185], v82 offset:4608
	s_waitcnt lgkmcnt(12)
	v_mfma_f32_32x32x16_bf16 v[18:33], v[150:153], v[94:97], v[18:33]
	v_exp_f32_e32 v98, v98
	v_exp_f32_e32 v99, v99
	v_exp_f32_e32 v100, v100
	v_exp_f32_e32 v101, v101
	ds_read_b128 v[186:189], v82 offset:6144
	ds_read_b128 v[130:133], v82 offset:6656
	s_waitcnt lgkmcnt(12)
	v_mfma_f32_32x32x16_bf16 v[34:49], v[150:153], v[66:69], v[34:49]
	v_exp_f32_e32 v102, v102
	v_exp_f32_e32 v103, v103
	v_exp_f32_e32 v104, v104
	v_exp_f32_e32 v105, v105
	s_waitcnt lgkmcnt(10)
	v_mfma_f32_32x32x16_bf16 v[18:33], v[146:149], v[70:73], v[18:33]
	v_exp_f32_e32 v106, v106
	v_exp_f32_e32 v107, v107
	v_exp_f32_e32 v108, v108
	v_exp_f32_e32 v109, v109
	s_waitcnt lgkmcnt(8)
	v_mfma_f32_32x32x16_bf16 v[34:49], v[146:149], v[74:77], v[34:49]
	v_exp_f32_e32 v110, v110
	v_exp_f32_e32 v111, v111
	v_exp_f32_e32 v112, v112
	v_exp_f32_e32 v113, v113
	s_add_i32 s40, s49, 0x2000
	s_cmpk_lg_i32 s49, 0x4000
	s_cselect_b32 s40, s40, 0
	v_add_u32_e32 v232, s65, v227
	s_waitcnt vmcnt(2) lgkmcnt(0)
	s_barrier
	ds_read_b64_tr_b16 v[234:235], v232 offset:24576
	ds_read_b64_tr_b16 v[236:237], v232 offset:25088
	s_waitcnt lgkmcnt(9)
	v_mfma_f32_32x32x16_bf16 v[82:97], v[78:81], v[174:177], v[50:65]
	v_add_f32_e32 v66, v114, v115
	v_add_f32_e32 v66, v116, v66
	v_add_f32_e32 v66, v117, v66
	v_add_f32_e32 v66, v118, v66
	v_add_f32_e32 v66, v119, v66
	v_cvt_pk_bf16_f32 v166, v114, v115
	v_cvt_pk_bf16_f32 v167, v116, v117
	ds_read_b64_tr_b16 v[114:115], v232 offset:28672
	ds_read_b64_tr_b16 v[116:117], v232 offset:29184
	v_add_f32_e32 v66, v120, v66
	v_add_f32_e32 v66, v121, v66
	v_add_f32_e32 v66, v122, v66
	v_add_f32_e32 v146, v123, v66
	s_waitcnt lgkmcnt(10)
	v_mfma_f32_32x32x16_bf16 v[66:81], v[134:137], v[174:177], v[50:65]
	v_cvt_pk_bf16_f32 v168, v118, v119
	v_cvt_pk_bf16_f32 v169, v120, v121
	ds_read_b64_tr_b16 v[118:119], v232 offset:25600
	ds_read_b64_tr_b16 v[120:121], v232 offset:26112
	s_waitcnt lgkmcnt(11)
	v_mfma_f32_32x32x16_bf16 v[82:97], v[138:141], v[170:173], v[82:97]
	v_add_f32_e32 v134, v124, v146
	v_add_f32_e32 v134, v125, v134
	v_add_f32_e32 v134, v126, v134
	v_add_f32_e32 v134, v127, v134
	v_cvt_pk_bf16_f32 v158, v122, v123
	v_cvt_pk_bf16_f32 v159, v124, v125
	ds_read_b64_tr_b16 v[122:123], v232 offset:29696
	ds_read_b64_tr_b16 v[124:125], v232 offset:30208
	s_waitcnt lgkmcnt(12)
	v_mfma_f32_32x32x16_bf16 v[66:81], v[142:145], v[170:173], v[66:81]
	v_add_f32_e32 v134, v128, v134
	v_add_f32_e32 v134, v129, v134
	v_add_f32_e32 v134, v98, v134
	v_add_f32_e32 v134, v99, v134
	v_cvt_pk_bf16_f32 v160, v126, v127
	v_cvt_pk_bf16_f32 v161, v128, v129
	ds_read_b64_tr_b16 v[126:127], v232 offset:26624
	ds_read_b64_tr_b16 v[128:129], v232 offset:27136
	s_waitcnt lgkmcnt(13)
	v_mfma_f32_32x32x16_bf16 v[82:97], v[178:181], v[162:165], v[82:97]
	v_add_f32_e32 v134, v100, v134
	v_add_f32_e32 v134, v101, v134
	v_add_f32_e32 v134, v102, v134
	v_add_f32_e32 v134, v103, v134
	v_cvt_pk_bf16_f32 v150, v98, v99
	v_cvt_pk_bf16_f32 v151, v100, v101
	ds_read_b64_tr_b16 v[238:239], v232 offset:30720
	ds_read_b64_tr_b16 v[240:241], v232 offset:31232
	s_waitcnt lgkmcnt(14)
	v_mfma_f32_32x32x16_bf16 v[66:81], v[182:185], v[162:165], v[66:81]
	v_add_f32_e32 v98, v104, v134
	v_add_f32_e32 v98, v105, v98
	v_add_f32_e32 v98, v106, v98
	v_add_f32_e32 v98, v107, v98
	v_cvt_pk_bf16_f32 v152, v102, v103
	v_cvt_pk_bf16_f32 v153, v104, v105
	ds_read_b64_tr_b16 v[102:103], v232 offset:27648
	ds_read_b64_tr_b16 v[104:105], v232 offset:28160
	s_waitcnt lgkmcnt(14)
; #define WAIT_BAR(N) asm volatile("s_waitcnt vmcnt(" #N ") lgkmcnt(0)\n\ts_barrier":::"memory")
;   #define RESC() do{ if(!FIXREF&&resc){ asm volatile("s_waitcnt lgkmcnt(0)":::"memory"); \
;       _Pragma("unroll") for(int d_=0;d_<2;++d_) _Pragma("unroll") for(int r=0;r<16;++r)o[d_][r]*=wsf[crow(r,hi)]; } }while(0)
;   #define ROT() do{sl_prev=sl_cur;sl_cur=sl_next;sl_next=(sl_next==(NSLOT-1)*SLOTB)?0:sl_next+SLOTB;}while(0)
;   #define ENDW(tt) do{ if((tt)+3<NT){WAIT_BAR(2);} else if((tt)+2<NT){WAIT_BAR(1);} else {WAIT_BAR(0);} }while(0)
; template<int THRL,bool FIXREF,bool HALFK> __device__ __forceinline__ void attn_unit(float mref,long rowbase,int q0,const bf16*Qh,int PQ,const bf16*__restrict__ Kh_,int PK,const bf16*__restrict__ Vh_,int PV,bf16*Oh,int PO,const bf16*Gh,int PG,u32x4(&okeep)[4],int omode,float lam,float oml,const float ...
;     ...
;   int t=1;
;     ...
;   for(;t+5<NT;t+=2){
;     STEP(pB0,pB1,pA0,pA1,t,true,true,true);     WAIT_BAR(2); RESC(); ROT();
;     STEP(pA0,pA1,pB0,pB1,t+1,true,true,true);   WAIT_BAR(2); RESC(); ROT();
;   }
;     ...
;   for(;t+1<NT;t+=2){
;     STEP(pB0,pB1,pA0,pA1,t,(t+3<NT),(t+1<NT),(t+1<NT));       ENDW(t);   RESC(); ROT();
	v_mfma_f32_32x32x16_bf16 v[82:97], v[186:189], v[154:157], v[82:97]
	v_add_f32_e32 v98, v108, v98
	v_add_f32_e32 v98, v109, v98
	v_add_f32_e32 v98, v110, v98
	v_add_f32_e32 v98, v111, v98
	v_cvt_pk_bf16_f32 v146, v106, v107
	v_cvt_pk_bf16_f32 v147, v108, v109
	ds_read_b64_tr_b16 v[106:107], v232 offset:31744
	ds_read_b64_tr_b16 v[108:109], v232 offset:32256
	v_mfma_f32_32x32x16_bf16 v[66:81], v[130:133], v[154:157], v[66:81]
	v_add_f32_e32 v98, v112, v98
	v_add_f32_e32 v98, v113, v98
	v_cvt_pk_bf16_f32 v148, v110, v111
	v_cvt_pk_bf16_f32 v149, v112, v113
	s_nop 0
	v_add_f32_e32 v232, v0, v98
	s_add_u32 s84, s80, s92
	s_addc_u32 s85, s81, s93
	s_add_i32 s41, s49, s62
	s_mov_b32 s42, m0
	s_mov_b32 m0, s41
	s_nop 0
	global_load_lds_dwordx4 v214, s[84:85]
	s_mov_b32 m0, s42
	s_add_u32 s82, s82, s4
	s_addc_u32 s83, s83, s5
	s_add_i32 s41, s40, s61
	s_mov_b32 s42, m0
	s_mov_b32 m0, s41
	s_nop 0
	global_load_lds_dwordx4 v212, s[82:83]
	s_mov_b32 m0, s42
	s_waitcnt lgkmcnt(14)
	v_mfma_f32_32x32x16_bf16 v[18:33], v[166:169], v[234:237], v[18:33]
	v_exp_f32_e32 v82, v82
	v_exp_f32_e32 v83, v83
	v_exp_f32_e32 v84, v84
	v_exp_f32_e32 v85, v85
	s_waitcnt lgkmcnt(12)
	v_mfma_f32_32x32x16_bf16 v[34:49], v[166:169], v[114:117], v[34:49]
	v_exp_f32_e32 v86, v86
	v_exp_f32_e32 v87, v87
	v_exp_f32_e32 v88, v88
	v_exp_f32_e32 v89, v89
	v_add_u32_e32 v0, s40, v228
	ds_read_b128 v[98:101], v0
	ds_read_b128 v[182:185], v0 offset:512
	s_waitcnt lgkmcnt(12)
	v_mfma_f32_32x32x16_bf16 v[18:33], v[158:161], v[118:121], v[18:33]
	v_exp_f32_e32 v90, v90
	v_exp_f32_e32 v91, v91
	v_exp_f32_e32 v92, v92
	v_exp_f32_e32 v93, v93
	ds_read_b128 v[186:189], v0 offset:2048
	ds_read_b128 v[178:181], v0 offset:2560
	s_waitcnt lgkmcnt(12)
	v_mfma_f32_32x32x16_bf16 v[34:49], v[158:161], v[122:125], v[34:49]
	v_exp_f32_e32 v94, v94
	v_exp_f32_e32 v95, v95
	v_exp_f32_e32 v96, v96
	v_exp_f32_e32 v97, v97
	ds_read_b128 v[142:145], v0 offset:4096
	ds_read_b128 v[138:141], v0 offset:4608
	s_waitcnt lgkmcnt(12)
	v_mfma_f32_32x32x16_bf16 v[18:33], v[150:153], v[126:129], v[18:33]
	v_exp_f32_e32 v66, v66
	v_exp_f32_e32 v67, v67
	v_exp_f32_e32 v68, v68
	v_exp_f32_e32 v69, v69
	ds_read_b128 v[134:137], v0 offset:6144
	ds_read_b128 v[130:133], v0 offset:6656
	s_waitcnt lgkmcnt(12)
	v_mfma_f32_32x32x16_bf16 v[34:49], v[150:153], v[238:241], v[34:49]
	v_exp_f32_e32 v70, v70
	v_exp_f32_e32 v71, v71
	v_exp_f32_e32 v72, v72
	v_exp_f32_e32 v73, v73
	s_waitcnt lgkmcnt(10)
	v_mfma_f32_32x32x16_bf16 v[18:33], v[146:149], v[102:105], v[18:33]
	v_exp_f32_e32 v74, v74
	v_exp_f32_e32 v75, v75
	v_exp_f32_e32 v76, v76
	v_exp_f32_e32 v77, v77
	s_waitcnt lgkmcnt(8)
	v_mfma_f32_32x32x16_bf16 v[34:49], v[146:149], v[106:109], v[34:49]
	v_exp_f32_e32 v78, v78
	v_exp_f32_e32 v79, v79
	v_exp_f32_e32 v80, v80
	v_exp_f32_e32 v81, v81
	s_add_i32 s41, s40, 0x2000
	s_cmpk_lg_i32 s40, 0x4000
	s_mov_b32 s66, s49
	s_cselect_b32 s49, s41, 0
	s_add_i32 s48, s48, 2
	s_add_u32 s80, s80, s10
	s_addc_u32 s81, s81, s11
	s_mov_b32 s65, s40
	s_cmp_gt_u32 s48, 56
	s_waitcnt vmcnt(2) lgkmcnt(0)
	s_barrier
	s_cbranch_scc0 .LBB0_451
	s_and_b32 s41, s64, 0x3fffffc0
	s_cmp_lg_u32 0, -1
	s_cselect_b32 s40, 0, 0
	s_add_i32 s42, s40, 0x6000
	v_add_u32_e32 v0, s42, v231
	s_lshl_b32 s41, s41, 2
	s_add_i32 s42, s41, 0
	v_add3_u32 v0, v0, v229, v230
	ds_read_b64_tr_b16 v[212:213], v227 offset:32768
	ds_read_b64_tr_b16 v[214:215], v227 offset:33280
	v_add_f32_e32 v102, v82, v83
	v_add_f32_e32 v102, v84, v102
	v_add_f32_e32 v102, v85, v102
	v_add_f32_e32 v102, v86, v102
	v_add_f32_e32 v102, v87, v102
	v_cvt_pk_bf16_f32 v166, v82, v83
	v_cvt_pk_bf16_f32 v167, v84, v85
	s_waitcnt lgkmcnt(9)
	v_mfma_f32_32x32x16_bf16 v[114:129], v[98:101], v[174:177], v[50:65]
	ds_read_b64_tr_b16 v[82:83], v227 offset:36864
	ds_read_b64_tr_b16 v[84:85], v227 offset:37376
	v_add_f32_e32 v98, v88, v102
	v_add_f32_e32 v98, v89, v98
	v_add_f32_e32 v98, v90, v98
	v_add_f32_e32 v146, v91, v98
	v_cvt_pk_bf16_f32 v168, v86, v87
	v_cvt_pk_bf16_f32 v169, v88, v89
	s_waitcnt lgkmcnt(10)
	v_mfma_f32_32x32x16_bf16 v[98:113], v[182:185], v[174:177], v[50:65]
	ds_read_b64_tr_b16 v[86:87], v227 offset:33792
	ds_read_b64_tr_b16 v[88:89], v227 offset:34304
	v_add_f32_e32 v146, v92, v146
	v_add_f32_e32 v146, v93, v146
	v_add_f32_e32 v146, v94, v146
	v_add_f32_e32 v146, v95, v146
	v_cvt_pk_bf16_f32 v158, v90, v91
	v_cvt_pk_bf16_f32 v159, v92, v93
	s_waitcnt lgkmcnt(11)
	v_mfma_f32_32x32x16_bf16 v[114:129], v[186:189], v[170:173], v[114:129]
	ds_read_b64_tr_b16 v[90:91], v227 offset:37888
	ds_read_b64_tr_b16 v[92:93], v227 offset:38400
	v_add_f32_e32 v146, v96, v146
	v_add_f32_e32 v146, v97, v146
	v_add_f32_e32 v146, v66, v146
	v_add_f32_e32 v146, v67, v146
	v_cvt_pk_bf16_f32 v160, v94, v95
	v_cvt_pk_bf16_f32 v161, v96, v97
	s_waitcnt lgkmcnt(12)
	v_mfma_f32_32x32x16_bf16 v[98:113], v[178:181], v[170:173], v[98:113]
	ds_read_b64_tr_b16 v[94:95], v227 offset:34816
	ds_read_b64_tr_b16 v[96:97], v227 offset:35328
	s_waitcnt lgkmcnt(13)
	v_mfma_f32_32x32x16_bf16 v[114:129], v[142:145], v[162:165], v[114:129]
	v_add_f32_e32 v142, v68, v146
	v_add_f32_e32 v142, v69, v142
	v_add_f32_e32 v142, v70, v142
	v_add_f32_e32 v142, v71, v142
	v_cvt_pk_bf16_f32 v150, v66, v67
	v_cvt_pk_bf16_f32 v151, v68, v69
	ds_read_b64_tr_b16 v[66:67], v227 offset:38912
	ds_read_b64_tr_b16 v[68:69], v227 offset:39424
	s_waitcnt lgkmcnt(14)
	v_mfma_f32_32x32x16_bf16 v[98:113], v[138:141], v[162:165], v[98:113]
	v_add_f32_e32 v138, v72, v142
	v_add_f32_e32 v138, v73, v138
	v_add_f32_e32 v138, v74, v138
	v_add_f32_e32 v138, v75, v138
	v_cvt_pk_bf16_f32 v152, v70, v71
	v_cvt_pk_bf16_f32 v153, v72, v73
	ds_read_b64_tr_b16 v[70:71], v227 offset:35840
	ds_read_b64_tr_b16 v[72:73], v227 offset:36352
	s_waitcnt lgkmcnt(14)
; #define WAIT_BAR(N) asm volatile("s_waitcnt vmcnt(" #N ") lgkmcnt(0)\n\ts_barrier":::"memory")
;   #define RESC() do{ if(!FIXREF&&resc){ asm volatile("s_waitcnt lgkmcnt(0)":::"memory"); \
;       _Pragma("unroll") for(int d_=0;d_<2;++d_) _Pragma("unroll") for(int r=0;r<16;++r)o[d_][r]*=wsf[crow(r,hi)]; } }while(0)
;   #define ROT() do{sl_prev=sl_cur;sl_cur=sl_next;sl_next=(sl_next==(NSLOT-1)*SLOTB)?0:sl_next+SLOTB;}while(0)
;   #define ENDW(tt) do{ if((tt)+3<NT){WAIT_BAR(2);} else if((tt)+2<NT){WAIT_BAR(1);} else {WAIT_BAR(0);} }while(0)
; template<int THRL,bool FIXREF,bool HALFK> __device__ __forceinline__ void attn_unit(float mref,long rowbase,int q0,const bf16*Qh,int PQ,const bf16*__restrict__ Kh_,int PK,const bf16*__restrict__ Vh_,int PV,bf16*Oh,int PO,const bf16*Gh,int PG,u32x4(&okeep)[4],int omode,float lam,float oml,const float ...
;     ...
;   int t=1;
;     ...
;   for(;t+5<NT;t+=2){
;     STEP(pB0,pB1,pA0,pA1,t,true,true,true);     WAIT_BAR(2); RESC(); ROT();
;     STEP(pA0,pA1,pB0,pB1,t+1,true,true,true);   WAIT_BAR(2); RESC(); ROT();
;   }
;     ...
;   for(;t+1<NT;t+=2){
;     STEP(pB0,pB1,pA0,pA1,t,(t+3<NT),(t+1<NT),(t+1<NT));       ENDW(t);   RESC(); ROT();
;     STEP(pA0,pA1,pB0,pB1,t+1,(t+4<NT),(t+2<NT),(t+2<NT));     ENDW(t+1); RESC(); ROT();
;   }
	v_mfma_f32_32x32x16_bf16 v[114:129], v[134:137], v[154:157], v[114:129]
	v_add_f32_e32 v134, v76, v138
	v_add_f32_e32 v134, v77, v134
	v_add_f32_e32 v134, v78, v134
	v_add_f32_e32 v134, v79, v134
	v_cvt_pk_bf16_f32 v146, v74, v75
	v_cvt_pk_bf16_f32 v147, v76, v77
	ds_read_b64_tr_b16 v[74:75], v227 offset:39936
	ds_read_b64_tr_b16 v[76:77], v227 offset:40448
	v_mfma_f32_32x32x16_bf16 v[98:113], v[130:133], v[154:157], v[98:113]
	v_add_f32_e32 v130, v80, v134
	v_add_f32_e32 v130, v81, v130
	v_add_f32_e32 v130, 0, v130
	v_cvt_pk_bf16_f32 v148, v78, v79
	v_cvt_pk_bf16_f32 v149, v80, v81
	s_mov_b64 s[46:47], 0xf8000
	s_add_i32 s40, s40, s63
	v_lshl_add_u64 v[78:79], v[210:211], 0, s[46:47]
	s_add_i32 s41, s40, 0x4000
	s_mov_b32 s43, m0
	s_mov_b32 m0, s41
	s_nop 0
	global_load_lds_dwordx4 v[78:79], off
	s_mov_b32 m0, s43
	v_lshl_add_u64 v[78:79], v[208:209], 0, s[18:19]
	s_mov_b32 s41, m0
	s_mov_b32 m0, s61
	s_nop 0
	global_load_lds_dwordx4 v[78:79], off
	s_mov_b32 m0, s41
	v_add_f32_e32 v229, v232, v130
	s_waitcnt lgkmcnt(14)
	v_mfma_f32_32x32x16_bf16 v[18:33], v[166:169], v[212:215], v[18:33]
	v_exp_f32_e32 v114, v114
	v_exp_f32_e32 v115, v115
	v_exp_f32_e32 v116, v116
	v_exp_f32_e32 v117, v117
	s_waitcnt lgkmcnt(12)
	v_mfma_f32_32x32x16_bf16 v[34:49], v[166:169], v[82:85], v[34:49]
	v_exp_f32_e32 v118, v118
	v_exp_f32_e32 v119, v119
	v_exp_f32_e32 v120, v120
	v_exp_f32_e32 v121, v121
	ds_read_b128 v[78:81], v228
	ds_read_b128 v[178:181], v228 offset:512
	s_waitcnt lgkmcnt(12)
	v_mfma_f32_32x32x16_bf16 v[18:33], v[158:161], v[86:89], v[18:33]
	v_exp_f32_e32 v122, v122
	v_exp_f32_e32 v123, v123
	v_exp_f32_e32 v124, v124
	v_exp_f32_e32 v125, v125
	ds_read_b128 v[86:89], v228 offset:2048
	ds_read_b128 v[182:185], v228 offset:2560
	s_waitcnt lgkmcnt(12)
	v_mfma_f32_32x32x16_bf16 v[34:49], v[158:161], v[90:93], v[34:49]
	v_exp_f32_e32 v126, v126
	v_exp_f32_e32 v127, v127
	v_exp_f32_e32 v128, v128
	v_exp_f32_e32 v129, v129
	ds_read_b128 v[90:93], v228 offset:4096
	ds_read_b128 v[186:189], v228 offset:4608
	s_waitcnt lgkmcnt(12)
	v_mfma_f32_32x32x16_bf16 v[18:33], v[150:153], v[94:97], v[18:33]
	v_exp_f32_e32 v98, v98
	v_exp_f32_e32 v99, v99
	v_exp_f32_e32 v100, v100
	v_exp_f32_e32 v101, v101
	ds_read_b128 v[94:97], v228 offset:6144
	ds_read_b128 v[82:85], v228 offset:6656
	s_waitcnt lgkmcnt(12)
	v_mfma_f32_32x32x16_bf16 v[34:49], v[150:153], v[66:69], v[34:49]
	v_exp_f32_e32 v102, v102
	v_exp_f32_e32 v103, v103
	v_exp_f32_e32 v104, v104
	v_exp_f32_e32 v105, v105
	s_waitcnt lgkmcnt(10)
	v_mfma_f32_32x32x16_bf16 v[18:33], v[146:149], v[70:73], v[18:33]
	v_exp_f32_e32 v106, v106
	v_exp_f32_e32 v107, v107
	v_exp_f32_e32 v108, v108
	v_exp_f32_e32 v109, v109
	s_waitcnt lgkmcnt(8)
	v_mfma_f32_32x32x16_bf16 v[34:49], v[146:149], v[74:77], v[34:49]
	v_exp_f32_e32 v110, v110
	v_exp_f32_e32 v111, v111
	v_exp_f32_e32 v112, v112
	v_exp_f32_e32 v113, v113
	s_waitcnt vmcnt(2) lgkmcnt(0)
	s_barrier
	ds_read_b64_tr_b16 v[212:213], v227 offset:40960
	ds_read_b64_tr_b16 v[214:215], v227 offset:41472
	v_add_f32_e32 v66, v114, v115
	v_add_f32_e32 v66, v116, v66
	v_add_f32_e32 v66, v117, v66
	v_add_f32_e32 v66, v118, v66
	v_add_f32_e32 v66, v119, v66
	v_cvt_pk_bf16_f32 v166, v114, v115
	v_cvt_pk_bf16_f32 v167, v116, v117
	s_waitcnt lgkmcnt(9)
	v_mfma_f32_32x32x16_bf16 v[130:145], v[78:81], v[174:177], v[50:65]
	ds_read_b64_tr_b16 v[114:115], v227 offset:45056
	ds_read_b64_tr_b16 v[116:117], v227 offset:45568
	v_add_f32_e32 v66, v120, v66
	v_add_f32_e32 v66, v121, v66
	v_add_f32_e32 v66, v122, v66
	v_add_f32_e32 v146, v123, v66
	s_waitcnt lgkmcnt(10)
	v_mfma_f32_32x32x16_bf16 v[66:81], v[178:181], v[174:177], v[50:65]
	v_cvt_pk_bf16_f32 v168, v118, v119
	v_cvt_pk_bf16_f32 v169, v120, v121
	ds_read_b64_tr_b16 v[118:119], v227 offset:41984
	ds_read_b64_tr_b16 v[120:121], v227 offset:42496
	s_waitcnt lgkmcnt(11)
	v_mfma_f32_32x32x16_bf16 v[130:145], v[86:89], v[170:173], v[130:145]
	v_add_f32_e32 v86, v124, v146
	v_add_f32_e32 v86, v125, v86
	v_add_f32_e32 v86, v126, v86
	v_add_f32_e32 v146, v127, v86
	v_cvt_pk_bf16_f32 v158, v122, v123
	v_cvt_pk_bf16_f32 v159, v124, v125
	ds_read_b64_tr_b16 v[86:87], v227 offset:46080
	ds_read_b64_tr_b16 v[88:89], v227 offset:46592
	s_waitcnt lgkmcnt(12)
	v_mfma_f32_32x32x16_bf16 v[66:81], v[182:185], v[170:173], v[66:81]
	v_add_f32_e32 v122, v128, v146
	v_add_f32_e32 v122, v129, v122
	v_add_f32_e32 v122, v98, v122
	v_add_f32_e32 v146, v99, v122
	v_cvt_pk_bf16_f32 v160, v126, v127
	v_cvt_pk_bf16_f32 v161, v128, v129
	ds_read_b64_tr_b16 v[122:123], v227 offset:43008
	ds_read_b64_tr_b16 v[124:125], v227 offset:43520
	s_waitcnt lgkmcnt(13)
	v_mfma_f32_32x32x16_bf16 v[130:145], v[90:93], v[162:165], v[130:145]
	v_add_f32_e32 v90, v100, v146
	v_add_f32_e32 v90, v101, v90
	v_add_f32_e32 v90, v102, v90
	v_add_f32_e32 v126, v103, v90
	v_cvt_pk_bf16_f32 v150, v98, v99
	v_cvt_pk_bf16_f32 v151, v100, v101
	ds_read_b64_tr_b16 v[90:91], v227 offset:47104
	ds_read_b64_tr_b16 v[92:93], v227 offset:47616
	s_waitcnt lgkmcnt(14)
	v_mfma_f32_32x32x16_bf16 v[66:81], v[186:189], v[162:165], v[66:81]
	v_add_f32_e32 v98, v104, v126
	v_add_f32_e32 v98, v105, v98
	v_add_f32_e32 v98, v106, v98
	v_add_f32_e32 v98, v107, v98
	v_cvt_pk_bf16_f32 v152, v102, v103
	v_cvt_pk_bf16_f32 v153, v104, v105
	ds_read_b64_tr_b16 v[102:103], v227 offset:44032
	ds_read_b64_tr_b16 v[104:105], v227 offset:44544
	s_waitcnt lgkmcnt(14)
; #define WAIT_BAR(N) asm volatile("s_waitcnt vmcnt(" #N ") lgkmcnt(0)\n\ts_barrier":::"memory")
;   #define RESC() do{ if(!FIXREF&&resc){ asm volatile("s_waitcnt lgkmcnt(0)":::"memory"); \
;       _Pragma("unroll") for(int d_=0;d_<2;++d_) _Pragma("unroll") for(int r=0;r<16;++r)o[d_][r]*=wsf[crow(r,hi)]; } }while(0)
;   #define ROT() do{sl_prev=sl_cur;sl_cur=sl_next;sl_next=(sl_next==(NSLOT-1)*SLOTB)?0:sl_next+SLOTB;}while(0)
;   #define ENDW(tt) do{ if((tt)+3<NT){WAIT_BAR(2);} else if((tt)+2<NT){WAIT_BAR(1);} else {WAIT_BAR(0);} }while(0)
; template<int THRL,bool FIXREF,bool HALFK> __device__ __forceinline__ void attn_unit(float mref,long rowbase,int q0,const bf16*Qh,int PQ,const bf16*__restrict__ Kh_,int PK,const bf16*__restrict__ Vh_,int PV,bf16*Oh,int PO,const bf16*Gh,int PG,u32x4(&okeep)[4],int omode,float lam,float oml,const float ...
;     ...
;   int t=1;
;     ...
;   for(;t+5<NT;t+=2){
;     STEP(pB0,pB1,pA0,pA1,t,true,true,true);     WAIT_BAR(2); RESC(); ROT();
;     STEP(pA0,pA1,pB0,pB1,t+1,true,true,true);   WAIT_BAR(2); RESC(); ROT();
;   }
;     ...
;   for(;t+1<NT;t+=2){
;     STEP(pB0,pB1,pA0,pA1,t,(t+3<NT),(t+1<NT),(t+1<NT));       ENDW(t);   RESC(); ROT();
;     STEP(pA0,pA1,pB0,pB1,t+1,(t+4<NT),(t+2<NT),(t+2<NT));     ENDW(t+1); RESC(); ROT();
;   }
	v_mfma_f32_32x32x16_bf16 v[130:145], v[94:97], v[154:157], v[130:145]
	v_add_f32_e32 v94, v108, v98
	v_add_f32_e32 v94, v109, v94
	v_add_f32_e32 v94, v110, v94
	v_add_f32_e32 v98, v111, v94
	v_cvt_pk_bf16_f32 v146, v106, v107
	v_cvt_pk_bf16_f32 v147, v108, v109
	ds_read_b64_tr_b16 v[94:95], v227 offset:48128
	ds_read_b64_tr_b16 v[96:97], v227 offset:48640
	v_mfma_f32_32x32x16_bf16 v[66:81], v[82:85], v[154:157], v[66:81]
	v_add_f32_e32 v82, v112, v98
	v_add_f32_e32 v82, v113, v82
	v_add_f32_e32 v82, 0, v82
	v_cvt_pk_bf16_f32 v148, v110, v111
	v_cvt_pk_bf16_f32 v149, v112, v113
	s_mov_b64 s[46:47], 0xfc000
	v_add_f32_e32 v229, v229, v82
	v_lshl_add_u64 v[82:83], v[210:211], 0, s[46:47]
	s_mov_b32 s41, m0
	s_mov_b32 m0, s62
	s_nop 0
	global_load_lds_dwordx4 v[82:83], off
	s_mov_b32 m0, s41
	v_lshl_add_u64 v[82:83], v[208:209], 0, s[6:7]
	s_add_i32 s41, s40, 0x8000
	s_mov_b32 s43, m0
	s_mov_b32 m0, s41
	s_nop 0
	global_load_lds_dwordx4 v[82:83], off
	s_mov_b32 m0, s43
	s_waitcnt lgkmcnt(14)
	v_mfma_f32_32x32x16_bf16 v[18:33], v[166:169], v[212:215], v[18:33]
	v_exp_f32_e32 v130, v130
	v_exp_f32_e32 v131, v131
	v_exp_f32_e32 v132, v132
	v_exp_f32_e32 v133, v133
	s_waitcnt lgkmcnt(12)
	v_mfma_f32_32x32x16_bf16 v[34:49], v[166:169], v[114:117], v[34:49]
	v_exp_f32_e32 v134, v134
	v_exp_f32_e32 v135, v135
	v_exp_f32_e32 v136, v136
	v_exp_f32_e32 v137, v137
	ds_read_b128 v[82:85], v228 offset:8192
	ds_read_b128 v[106:109], v228 offset:8704
	s_waitcnt lgkmcnt(12)
	v_mfma_f32_32x32x16_bf16 v[18:33], v[158:161], v[118:121], v[18:33]
	v_exp_f32_e32 v138, v138
	v_exp_f32_e32 v139, v139
	v_exp_f32_e32 v140, v140
	v_exp_f32_e32 v141, v141
	ds_read_b128 v[110:113], v228 offset:10240
	ds_read_b128 v[178:181], v228 offset:10752
	s_waitcnt lgkmcnt(12)
	v_mfma_f32_32x32x16_bf16 v[34:49], v[158:161], v[86:89], v[34:49]
	v_exp_f32_e32 v142, v142
	v_exp_f32_e32 v143, v143
	v_exp_f32_e32 v144, v144
	v_exp_f32_e32 v145, v145
	ds_read_b128 v[182:185], v228 offset:12288
	ds_read_b128 v[186:189], v228 offset:12800
	s_waitcnt lgkmcnt(12)
	v_mfma_f32_32x32x16_bf16 v[18:33], v[150:153], v[122:125], v[18:33]
	v_exp_f32_e32 v66, v66
	v_exp_f32_e32 v67, v67
	v_exp_f32_e32 v68, v68
	v_exp_f32_e32 v69, v69
	ds_read_b128 v[210:213], v228 offset:14336
	ds_read_b128 v[98:101], v228 offset:14848
	s_waitcnt lgkmcnt(12)
	v_mfma_f32_32x32x16_bf16 v[34:49], v[150:153], v[90:93], v[34:49]
	v_exp_f32_e32 v70, v70
	v_exp_f32_e32 v71, v71
	v_exp_f32_e32 v72, v72
	v_exp_f32_e32 v73, v73
	s_waitcnt lgkmcnt(10)
	v_mfma_f32_32x32x16_bf16 v[18:33], v[146:149], v[102:105], v[18:33]
	v_exp_f32_e32 v74, v74
	v_exp_f32_e32 v75, v75
	v_exp_f32_e32 v76, v76
	v_exp_f32_e32 v77, v77
	s_waitcnt lgkmcnt(8)
	v_mfma_f32_32x32x16_bf16 v[34:49], v[146:149], v[94:97], v[34:49]
	v_exp_f32_e32 v78, v78
	v_exp_f32_e32 v79, v79
	v_exp_f32_e32 v80, v80
	v_exp_f32_e32 v81, v81
	s_waitcnt vmcnt(2) lgkmcnt(0)
	s_barrier
	ds_read_b64_tr_b16 v[102:103], v227 offset:24576
	ds_read_b64_tr_b16 v[104:105], v227 offset:25088
	v_add_f32_e32 v86, v130, v131
	v_add_f32_e32 v86, v132, v86
	v_add_f32_e32 v86, v133, v86
	v_add_f32_e32 v86, v134, v86
	v_add_f32_e32 v86, v135, v86
	v_cvt_pk_bf16_f32 v166, v130, v131
	v_cvt_pk_bf16_f32 v167, v132, v133
	s_waitcnt lgkmcnt(9)
	v_mfma_f32_32x32x16_bf16 v[114:129], v[82:85], v[174:177], v[50:65]
	ds_read_b64_tr_b16 v[130:131], v227 offset:28672
	ds_read_b64_tr_b16 v[132:133], v227 offset:29184
	v_add_f32_e32 v82, v136, v86
	v_add_f32_e32 v82, v137, v82
	v_add_f32_e32 v82, v138, v82
	v_add_f32_e32 v146, v139, v82
	v_cvt_pk_bf16_f32 v168, v134, v135
	v_cvt_pk_bf16_f32 v169, v136, v137
	s_waitcnt lgkmcnt(10)
	v_mfma_f32_32x32x16_bf16 v[82:97], v[106:109], v[174:177], v[50:65]
	ds_read_b64_tr_b16 v[106:107], v227 offset:25600
	ds_read_b64_tr_b16 v[108:109], v227 offset:26112
	s_waitcnt lgkmcnt(11)
	v_mfma_f32_32x32x16_bf16 v[114:129], v[110:113], v[170:173], v[114:129]
	v_add_f32_e32 v110, v140, v146
	v_add_f32_e32 v110, v141, v110
	v_add_f32_e32 v110, v142, v110
	v_add_f32_e32 v134, v143, v110
	v_cvt_pk_bf16_f32 v158, v138, v139
	v_cvt_pk_bf16_f32 v159, v140, v141
	ds_read_b64_tr_b16 v[110:111], v227 offset:29696
	ds_read_b64_tr_b16 v[112:113], v227 offset:30208
	v_add_f32_e32 v134, v144, v134
	v_add_f32_e32 v134, v145, v134
	v_add_f32_e32 v134, v66, v134
	v_add_f32_e32 v138, v67, v134
	v_cvt_pk_bf16_f32 v160, v142, v143
	v_cvt_pk_bf16_f32 v161, v144, v145
	s_waitcnt lgkmcnt(12)
	v_mfma_f32_32x32x16_bf16 v[82:97], v[178:181], v[170:173], v[82:97]
	ds_read_b64_tr_b16 v[134:135], v227 offset:26624
	ds_read_b64_tr_b16 v[136:137], v227 offset:27136
	v_add_f32_e32 v138, v68, v138
	v_add_f32_e32 v138, v69, v138
	v_add_f32_e32 v138, v70, v138
	v_add_f32_e32 v138, v71, v138
	v_cvt_pk_bf16_f32 v150, v66, v67
	v_cvt_pk_bf16_f32 v151, v68, v69
	s_waitcnt lgkmcnt(13)
	v_mfma_f32_32x32x16_bf16 v[114:129], v[182:185], v[162:165], v[114:129]
	ds_read_b64_tr_b16 v[66:67], v227 offset:30720
	ds_read_b64_tr_b16 v[68:69], v227 offset:31232
	v_add_f32_e32 v138, v72, v138
	v_add_f32_e32 v138, v73, v138
	v_add_f32_e32 v138, v74, v138
	v_add_f32_e32 v138, v75, v138
	v_cvt_pk_bf16_f32 v152, v70, v71
	v_cvt_pk_bf16_f32 v153, v72, v73
	s_waitcnt lgkmcnt(14)
	v_mfma_f32_32x32x16_bf16 v[82:97], v[186:189], v[162:165], v[82:97]
	ds_read_b64_tr_b16 v[70:71], v227 offset:27648
	ds_read_b64_tr_b16 v[72:73], v227 offset:28160
	v_add_f32_e32 v138, v76, v138
	v_add_f32_e32 v138, v77, v138
	v_add_f32_e32 v138, v78, v138
	v_add_f32_e32 v138, v79, v138
	v_cvt_pk_bf16_f32 v146, v74, v75
	v_cvt_pk_bf16_f32 v147, v76, v77
	s_waitcnt lgkmcnt(14)
; #define WAIT_BAR(N) asm volatile("s_waitcnt vmcnt(" #N ") lgkmcnt(0)\n\ts_barrier":::"memory")
;   #define RESC() do{ if(!FIXREF&&resc){ asm volatile("s_waitcnt lgkmcnt(0)":::"memory"); \
;       _Pragma("unroll") for(int d_=0;d_<2;++d_) _Pragma("unroll") for(int r=0;r<16;++r)o[d_][r]*=wsf[crow(r,hi)]; } }while(0)
;   #define ROT() do{sl_prev=sl_cur;sl_cur=sl_next;sl_next=(sl_next==(NSLOT-1)*SLOTB)?0:sl_next+SLOTB;}while(0)
;   #define ENDW(tt) do{ if((tt)+3<NT){WAIT_BAR(2);} else if((tt)+2<NT){WAIT_BAR(1);} else {WAIT_BAR(0);} }while(0)
; template<int THRL,bool FIXREF,bool HALFK> __device__ __forceinline__ void attn_unit(float mref,long rowbase,int q0,const bf16*Qh,int PQ,const bf16*__restrict__ Kh_,int PK,const bf16*__restrict__ Vh_,int PV,bf16*Oh,int PO,const bf16*Gh,int PG,u32x4(&okeep)[4],int omode,float lam,float oml,const float ...
;     ...
;   int t=1;
;     ...
;   for(;t+5<NT;t+=2){
;     STEP(pB0,pB1,pA0,pA1,t,true,true,true);     WAIT_BAR(2); RESC(); ROT();
;     STEP(pA0,pA1,pB0,pB1,t+1,true,true,true);   WAIT_BAR(2); RESC(); ROT();
;   }
;     ...
;   for(;t+1<NT;t+=2){
;     STEP(pB0,pB1,pA0,pA1,t,(t+3<NT),(t+1<NT),(t+1<NT));       ENDW(t);   RESC(); ROT();
;     STEP(pA0,pA1,pB0,pB1,t+1,(t+4<NT),(t+2<NT),(t+2<NT));     ENDW(t+1); RESC(); ROT();
;   }
	v_mfma_f32_32x32x16_bf16 v[114:129], v[210:213], v[154:157], v[114:129]
	ds_read_b64_tr_b16 v[74:75], v227 offset:31744
	ds_read_b64_tr_b16 v[76:77], v227 offset:32256
	v_mfma_f32_32x32x16_bf16 v[82:97], v[98:101], v[154:157], v[82:97]
	v_add_f32_e32 v98, v80, v138
	v_add_f32_e32 v98, v81, v98
	v_add_f32_e32 v98, 0, v98
	v_cvt_pk_bf16_f32 v148, v78, v79
	v_cvt_pk_bf16_f32 v149, v80, v81
	v_lshl_add_u64 v[78:79], v[208:209], 0, s[94:95]
	s_add_i32 s40, s40, 0xa000
	s_mov_b32 s41, m0
	s_mov_b32 m0, s40
	s_nop 0
	global_load_lds_dwordx4 v[78:79], off
	s_mov_b32 m0, s41
	v_add_f32_e32 v214, v229, v98
	s_waitcnt lgkmcnt(14)
	v_mfma_f32_32x32x16_bf16 v[18:33], v[166:169], v[102:105], v[18:33]
	v_exp_f32_e32 v114, v114
	v_exp_f32_e32 v115, v115
	v_exp_f32_e32 v116, v116
	v_exp_f32_e32 v117, v117
	s_waitcnt lgkmcnt(12)
	v_mfma_f32_32x32x16_bf16 v[34:49], v[166:169], v[130:133], v[34:49]
	v_exp_f32_e32 v118, v118
	v_exp_f32_e32 v119, v119
	v_exp_f32_e32 v120, v120
	v_exp_f32_e32 v121, v121
	ds_read_b128 v[78:81], v228 offset:16384
	ds_read_b128 v[138:141], v228 offset:16896
	s_waitcnt lgkmcnt(12)
	v_mfma_f32_32x32x16_bf16 v[18:33], v[158:161], v[106:109], v[18:33]
	v_exp_f32_e32 v122, v122
	v_exp_f32_e32 v123, v123
	v_exp_f32_e32 v124, v124
	v_exp_f32_e32 v125, v125
	ds_read_b128 v[142:145], v228 offset:18432
	ds_read_b128 v[178:181], v228 offset:18944
	s_waitcnt lgkmcnt(12)
	v_mfma_f32_32x32x16_bf16 v[34:49], v[158:161], v[110:113], v[34:49]
	v_exp_f32_e32 v126, v126
	v_exp_f32_e32 v127, v127
	v_exp_f32_e32 v128, v128
	v_exp_f32_e32 v129, v129
	ds_read_b128 v[182:185], v228 offset:20480
	ds_read_b128 v[186:189], v228 offset:20992
	s_waitcnt lgkmcnt(12)
	v_mfma_f32_32x32x16_bf16 v[18:33], v[150:153], v[134:137], v[18:33]
	v_exp_f32_e32 v82, v82
	v_exp_f32_e32 v83, v83
	v_exp_f32_e32 v84, v84
	v_exp_f32_e32 v85, v85
	ds_read_b128 v[134:137], v228 offset:22528
	ds_read_b128 v[130:133], v228 offset:23040
	s_waitcnt lgkmcnt(12)
	v_mfma_f32_32x32x16_bf16 v[34:49], v[150:153], v[66:69], v[34:49]
	v_exp_f32_e32 v86, v86
	v_exp_f32_e32 v87, v87
	v_exp_f32_e32 v88, v88
	v_exp_f32_e32 v89, v89
	s_waitcnt lgkmcnt(10)
	v_mfma_f32_32x32x16_bf16 v[18:33], v[146:149], v[70:73], v[18:33]
	v_exp_f32_e32 v90, v90
	v_exp_f32_e32 v91, v91
	v_exp_f32_e32 v92, v92
	v_exp_f32_e32 v93, v93
	s_waitcnt lgkmcnt(8)
	v_mfma_f32_32x32x16_bf16 v[34:49], v[146:149], v[74:77], v[34:49]
	v_exp_f32_e32 v94, v94
	v_exp_f32_e32 v95, v95
	v_exp_f32_e32 v96, v96
	v_exp_f32_e32 v97, v97
	s_waitcnt vmcnt(1) lgkmcnt(0)
	s_barrier
	ds_read_b64_tr_b16 v[210:211], v227 offset:32768
	ds_read_b64_tr_b16 v[212:213], v227 offset:33280
	v_add_f32_e32 v66, v114, v115
	v_add_f32_e32 v66, v116, v66
	v_add_f32_e32 v66, v117, v66
	v_add_f32_e32 v66, v118, v66
	v_add_f32_e32 v66, v119, v66
	v_cvt_pk_bf16_f32 v166, v114, v115
	v_cvt_pk_bf16_f32 v167, v116, v117
	s_waitcnt lgkmcnt(9)
	v_mfma_f32_32x32x16_bf16 v[98:113], v[78:81], v[174:177], v[50:65]
	ds_read_b64_tr_b16 v[114:115], v227 offset:36864
	ds_read_b64_tr_b16 v[116:117], v227 offset:37376
	v_add_f32_e32 v66, v120, v66
	v_add_f32_e32 v66, v121, v66
	v_add_f32_e32 v66, v122, v66
	v_add_f32_e32 v146, v123, v66
	s_waitcnt lgkmcnt(10)
	v_mfma_f32_32x32x16_bf16 v[66:81], v[138:141], v[174:177], v[50:65]
	v_cvt_pk_bf16_f32 v168, v118, v119
	v_cvt_pk_bf16_f32 v169, v120, v121
	ds_read_b64_tr_b16 v[138:139], v227 offset:33792
	ds_read_b64_tr_b16 v[140:141], v227 offset:34304
	v_add_f32_e32 v118, v124, v146
	v_add_f32_e32 v118, v125, v118
	v_add_f32_e32 v118, v126, v118
	v_add_f32_e32 v118, v127, v118
	v_cvt_pk_bf16_f32 v158, v122, v123
	v_cvt_pk_bf16_f32 v159, v124, v125
	s_waitcnt lgkmcnt(11)
	v_mfma_f32_32x32x16_bf16 v[98:113], v[142:145], v[170:173], v[98:113]
	ds_read_b64_tr_b16 v[120:121], v227 offset:37888
	ds_read_b64_tr_b16 v[122:123], v227 offset:38400
	s_waitcnt lgkmcnt(12)
	v_mfma_f32_32x32x16_bf16 v[66:81], v[178:181], v[170:173], v[66:81]
	v_add_f32_e32 v118, v128, v118
	v_add_f32_e32 v118, v129, v118
	v_add_f32_e32 v118, v82, v118
	v_add_f32_e32 v118, v83, v118
	v_cvt_pk_bf16_f32 v160, v126, v127
	v_cvt_pk_bf16_f32 v161, v128, v129
	ds_read_b64_tr_b16 v[124:125], v227 offset:34816
	ds_read_b64_tr_b16 v[126:127], v227 offset:35328
	v_add_f32_e32 v118, v84, v118
	v_add_f32_e32 v118, v85, v118
	v_add_f32_e32 v118, v86, v118
	v_add_f32_e32 v118, v87, v118
	v_cvt_pk_bf16_f32 v150, v82, v83
	v_cvt_pk_bf16_f32 v151, v84, v85
	s_waitcnt lgkmcnt(13)
	v_mfma_f32_32x32x16_bf16 v[98:113], v[182:185], v[162:165], v[98:113]
	ds_read_b64_tr_b16 v[82:83], v227 offset:38912
	ds_read_b64_tr_b16 v[84:85], v227 offset:39424
	s_waitcnt lgkmcnt(14)
	v_mfma_f32_32x32x16_bf16 v[66:81], v[186:189], v[162:165], v[66:81]
	v_add_f32_e32 v118, v88, v118
	v_add_f32_e32 v118, v89, v118
	v_add_f32_e32 v118, v90, v118
	v_add_f32_e32 v118, v91, v118
	v_cvt_pk_bf16_f32 v152, v86, v87
	v_cvt_pk_bf16_f32 v153, v88, v89
	ds_read_b64_tr_b16 v[86:87], v227 offset:35840
	ds_read_b64_tr_b16 v[88:89], v227 offset:36352
	v_add_f32_e32 v118, v92, v118
	v_add_f32_e32 v118, v93, v118
	v_add_f32_e32 v118, v94, v118
	v_add_f32_e32 v118, v95, v118
	v_cvt_pk_bf16_f32 v146, v90, v91
	v_cvt_pk_bf16_f32 v147, v92, v93
	s_waitcnt lgkmcnt(14)
	v_mfma_f32_32x32x16_bf16 v[98:113], v[134:137], v[154:157], v[98:113]
	ds_read_b64_tr_b16 v[90:91], v227 offset:39936
	ds_read_b64_tr_b16 v[92:93], v227 offset:40448
	v_mfma_f32_32x32x16_bf16 v[66:81], v[130:133], v[154:157], v[66:81]
	v_add_f32_e32 v118, v96, v118
	v_add_f32_e32 v118, v97, v118
	v_add_f32_e32 v118, 0, v118
	v_cvt_pk_bf16_f32 v148, v94, v95
	v_cvt_pk_bf16_f32 v149, v96, v97
	v_lshl_add_u64 v[94:95], v[208:209], 0, s[26:27]
	s_mov_b32 s40, m0
	s_mov_b32 m0, s61
	s_nop 0
	global_load_lds_dwordx4 v[94:95], off
	s_mov_b32 m0, s40
	v_add_f32_e32 v118, v214, v118
	s_waitcnt lgkmcnt(14)
; #define WAIT_BAR(N) asm volatile("s_waitcnt vmcnt(" #N ") lgkmcnt(0)\n\ts_barrier":::"memory")
;   #define RESC() do{ if(!FIXREF&&resc){ asm volatile("s_waitcnt lgkmcnt(0)":::"memory"); \
;       _Pragma("unroll") for(int d_=0;d_<2;++d_) _Pragma("unroll") for(int r=0;r<16;++r)o[d_][r]*=wsf[crow(r,hi)]; } }while(0)
;   #define ROT() do{sl_prev=sl_cur;sl_cur=sl_next;sl_next=(sl_next==(NSLOT-1)*SLOTB)?0:sl_next+SLOTB;}while(0)
;   #define ENDW(tt) do{ if((tt)+3<NT){WAIT_BAR(2);} else if((tt)+2<NT){WAIT_BAR(1);} else {WAIT_BAR(0);} }while(0)
; template<int THRL,bool FIXREF,bool HALFK> __device__ __forceinline__ void attn_unit(float mref,long rowbase,int q0,const bf16*Qh,int PQ,const bf16*__restrict__ Kh_,int PK,const bf16*__restrict__ Vh_,int PV,bf16*Oh,int PO,const bf16*Gh,int PG,u32x4(&okeep)[4],int omode,float lam,float oml,const float ...
;     ...
;   int t=1;
;     ...
;   for(;t+5<NT;t+=2){
;     STEP(pB0,pB1,pA0,pA1,t,true,true,true);     WAIT_BAR(2); RESC(); ROT();
;     STEP(pA0,pA1,pB0,pB1,t+1,true,true,true);   WAIT_BAR(2); RESC(); ROT();
;   }
;     ...
;   for(;t+1<NT;t+=2){
;     STEP(pB0,pB1,pA0,pA1,t,(t+3<NT),(t+1<NT),(t+1<NT));       ENDW(t);   RESC(); ROT();
;     STEP(pA0,pA1,pB0,pB1,t+1,(t+4<NT),(t+2<NT),(t+2<NT));     ENDW(t+1); RESC(); ROT();
;   }
;   STEP(pB0,pB1,pA0,pA1,NT-1,false,false,false); RESC();
	v_mfma_f32_32x32x16_bf16 v[18:33], v[166:169], v[210:213], v[18:33]
	v_exp_f32_e32 v98, v98
	v_exp_f32_e32 v99, v99
	v_exp_f32_e32 v100, v100
	v_exp_f32_e32 v101, v101
	s_waitcnt lgkmcnt(12)
	v_mfma_f32_32x32x16_bf16 v[34:49], v[166:169], v[114:117], v[34:49]
	v_exp_f32_e32 v102, v102
	v_exp_f32_e32 v103, v103
	v_exp_f32_e32 v104, v104
	v_exp_f32_e32 v105, v105
	ds_read_b128 v[128:131], v228
	ds_read_b128 v[132:135], v228 offset:512
	s_waitcnt lgkmcnt(12)
	v_mfma_f32_32x32x16_bf16 v[18:33], v[158:161], v[138:141], v[18:33]
	v_exp_f32_e32 v106, v106
	v_exp_f32_e32 v107, v107
	v_exp_f32_e32 v108, v108
	v_exp_f32_e32 v109, v109
	ds_read_b128 v[136:139], v228 offset:2048
	ds_read_b128 v[140:143], v228 offset:2560
	s_waitcnt lgkmcnt(12)
	v_mfma_f32_32x32x16_bf16 v[34:49], v[158:161], v[120:123], v[34:49]
	v_exp_f32_e32 v110, v110
	v_exp_f32_e32 v111, v111
	v_exp_f32_e32 v112, v112
	v_exp_f32_e32 v113, v113
	ds_read_b128 v[120:123], v228 offset:4096
	ds_read_b128 v[178:181], v228 offset:4608
	s_waitcnt lgkmcnt(12)
	v_mfma_f32_32x32x16_bf16 v[18:33], v[150:153], v[124:127], v[18:33]
	v_exp_f32_e32 v66, v66
	v_exp_f32_e32 v67, v67
	v_exp_f32_e32 v68, v68
	v_exp_f32_e32 v69, v69
	ds_read_b128 v[124:127], v228 offset:6144
	ds_read_b128 v[114:117], v228 offset:6656
	s_waitcnt lgkmcnt(12)
	v_mfma_f32_32x32x16_bf16 v[34:49], v[150:153], v[82:85], v[34:49]
	v_exp_f32_e32 v70, v70
	v_exp_f32_e32 v71, v71
	v_exp_f32_e32 v72, v72
	v_exp_f32_e32 v73, v73
	s_waitcnt lgkmcnt(10)
	v_mfma_f32_32x32x16_bf16 v[18:33], v[146:149], v[86:89], v[18:33]
	v_exp_f32_e32 v74, v74
	v_exp_f32_e32 v75, v75
	v_exp_f32_e32 v76, v76
	v_exp_f32_e32 v77, v77
	s_waitcnt lgkmcnt(8)
	v_mfma_f32_32x32x16_bf16 v[34:49], v[146:149], v[90:93], v[34:49]
	v_exp_f32_e32 v78, v78
	v_exp_f32_e32 v79, v79
	v_exp_f32_e32 v80, v80
	v_exp_f32_e32 v81, v81
	s_waitcnt vmcnt(0) lgkmcnt(0)
	s_barrier
	ds_read_b64_tr_b16 v[182:183], v227 offset:40960
	ds_read_b64_tr_b16 v[184:185], v227 offset:41472
	v_add_f32_e32 v82, v98, v99
	v_add_f32_e32 v82, v100, v82
	v_add_f32_e32 v82, v101, v82
	v_add_f32_e32 v82, v102, v82
	v_add_f32_e32 v119, v103, v82
	v_cvt_pk_bf16_f32 v166, v98, v99
	v_cvt_pk_bf16_f32 v167, v100, v101
	s_waitcnt lgkmcnt(9)
	v_mfma_f32_32x32x16_bf16 v[82:97], v[128:131], v[174:177], v[50:65]
	ds_read_b64_tr_b16 v[98:99], v227 offset:45056
	ds_read_b64_tr_b16 v[100:101], v227 offset:45568
	v_add_f32_e32 v119, v104, v119
	v_add_f32_e32 v119, v105, v119
	v_add_f32_e32 v119, v106, v119
	v_add_f32_e32 v119, v107, v119
	v_cvt_pk_bf16_f32 v168, v102, v103
	v_cvt_pk_bf16_f32 v169, v104, v105
	s_waitcnt lgkmcnt(10)
	v_mfma_f32_32x32x16_bf16 v[50:65], v[132:135], v[174:177], v[50:65]
	ds_read_b64_tr_b16 v[102:103], v227 offset:41984
	ds_read_b64_tr_b16 v[104:105], v227 offset:42496
	v_add_f32_e32 v119, v108, v119
	v_add_f32_e32 v119, v109, v119
	v_add_f32_e32 v119, v110, v119
	v_add_f32_e32 v119, v111, v119
	v_cvt_pk_bf16_f32 v158, v106, v107
	v_cvt_pk_bf16_f32 v159, v108, v109
	s_waitcnt lgkmcnt(11)
	v_mfma_f32_32x32x16_bf16 v[82:97], v[136:139], v[170:173], v[82:97]
	ds_read_b64_tr_b16 v[106:107], v227 offset:46080
	ds_read_b64_tr_b16 v[108:109], v227 offset:46592
	v_add_f32_e32 v119, v112, v119
	v_add_f32_e32 v119, v113, v119
	v_add_f32_e32 v119, v66, v119
	v_add_f32_e32 v119, v67, v119
	v_cvt_pk_bf16_f32 v160, v110, v111
	v_cvt_pk_bf16_f32 v161, v112, v113
	s_waitcnt lgkmcnt(12)
	v_mfma_f32_32x32x16_bf16 v[50:65], v[140:143], v[170:173], v[50:65]
	ds_read_b64_tr_b16 v[110:111], v227 offset:43008
	ds_read_b64_tr_b16 v[112:113], v227 offset:43520
	v_add_f32_e32 v119, v68, v119
	v_add_f32_e32 v119, v69, v119
	v_add_f32_e32 v119, v70, v119
	v_add_f32_e32 v119, v71, v119
	v_cvt_pk_bf16_f32 v150, v66, v67
	v_cvt_pk_bf16_f32 v151, v68, v69
	s_waitcnt lgkmcnt(13)
	v_mfma_f32_32x32x16_bf16 v[82:97], v[120:123], v[162:165], v[82:97]
	ds_read_b64_tr_b16 v[66:67], v227 offset:47104
	ds_read_b64_tr_b16 v[68:69], v227 offset:47616
	v_add_f32_e32 v119, v72, v119
	v_add_f32_e32 v119, v73, v119
	v_add_f32_e32 v119, v74, v119
	v_add_f32_e32 v119, v75, v119
	v_cvt_pk_bf16_f32 v152, v70, v71
	v_cvt_pk_bf16_f32 v153, v72, v73
	s_waitcnt lgkmcnt(14)
	v_mfma_f32_32x32x16_bf16 v[50:65], v[178:181], v[162:165], v[50:65]
	ds_read_b64_tr_b16 v[70:71], v227 offset:44032
	ds_read_b64_tr_b16 v[72:73], v227 offset:44544
	v_add_f32_e32 v119, v76, v119
	v_add_f32_e32 v119, v77, v119
	v_add_f32_e32 v119, v78, v119
	v_add_f32_e32 v119, v79, v119
	v_cvt_pk_bf16_f32 v146, v74, v75
	v_cvt_pk_bf16_f32 v147, v76, v77
	s_waitcnt lgkmcnt(14)
; #define SBAR() __builtin_amdgcn_sched_barrier(0)
;   #define RESC() do{ if(!FIXREF&&resc){ asm volatile("s_waitcnt lgkmcnt(0)":::"memory"); \
;       _Pragma("unroll") for(int d_=0;d_<2;++d_) _Pragma("unroll") for(int r=0;r<16;++r)o[d_][r]*=wsf[crow(r,hi)]; } }while(0)
;   #define PKW(P,B) cvtpk_s(P[B],P[B+1])
; template<int THRL,bool FIXREF,bool HALFK> __device__ __forceinline__ void attn_unit(float mref,long rowbase,int q0,const bf16*Qh,int PQ,const bf16*__restrict__ Kh_,int PK,const bf16*__restrict__ Vh_,int PV,bf16*Oh,int PO,const bf16*Gh,int PG,u32x4(&okeep)[4],int omode,float lam,float oml,const float ...
;     ...
;   STEP(pB0,pB1,pA0,pA1,NT-1,false,false,false); RESC();
;   { float sacc=pB0[0]+pB0[1]; _Pragma("unroll") for(int r=2;r<16;++r)sacc+=pB0[r]; _Pragma("unroll") for(int r=0;r<16;++r)sacc+=pB1[r]; l_reg+=sacc;
;     pw0=(u32x4){PKW(pB0,0),PKW(pB0,2),PKW(pB0,4),PKW(pB0,6)};pw1=(u32x4){PKW(pB0,8),PKW(pB0,10),PKW(pB0,12),PKW(pB0,14)};pw2=(u32x4){PKW(pB1,0),PKW(pB1,2),PKW(pB1,4),PKW(pB1,6)};pw3=(u32x4){PKW(pB1,8),PKW(pB1,10),PKW(pB1,12),PKW(pB1,14)};
;     SBAR(); pv(o,vb0+sl_cur,PAF(0),PAF(1),PAF(2),PAF(3)); }
;     ...
;   {auto rr=__builtin_amdgcn_permlane32_swap(__float_as_uint(l_reg),__float_as_uint(l_reg),false,false);l_reg=__uint_as_float(rr[0])+__uint_as_float(rr[1]);}
;   if(hi==0)wsf[32+r32]=l_reg;asm volatile("s_waitcnt lgkmcnt(0)":::"memory");
	v_mfma_f32_32x32x16_bf16 v[82:97], v[124:127], v[154:157], v[82:97]
	ds_read_b64_tr_b16 v[74:75], v227 offset:48128
	ds_read_b64_tr_b16 v[76:77], v227 offset:48640
	v_mfma_f32_32x32x16_bf16 v[50:65], v[114:117], v[154:157], v[50:65]
	v_add_f32_e32 v114, v80, v119
	v_add_f32_e32 v114, v81, v114
	v_add_f32_e32 v114, 0, v114
	v_cvt_pk_bf16_f32 v148, v78, v79
	v_cvt_pk_bf16_f32 v149, v80, v81
	s_waitcnt lgkmcnt(14)
	v_mfma_f32_32x32x16_bf16 v[18:33], v[166:169], v[182:185], v[18:33]
	s_nop 1
	v_exp_f32_e32 v82, v82
	v_exp_f32_e32 v83, v83
	v_exp_f32_e32 v84, v84
	v_exp_f32_e32 v85, v85
	s_waitcnt lgkmcnt(12)
	v_mfma_f32_32x32x16_bf16 v[34:49], v[166:169], v[98:101], v[34:49]
	v_exp_f32_e32 v86, v86
	v_exp_f32_e32 v87, v87
	v_exp_f32_e32 v88, v88
	v_exp_f32_e32 v89, v89
	s_waitcnt lgkmcnt(10)
	v_mfma_f32_32x32x16_bf16 v[18:33], v[158:161], v[102:105], v[18:33]
	v_exp_f32_e32 v90, v90
	v_exp_f32_e32 v91, v91
	v_exp_f32_e32 v92, v92
	v_exp_f32_e32 v93, v93
	s_waitcnt lgkmcnt(8)
	v_mfma_f32_32x32x16_bf16 v[34:49], v[158:161], v[106:109], v[34:49]
	v_exp_f32_e32 v94, v94
	v_exp_f32_e32 v95, v95
	v_exp_f32_e32 v96, v96
	v_exp_f32_e32 v97, v97
	s_waitcnt lgkmcnt(6)
	v_mfma_f32_32x32x16_bf16 v[18:33], v[150:153], v[110:113], v[18:33]
	v_exp_f32_e32 v50, v50
	v_exp_f32_e32 v51, v51
	v_exp_f32_e32 v52, v52
	v_exp_f32_e32 v53, v53
	s_waitcnt lgkmcnt(4)
	v_mfma_f32_32x32x16_bf16 v[34:49], v[150:153], v[66:69], v[34:49]
	v_exp_f32_e32 v54, v54
	v_exp_f32_e32 v55, v55
	v_exp_f32_e32 v56, v56
	v_exp_f32_e32 v57, v57
	s_waitcnt lgkmcnt(2)
	v_mfma_f32_32x32x16_bf16 v[18:33], v[146:149], v[70:73], v[18:33]
	v_exp_f32_e32 v58, v58
	v_exp_f32_e32 v59, v59
	v_exp_f32_e32 v60, v60
	v_exp_f32_e32 v61, v61
	s_waitcnt lgkmcnt(0)
	v_mfma_f32_32x32x16_bf16 v[34:49], v[146:149], v[74:77], v[34:49]
	v_exp_f32_e32 v62, v62
	v_exp_f32_e32 v63, v63
	v_exp_f32_e32 v64, v64
	v_exp_f32_e32 v65, v65
	v_add_f32_e32 v66, v82, v83
	v_add_f32_e32 v66, v84, v66
	v_add_f32_e32 v66, v85, v66
	v_add_f32_e32 v66, v86, v66
	v_add_f32_e32 v66, v87, v66
	v_add_f32_e32 v66, v88, v66
	v_add_f32_e32 v66, v89, v66
	v_add_f32_e32 v66, v90, v66
	v_add_f32_e32 v66, v91, v66
	v_add_f32_e32 v66, v92, v66
	v_add_f32_e32 v66, v93, v66
	v_add_f32_e32 v66, v94, v66
	v_add_f32_e32 v66, v95, v66
	v_add_f32_e32 v66, v96, v66
	v_add_f32_e32 v66, v97, v66
	v_add_f32_e32 v66, v50, v66
	v_add_f32_e32 v66, v51, v66
	v_add_f32_e32 v66, v52, v66
	v_add_f32_e32 v66, v53, v66
	v_add_f32_e32 v66, v54, v66
	v_add_f32_e32 v66, v55, v66
	v_add_f32_e32 v66, v56, v66
	v_add_f32_e32 v66, v57, v66
	v_add_f32_e32 v66, v58, v66
	v_add_f32_e32 v66, v59, v66
	v_add_f32_e32 v66, v60, v66
	v_add_f32_e32 v66, v61, v66
	v_add_f32_e32 v66, v62, v66
	v_add_f32_e32 v66, v63, v66
	v_add_f32_e32 v66, v64, v66
	v_add_f32_e32 v66, v65, v66
	v_add_f32_e32 v67, v118, v114
	v_add_f32_e32 v66, v67, v66
	v_cvt_pk_bf16_f32 v68, v82, v83
	v_cvt_pk_bf16_f32 v69, v84, v85
	v_cvt_pk_bf16_f32 v70, v86, v87
	v_cvt_pk_bf16_f32 v71, v88, v89
	v_cvt_pk_bf16_f32 v72, v90, v91
	v_cvt_pk_bf16_f32 v73, v92, v93
	v_cvt_pk_bf16_f32 v74, v94, v95
	v_cvt_pk_bf16_f32 v75, v96, v97
	v_cvt_pk_bf16_f32 v50, v50, v51
	v_cvt_pk_bf16_f32 v51, v52, v53
	v_cvt_pk_bf16_f32 v52, v54, v55
	v_cvt_pk_bf16_f32 v53, v56, v57
	v_cvt_pk_bf16_f32 v54, v58, v59
	v_cvt_pk_bf16_f32 v55, v60, v61
	v_cvt_pk_bf16_f32 v56, v62, v63
	v_cvt_pk_bf16_f32 v57, v64, v65
	ds_read_b64_tr_b16 v[58:59],v0 offset:0
	ds_read_b64_tr_b16 v[60:61],v0 offset:512
	ds_read_b64_tr_b16 v[62:63],v0 offset:1024
	ds_read_b64_tr_b16 v[64:65],v0 offset:1536
	ds_read_b64_tr_b16 v[76:77],v0 offset:2048
	ds_read_b64_tr_b16 v[78:79],v0 offset:2560
	ds_read_b64_tr_b16 v[80:81],v0 offset:3072
	ds_read_b64_tr_b16 v[82:83],v0 offset:3584
	s_waitcnt lgkmcnt(0)
	s_nop 0
	v_mfma_f32_32x32x16_bf16 v[18:33], v[68:71], v[58:61], v[18:33]
	ds_read_b64_tr_b16 v[58:59],v0 offset:4096
	ds_read_b64_tr_b16 v[60:61],v0 offset:4608
	v_mfma_f32_32x32x16_bf16 v[18:33], v[72:75], v[62:65], v[18:33]
	ds_read_b64_tr_b16 v[62:63],v0 offset:5120
	ds_read_b64_tr_b16 v[64:65],v0 offset:5632
	v_mfma_f32_32x32x16_bf16 v[18:33], v[50:53], v[76:79], v[18:33]
	ds_read_b64_tr_b16 v[76:77],v0 offset:6144
	ds_read_b64_tr_b16 v[78:79],v0 offset:6656
	v_mfma_f32_32x32x16_bf16 v[18:33], v[54:57], v[80:83], v[18:33]
	ds_read_b64_tr_b16 v[80:81],v0 offset:7168
	ds_read_b64_tr_b16 v[82:83],v0 offset:7680
	s_waitcnt lgkmcnt(0)
	v_mfma_f32_32x32x16_bf16 v[34:49], v[68:71], v[58:61], v[34:49]
	v_mov_b32_e32 v0, v66
	s_nop 1
	v_permlane32_swap_b32_e32 v66, v0
	v_cmp_gt_u32_e32 vcc, 32, v205
	v_mfma_f32_32x32x16_bf16 v[34:49], v[72:75], v[62:65], v[34:49]
	v_mfma_f32_32x32x16_bf16 v[34:49], v[50:53], v[76:79], v[34:49]
	v_mfma_f32_32x32x16_bf16 v[34:49], v[54:57], v[80:83], v[34:49]
	s_and_saveexec_b64 s[40:41], vcc
	s_cbranch_execz .LBB0_449
	v_lshl_add_u32 v50, v216, 2, s42
	v_add_f32_e32 v0, v66, v0
	ds_write_b32 v50, v0 offset:49280
	s_branch .LBB0_449

;   #define CMASK(P0,P1,t) do{}while(0)
;   #define CMASK(P0,P1,t) do{}while(0)
; template<int THRL,bool FIXREF,bool HALFK> __device__ __forceinline__ void attn_unit(float mref,long rowbase,int q0,const bf16*Qh,int PQ,const bf16*__restrict__ Kh_,int PK,const bf16*__restrict__ Vh_,int PV,bf16*Oh,int PO,const bf16*Gh,int PG,u32x4(&okeep)[4],int omode,float lam,float oml,const float ...
;   const int tid=fresh_tid(),lane=tid&63,r32=lane&31,hi=lane>>5; const int wid=__builtin_amdgcn_readfirstlane(tid>>6);
;   const bf16*Qw=Qh+(rowbase+q0+wid*QBLK)*PQ;
;   const bf16*Kh=Kh_+rowbase*PK,*Vh=Vh_+rowbase*PV;
;   const unsigned lds0=(unsigned)(uintptr_t)shm;
;   float*wsf=(float*)(shm+LDS_WS)+wid*64;
;   const bf16*ksrc=Kh+(long)lane*PK+wid*8;
;   const bf16*vsrc=Vh+(long)(16*(wid&3)+(lane>>2))*PV+(wid>>2)*32+(lane&3)*8;
;   const unsigned kdst=lds0+LDS_K+wid*1024, vdst=lds0+LDS_V+wid*1024;
;     ...
;   const int vb0=(int)(lds0+LDS_V)+((lane>>4)&1)*32+(lane&3)*8+(4*hi+((lane&15)>>2))*64;
;   const char*Kbase=shm+LDS_K; bf16x8 kf[8];
;   const lds_cptr shm3=(lds_cptr)shm; const lds_cptr kp0=shm3+LDS_K+hi*1024+r32*16; const lds_cptr vp0=shm3+LDS_V+((lane>>4)&1)*32+(lane&3)*8+(4*hi+((lane&15)>>2))*64;
;   constexpr int NT=SEQ/KVBLK;
;   if(Gh){ const bf16*Gw=Gh+(rowbase+q0+wid*QBLK)*PG;
;     #pragma unroll
;     for(int i=0;i<4;++i) glds16(Gw+(long)(i*8+(lane>>3))*PG+(lane&7)*8,(unsigned)__builtin_amdgcn_readfirstlane(lds0+LDS_GST+wid*4096+i*1024)); }
;   DMA_K(0,0);DMA_V(0,0);DMA_K(1,SLOTB);
;   bf16x8 qr[4];
;   #pragma unroll
;   for(int d0=0;d0<4;++d0)qr[d0]=*reinterpret_cast<const bf16x8*>(&Qw[(long)r32*PQ+d0*16+hi*8]);
;   float mhat=0.f,l_reg=0.f;f32x16 o[2];o[0]=f32x16{};o[1]=f32x16{};f32x16 negm=f32x16{};
;   if constexpr(FIXREF){ mhat=mref; _Pragma("unroll") for(int r=0;r<16;++r)negm[r]=-mref; }
;   asm volatile("":"+v"(negm));
;     ...
;   bool resc=false;
;     ...
;   f32x16 pA0,pA1,pB0,pB1;
;   int sl_prev=0,sl_cur=0,sl_next=SLOTB;
;     ...
;   DMA_K(2,2*SLOTB);
;   WAIT_BAR(3);
;   qkt<HALFK?2:4>(pA0,pA1,Kbase,qr,negm,r32,hi);asm volatile("s_nop 15\n\ts_nop 7":"+v"(pA0),"+v"(pA1));CMASK(pA0,pA1,0);
;   START(pA0,pA1);
;   _Pragma("unroll") for(int r=0;r<16;++r)pA1[r]=__builtin_amdgcn_exp2f(pA1[r]);
;   WAIT_BAR(0);
;   DMA_K(3,0);DMA_V(1,SLOTB);
;   ROT();
;   if constexpr(HALFK){ kload2(kf,kp0+sl_cur,0); kload2(kf,kp0+sl_cur,1); } else kload8(kf,kp0+sl_cur);
;   WAIT_BAR(2);
.LBB0_460:
	s_or_b32 s20, s88, s68
	s_xor_b64 s[42:43], s[42:43], -1
	s_xor_b64 s[40:41], s[48:49], -1
	s_lshl_b64 s[48:49], s[20:21], 1
	s_add_u32 s20, s2, s48
	s_addc_u32 s80, s3, s49
	s_lshl_b64 s[50:51], s[46:47], 9
	s_add_u32 s84, s20, s50
	s_addc_u32 s85, s80, s51
	s_add_u32 s48, s71, s48
	s_addc_u32 s49, s73, s49
	v_lshlrev_b32_e32 v0, 9, v209
	v_lshl_add_u64 v[18:19], s[48:49], 0, v[0:1]
	s_lshl_b32 s48, s79, 3
	s_ashr_i32 s49, s48, 31
	s_lshl_b64 s[48:49], s[48:49], 1
	v_lshl_add_u64 v[174:175], v[18:19], 0, s[48:49]
	s_lshl_b32 s20, s79, 4
	v_lshrrev_b32_e32 v18, 2, v209
	v_and_or_b32 v18, s20, 48, v18
	s_ashr_i32 s20, s83, 3
	s_and_b32 s50, s20, 0xffffffe0
	s_ashr_i32 s51, s50, 31
	v_mul_u32_u24_e32 v18, 0xf00, v18
	s_lshl_b64 s[50:51], s[50:51], 1
	s_lshl_b32 s82, s79, 10
	v_lshlrev_b32_e32 v104, 1, v18
	v_mov_b32_e32 v105, v1
	s_cmp_lg_u32 0, -1
	v_lshl_add_u64 v[18:19], s[16:17], 0, v[104:105]
	v_and_b32_e32 v215, 24, v211
	s_cselect_b32 s20, 0, 0
	v_lshl_add_u64 v[18:19], v[18:19], 0, s[50:51]
	v_lshlrev_b32_e32 v20, 1, v215
	v_mov_b32_e32 v21, v1
	s_add_i32 s81, s82, s20
	s_mov_b32 s20, m0
	s_mov_b32 m0, s81
	s_nop 0
	global_load_lds_dwordx4 v[174:175], off
	s_mov_b32 m0, s20
	v_and_b32_e32 v171, 31, v102
	v_lshl_add_u64 v[172:173], v[18:19], 0, v[20:21]
	s_add_i32 s80, s81, 0x6000
	s_mov_b32 s20, m0
	s_mov_b32 m0, s80
	s_nop 0
	global_load_lds_dwordx4 v[172:173], off
	s_mov_b32 m0, s20
	v_lshl_add_u64 v[18:19], v[174:175], 0, s[10:11]
	v_lshrrev_b32_e32 v212, 5, v209
	s_add_i32 s20, s81, 0x2000
	s_mov_b32 s86, m0
	s_mov_b32 m0, s20
	s_nop 0
	global_load_lds_dwordx4 v[18:19], off
	s_mov_b32 m0, s86
	v_lshlrev_b32_e32 v18, 9, v171
	v_lshl_or_b32 v18, v212, 4, v18
	global_load_dwordx4 v[166:169], v18, s[84:85]
	global_load_dwordx4 v[162:165], v18, s[84:85] offset:32
	v_mov_b64_e32 v[64:65], v[16:17]
	v_mov_b64_e32 v[62:63], v[14:15]
	v_mov_b64_e32 v[60:61], v[12:13]
	v_mov_b64_e32 v[58:59], v[10:11]
	v_mov_b64_e32 v[56:57], v[8:9]
	v_mov_b64_e32 v[54:55], v[6:7]
	v_mov_b64_e32 v[52:53], v[4:5]
	v_mov_b64_e32 v[50:51], v[2:3]
	v_lshlrev_b32_e32 v18, 10, v212
	v_lshlrev_b32_e32 v19, 4, v171
	v_add3_u32 v214, 0, v18, v19
	v_lshl_add_u64 v[18:19], v[174:175], 0, s[92:93]
	s_add_i32 s20, s81, 0x4000
	s_mov_b32 s84, m0
	s_mov_b32 m0, s20
	s_nop 0
	global_load_lds_dwordx4 v[18:19], off
	s_mov_b32 m0, s84
	s_waitcnt vmcnt(3) lgkmcnt(0)
	s_barrier
	ds_read_b128 v[18:21], v214
	ds_read_b128 v[66:69], v214 offset:512
	ds_read_b128 v[70:73], v214 offset:2560
	ds_read_b128 v[74:77], v214 offset:2048
	v_lshl_add_u64 v[98:99], v[174:175], 0, s[36:37]
	v_lshl_add_u64 v[100:101], v[172:173], 0, s[22:23]
	s_add_i32 s20, s81, 0x8000
	v_mov_b32_e32 v227, 0
	s_mov_b32 s84, -1
	s_mov_b32 s87, 0
	s_movk_i32 s86, 0x2000
	s_movk_i32 s85, 0x4000
	s_waitcnt vmcnt(1) lgkmcnt(3)
	v_mfma_f32_32x32x16_bf16 v[34:49], v[18:21], v[166:169], v[50:65]
	s_waitcnt lgkmcnt(2)
	v_mfma_f32_32x32x16_bf16 v[18:33], v[66:69], v[166:169], v[50:65]
	v_lshlrev_b32_e32 v66, 1, v102
	v_lshlrev_b32_e32 v67, 4, v102
	v_and_b32_e32 v216, 32, v66
	v_and_b32_e32 v66, 0xc0, v67
	v_lshl_or_b32 v217, v212, 8, v66
	v_add_u32_e32 v66, 0, v216
	v_add3_u32 v213, v66, v215, v217
	s_waitcnt vmcnt(0) lgkmcnt(0)
	v_mfma_f32_32x32x16_bf16 v[34:49], v[74:77], v[162:165], v[34:49]
	v_mfma_f32_32x32x16_bf16 v[18:33], v[70:73], v[162:165], v[18:33]
	s_nop 15
	s_nop 7
	s_waitcnt vmcnt(0) lgkmcnt(0)
	s_barrier
	s_mov_b32 s89, m0
	s_mov_b32 m0, s81
	s_nop 0
	global_load_lds_dwordx4 v[98:99], off
	s_mov_b32 m0, s89
	s_nop 0
	s_mov_b32 s89, m0
	s_mov_b32 m0, s20
	s_nop 0
	global_load_lds_dwordx4 v[100:101], off
	s_mov_b32 m0, s89
	s_nop 10
	v_exp_f32_e32 v66, v18
	ds_read_b128 v[98:101], v214 offset:8192
	ds_read_b128 v[134:137], v214 offset:8704
	ds_read_b128 v[138:141], v214 offset:10240
	ds_read_b128 v[130:133], v214 offset:10752
	v_and_b32_e32 v18, 3, v102
	s_add_i32 s20, s67, s88
	v_exp_f32_e32 v67, v19
	v_lshl_or_b32 v18, v18, 4, s50
	v_subrev_u32_e32 v18, s50, v18
	s_add_u32 s38, s34, s50
	s_addc_u32 s39, s35, s51
	s_lshl_b64 s[50:51], s[20:21], 1
	s_add_u32 s20, s77, s50
	v_exp_f32_e32 v82, v34
	v_exp_f32_e32 v83, v35
	v_exp_f32_e32 v84, v36
	v_exp_f32_e32 v85, v37
	v_exp_f32_e32 v86, v38
	v_exp_f32_e32 v87, v39
	v_exp_f32_e32 v88, v40
	v_exp_f32_e32 v89, v41
	v_exp_f32_e32 v90, v42
	v_exp_f32_e32 v91, v43
	v_exp_f32_e32 v92, v44
	v_exp_f32_e32 v93, v45
	v_exp_f32_e32 v94, v46
	v_exp_f32_e32 v95, v47
	v_exp_f32_e32 v96, v48
	v_exp_f32_e32 v97, v49
	v_exp_f32_e32 v68, v20
	v_exp_f32_e32 v69, v21
	v_exp_f32_e32 v70, v22
	v_exp_f32_e32 v71, v23
	v_exp_f32_e32 v72, v24
	v_exp_f32_e32 v73, v25
	v_exp_f32_e32 v74, v26
	v_exp_f32_e32 v75, v27
	v_exp_f32_e32 v76, v28
	v_exp_f32_e32 v77, v29
	v_exp_f32_e32 v78, v30
	v_exp_f32_e32 v79, v31
	v_exp_f32_e32 v80, v32
	v_exp_f32_e32 v81, v33
	s_addc_u32 s50, s78, s51
	s_waitcnt vmcnt(2) lgkmcnt(0)
	s_barrier
	s_add_u32 s48, s20, s48
	v_add_u32_e32 v142, v18, v104
	s_addc_u32 s49, s50, s49
	v_mov_b32_e32 v144, v0
	s_mov_b32 s12, s48
	s_mov_b32 s13, s49
	v_mov_b32_e32 v18, 0
	v_mov_b32_e32 v19, v227
	v_mov_b32_e32 v20, v227
	v_mov_b32_e32 v21, v227
	v_mov_b32_e32 v22, v227
	v_mov_b32_e32 v23, v227
	v_mov_b32_e32 v24, v227
	v_mov_b32_e32 v25, v227
	v_mov_b32_e32 v26, v227
	v_mov_b32_e32 v27, v227
	v_mov_b32_e32 v28, v227
	v_mov_b32_e32 v29, v227
	v_mov_b32_e32 v30, v227
	v_mov_b32_e32 v31, v227
	v_mov_b32_e32 v32, v227
	v_mov_b32_e32 v33, v227
	v_mov_b32_e32 v34, 0
	v_mov_b32_e32 v35, v227
	v_mov_b32_e32 v36, v227
	v_mov_b32_e32 v37, v227
	v_mov_b32_e32 v38, v227
	v_mov_b32_e32 v39, v227
	v_mov_b32_e32 v40, v227
	v_mov_b32_e32 v41, v227
	v_mov_b32_e32 v42, v227
	v_mov_b32_e32 v43, v227
	v_mov_b32_e32 v44, v227
	v_mov_b32_e32 v45, v227
	v_mov_b32_e32 v46, v227
	v_mov_b32_e32 v47, v227
	v_mov_b32_e32 v48, v227
	v_mov_b32_e32 v49, v227
; #define WAIT_BAR(N) asm volatile("s_waitcnt vmcnt(" #N ") lgkmcnt(0)\n\ts_barrier":::"memory")
;   #define RESC() do{ if(!FIXREF&&resc){ asm volatile("s_waitcnt lgkmcnt(0)":::"memory"); \
;       _Pragma("unroll") for(int d_=0;d_<2;++d_) _Pragma("unroll") for(int r=0;r<16;++r)o[d_][r]*=wsf[crow(r,hi)]; } }while(0)
;   #define ROT() do{sl_prev=sl_cur;sl_cur=sl_next;sl_next=(sl_next==(NSLOT-1)*SLOTB)?0:sl_next+SLOTB;}while(0)
; template<int THRL,bool FIXREF,bool HALFK> __device__ __forceinline__ void attn_unit(float mref,long rowbase,int q0,const bf16*Qh,int PQ,const bf16*__restrict__ Kh_,int PK,const bf16*__restrict__ Vh_,int PV,bf16*Oh,int PO,const bf16*Gh,int PG,u32x4(&okeep)[4],int omode,float lam,float oml,const float ...
;     ...
;   int t=1;
;     ...
;   for(;t+5<NT;t+=2){
;     STEP(pB0,pB1,pA0,pA1,t,true,true,true);     WAIT_BAR(2); RESC(); ROT();
;     STEP(pA0,pA1,pB0,pB1,t+1,true,true,true);   WAIT_BAR(2); RESC(); ROT();
.LBB0_461:
	v_add_u32_e32 v0, s87, v213
	ds_read_b64_tr_b16 v[228:229], v0 offset:24576
	ds_read_b64_tr_b16 v[230:231], v0 offset:25088
	v_add_f32_e32 v102, v82, v83
	v_add_f32_e32 v102, v84, v102
	v_add_f32_e32 v102, v85, v102
	v_add_f32_e32 v102, v86, v102
	v_add_f32_e32 v102, v87, v102
	v_cvt_pk_bf16_f32 v158, v82, v83
	v_cvt_pk_bf16_f32 v159, v84, v85
	s_waitcnt lgkmcnt(5)
	v_mfma_f32_32x32x16_bf16 v[114:129], v[98:101], v[166:169], v[50:65]
	ds_read_b64_tr_b16 v[82:83], v0 offset:28672
	ds_read_b64_tr_b16 v[84:85], v0 offset:29184
	v_add_f32_e32 v98, v88, v102
	v_add_f32_e32 v98, v89, v98
	v_add_f32_e32 v98, v90, v98
	v_add_f32_e32 v146, v91, v98
	s_waitcnt lgkmcnt(6)
	v_mfma_f32_32x32x16_bf16 v[98:113], v[134:137], v[166:169], v[50:65]
	v_cvt_pk_bf16_f32 v160, v86, v87
	v_cvt_pk_bf16_f32 v161, v88, v89
	ds_read_b64_tr_b16 v[86:87], v0 offset:25600
	ds_read_b64_tr_b16 v[88:89], v0 offset:26112
	v_add_f32_e32 v134, v92, v146
	v_add_f32_e32 v134, v93, v134
	v_add_f32_e32 v134, v94, v134
	v_add_f32_e32 v134, v95, v134
	v_cvt_pk_bf16_f32 v154, v90, v91
	v_cvt_pk_bf16_f32 v155, v92, v93
	s_waitcnt lgkmcnt(7)
	v_mfma_f32_32x32x16_bf16 v[114:129], v[138:141], v[162:165], v[114:129]
	ds_read_b64_tr_b16 v[90:91], v0 offset:29696
	ds_read_b64_tr_b16 v[92:93], v0 offset:30208
	s_waitcnt lgkmcnt(8)
	v_mfma_f32_32x32x16_bf16 v[98:113], v[130:133], v[162:165], v[98:113]
	v_add_f32_e32 v130, v96, v134
	v_add_f32_e32 v130, v97, v130
	v_add_f32_e32 v130, v66, v130
	v_add_f32_e32 v130, v67, v130
	v_cvt_pk_bf16_f32 v156, v94, v95
	v_cvt_pk_bf16_f32 v157, v96, v97
	ds_read_b64_tr_b16 v[94:95], v0 offset:26624
	ds_read_b64_tr_b16 v[96:97], v0 offset:27136
	v_add_f32_e32 v130, v68, v130
	v_add_f32_e32 v130, v69, v130
	v_add_f32_e32 v130, v70, v130
	v_add_f32_e32 v130, v71, v130
	v_cvt_pk_bf16_f32 v150, v66, v67
	v_cvt_pk_bf16_f32 v151, v68, v69
	ds_read_b64_tr_b16 v[66:67], v0 offset:30720
	ds_read_b64_tr_b16 v[68:69], v0 offset:31232
	v_add_f32_e32 v130, v72, v130
	v_add_f32_e32 v130, v73, v130
	v_add_f32_e32 v130, v74, v130
	v_add_f32_e32 v130, v75, v130
	v_cvt_pk_bf16_f32 v152, v70, v71
	v_cvt_pk_bf16_f32 v153, v72, v73
	ds_read_b64_tr_b16 v[70:71], v0 offset:27648
	ds_read_b64_tr_b16 v[72:73], v0 offset:28160
	v_add_f32_e32 v130, v76, v130
	v_add_f32_e32 v130, v77, v130
	v_add_f32_e32 v130, v78, v130
	v_add_f32_e32 v130, v79, v130
	v_cvt_pk_bf16_f32 v146, v74, v75
	v_cvt_pk_bf16_f32 v147, v76, v77
	ds_read_b64_tr_b16 v[74:75], v0 offset:31744
	ds_read_b64_tr_b16 v[76:77], v0 offset:32256
	v_add_f32_e32 v0, v80, v130
	v_add_f32_e32 v0, v81, v0
	v_cvt_pk_bf16_f32 v148, v78, v79
	v_cvt_pk_bf16_f32 v149, v80, v81
	s_add_u32 s98, s12, s36
	s_addc_u32 s99, s13, s37
	s_add_i32 s20, s86, s81
	s_mov_b32 s48, m0
	s_mov_b32 m0, s20
	s_nop 0
	global_load_lds_dwordx4 v144, s[98:99]
	s_mov_b32 m0, s48
	s_add_u32 s98, s38, s22
	s_addc_u32 s99, s39, s23
	s_add_i32 s20, s85, s80
	s_mov_b32 s48, m0
	s_mov_b32 m0, s20
	s_nop 0
	global_load_lds_dwordx4 v142, s[98:99]
	s_mov_b32 m0, s48
	v_add_f32_e32 v0, v227, v0
	s_waitcnt lgkmcnt(14)
	v_mfma_f32_32x32x16_bf16 v[18:33], v[158:161], v[228:231], v[18:33]
	v_exp_f32_e32 v114, v114
	v_exp_f32_e32 v115, v115
	v_exp_f32_e32 v116, v116
	v_exp_f32_e32 v117, v117
	s_waitcnt lgkmcnt(12)
	v_mfma_f32_32x32x16_bf16 v[34:49], v[158:161], v[82:85], v[34:49]
	v_exp_f32_e32 v118, v118
	v_exp_f32_e32 v119, v119
	v_exp_f32_e32 v120, v120
	v_exp_f32_e32 v121, v121
	v_add_u32_e32 v82, s85, v214
	ds_read_b128 v[78:81], v82
	ds_read_b128 v[130:133], v82 offset:512
	s_waitcnt lgkmcnt(12)
	v_mfma_f32_32x32x16_bf16 v[18:33], v[154:157], v[86:89], v[18:33]
	v_exp_f32_e32 v122, v122
	v_exp_f32_e32 v123, v123
	v_exp_f32_e32 v124, v124
	v_exp_f32_e32 v125, v125
	ds_read_b128 v[134:137], v82 offset:2048
	ds_read_b128 v[138:141], v82 offset:2560
	s_waitcnt lgkmcnt(12)
	v_mfma_f32_32x32x16_bf16 v[34:49], v[154:157], v[90:93], v[34:49]
	v_exp_f32_e32 v126, v126
	v_exp_f32_e32 v127, v127
	v_exp_f32_e32 v128, v128
	v_exp_f32_e32 v129, v129
	s_waitcnt lgkmcnt(10)
	v_mfma_f32_32x32x16_bf16 v[18:33], v[150:153], v[94:97], v[18:33]
	v_exp_f32_e32 v98, v98
	v_exp_f32_e32 v99, v99
	v_exp_f32_e32 v100, v100
	v_exp_f32_e32 v101, v101
	s_waitcnt lgkmcnt(8)
	v_mfma_f32_32x32x16_bf16 v[34:49], v[150:153], v[66:69], v[34:49]
	v_exp_f32_e32 v102, v102
	v_exp_f32_e32 v103, v103
	v_exp_f32_e32 v104, v104
	v_exp_f32_e32 v105, v105
	s_waitcnt lgkmcnt(6)
	v_mfma_f32_32x32x16_bf16 v[18:33], v[146:149], v[70:73], v[18:33]
	v_exp_f32_e32 v106, v106
	v_exp_f32_e32 v107, v107
	v_exp_f32_e32 v108, v108
	v_exp_f32_e32 v109, v109
	s_waitcnt lgkmcnt(4)
	v_mfma_f32_32x32x16_bf16 v[34:49], v[146:149], v[74:77], v[34:49]
	v_exp_f32_e32 v110, v110
	v_exp_f32_e32 v111, v111
	v_exp_f32_e32 v112, v112
	v_exp_f32_e32 v113, v113
	s_add_i32 s20, s85, 0x2000
	s_cmpk_lg_i32 s85, 0x4000
	s_cselect_b32 s20, s20, 0
	v_add_u32_e32 v227, s86, v213
	s_waitcnt vmcnt(2) lgkmcnt(0)
	s_barrier
; #define WAIT_BAR(N) asm volatile("s_waitcnt vmcnt(" #N ") lgkmcnt(0)\n\ts_barrier":::"memory")
;   #define RESC() do{ if(!FIXREF&&resc){ asm volatile("s_waitcnt lgkmcnt(0)":::"memory"); \
;       _Pragma("unroll") for(int d_=0;d_<2;++d_) _Pragma("unroll") for(int r=0;r<16;++r)o[d_][r]*=wsf[crow(r,hi)]; } }while(0)
;   #define ROT() do{sl_prev=sl_cur;sl_cur=sl_next;sl_next=(sl_next==(NSLOT-1)*SLOTB)?0:sl_next+SLOTB;}while(0)
;   #define ENDW(tt) do{ if((tt)+3<NT){WAIT_BAR(2);} else if((tt)+2<NT){WAIT_BAR(1);} else {WAIT_BAR(0);} }while(0)
; template<int THRL,bool FIXREF,bool HALFK> __device__ __forceinline__ void attn_unit(float mref,long rowbase,int q0,const bf16*Qh,int PQ,const bf16*__restrict__ Kh_,int PK,const bf16*__restrict__ Vh_,int PV,bf16*Oh,int PO,const bf16*Gh,int PG,u32x4(&okeep)[4],int omode,float lam,float oml,const float ...
;     ...
;   int t=1;
;     ...
;   for(;t+5<NT;t+=2){
;     STEP(pB0,pB1,pA0,pA1,t,true,true,true);     WAIT_BAR(2); RESC(); ROT();
;     STEP(pA0,pA1,pB0,pB1,t+1,true,true,true);   WAIT_BAR(2); RESC(); ROT();
;   }
;     ...
;   for(;t+1<NT;t+=2){
;     STEP(pB0,pB1,pA0,pA1,t,(t+3<NT),(t+1<NT),(t+1<NT));       ENDW(t);   RESC(); ROT();
	ds_read_b64_tr_b16 v[228:229], v227 offset:24576
	ds_read_b64_tr_b16 v[230:231], v227 offset:25088
	s_waitcnt lgkmcnt(5)
	v_mfma_f32_32x32x16_bf16 v[82:97], v[78:81], v[166:169], v[50:65]
	v_add_f32_e32 v66, v114, v115
	v_add_f32_e32 v66, v116, v66
	v_add_f32_e32 v66, v117, v66
	v_add_f32_e32 v66, v118, v66
	v_add_f32_e32 v66, v119, v66
	v_cvt_pk_bf16_f32 v158, v114, v115
	v_cvt_pk_bf16_f32 v159, v116, v117
	ds_read_b64_tr_b16 v[114:115], v227 offset:28672
	ds_read_b64_tr_b16 v[116:117], v227 offset:29184
	v_add_f32_e32 v66, v120, v66
	v_add_f32_e32 v66, v121, v66
	v_add_f32_e32 v66, v122, v66
	v_add_f32_e32 v146, v123, v66
	s_waitcnt lgkmcnt(6)
	v_mfma_f32_32x32x16_bf16 v[66:81], v[130:133], v[166:169], v[50:65]
	v_cvt_pk_bf16_f32 v160, v118, v119
	v_cvt_pk_bf16_f32 v161, v120, v121
	ds_read_b64_tr_b16 v[118:119], v227 offset:25600
	ds_read_b64_tr_b16 v[120:121], v227 offset:26112
	s_waitcnt lgkmcnt(7)
	v_mfma_f32_32x32x16_bf16 v[82:97], v[134:137], v[162:165], v[82:97]
	v_add_f32_e32 v130, v124, v146
	v_add_f32_e32 v130, v125, v130
	v_add_f32_e32 v130, v126, v130
	v_add_f32_e32 v130, v127, v130
	v_cvt_pk_bf16_f32 v154, v122, v123
	v_cvt_pk_bf16_f32 v155, v124, v125
	ds_read_b64_tr_b16 v[122:123], v227 offset:29696
	ds_read_b64_tr_b16 v[124:125], v227 offset:30208
	s_waitcnt lgkmcnt(8)
	v_mfma_f32_32x32x16_bf16 v[66:81], v[138:141], v[162:165], v[66:81]
	v_add_f32_e32 v130, v128, v130
	v_add_f32_e32 v130, v129, v130
	v_add_f32_e32 v130, v98, v130
	v_add_f32_e32 v130, v99, v130
	v_cvt_pk_bf16_f32 v156, v126, v127
	v_cvt_pk_bf16_f32 v157, v128, v129
	ds_read_b64_tr_b16 v[126:127], v227 offset:26624
	ds_read_b64_tr_b16 v[128:129], v227 offset:27136
	v_add_f32_e32 v130, v100, v130
	v_add_f32_e32 v130, v101, v130
	v_add_f32_e32 v130, v102, v130
	v_add_f32_e32 v130, v103, v130
	v_cvt_pk_bf16_f32 v150, v98, v99
	v_cvt_pk_bf16_f32 v151, v100, v101
	ds_read_b64_tr_b16 v[232:233], v227 offset:30720
	ds_read_b64_tr_b16 v[234:235], v227 offset:31232
	v_add_f32_e32 v98, v104, v130
	v_add_f32_e32 v98, v105, v98
	v_add_f32_e32 v98, v106, v98
	v_add_f32_e32 v98, v107, v98
	v_cvt_pk_bf16_f32 v152, v102, v103
	v_cvt_pk_bf16_f32 v153, v104, v105
	ds_read_b64_tr_b16 v[102:103], v227 offset:27648
	ds_read_b64_tr_b16 v[104:105], v227 offset:28160
	v_add_f32_e32 v98, v108, v98
	v_add_f32_e32 v98, v109, v98
	v_add_f32_e32 v98, v110, v98
	v_add_f32_e32 v98, v111, v98
	v_cvt_pk_bf16_f32 v146, v106, v107
	v_cvt_pk_bf16_f32 v147, v108, v109
	ds_read_b64_tr_b16 v[106:107], v227 offset:31744
	ds_read_b64_tr_b16 v[108:109], v227 offset:32256
	v_add_f32_e32 v98, v112, v98
	v_add_f32_e32 v98, v113, v98
	v_cvt_pk_bf16_f32 v148, v110, v111
	v_cvt_pk_bf16_f32 v149, v112, v113
	s_nop 0
	v_add_f32_e32 v227, v0, v98
	s_add_u32 s98, s12, s96
	s_addc_u32 s99, s13, s97
	s_add_i32 s48, s85, s81
	s_mov_b32 s49, m0
	s_mov_b32 m0, s48
	s_nop 0
	global_load_lds_dwordx4 v144, s[98:99]
	s_mov_b32 m0, s49
	s_add_u32 s38, s38, s4
	s_addc_u32 s39, s39, s5
	s_add_i32 s48, s20, s80
	s_mov_b32 s49, m0
	s_mov_b32 m0, s48
	s_nop 0
	global_load_lds_dwordx4 v142, s[38:39]
	s_mov_b32 m0, s49
	s_waitcnt lgkmcnt(14)
	v_mfma_f32_32x32x16_bf16 v[18:33], v[158:161], v[228:231], v[18:33]
	v_exp_f32_e32 v82, v82
	v_exp_f32_e32 v83, v83
	v_exp_f32_e32 v84, v84
	v_exp_f32_e32 v85, v85
	s_waitcnt lgkmcnt(12)
	v_mfma_f32_32x32x16_bf16 v[34:49], v[158:161], v[114:117], v[34:49]
	v_exp_f32_e32 v86, v86
	v_exp_f32_e32 v87, v87
	v_exp_f32_e32 v88, v88
	v_exp_f32_e32 v89, v89
	v_add_u32_e32 v0, s20, v214
	ds_read_b128 v[98:101], v0
	ds_read_b128 v[134:137], v0 offset:512
	s_waitcnt lgkmcnt(12)
	v_mfma_f32_32x32x16_bf16 v[18:33], v[154:157], v[118:121], v[18:33]
	v_exp_f32_e32 v90, v90
	v_exp_f32_e32 v91, v91
	v_exp_f32_e32 v92, v92
	v_exp_f32_e32 v93, v93
	ds_read_b128 v[138:141], v0 offset:2048
	ds_read_b128 v[130:133], v0 offset:2560
	s_waitcnt lgkmcnt(12)
	v_mfma_f32_32x32x16_bf16 v[34:49], v[154:157], v[122:125], v[34:49]
	v_exp_f32_e32 v94, v94
	v_exp_f32_e32 v95, v95
	v_exp_f32_e32 v96, v96
	v_exp_f32_e32 v97, v97
	s_waitcnt lgkmcnt(10)
	v_mfma_f32_32x32x16_bf16 v[18:33], v[150:153], v[126:129], v[18:33]
	v_exp_f32_e32 v66, v66
	v_exp_f32_e32 v67, v67
	v_exp_f32_e32 v68, v68
	v_exp_f32_e32 v69, v69
	s_waitcnt lgkmcnt(8)
	v_mfma_f32_32x32x16_bf16 v[34:49], v[150:153], v[232:235], v[34:49]
	v_exp_f32_e32 v70, v70
	v_exp_f32_e32 v71, v71
	v_exp_f32_e32 v72, v72
	v_exp_f32_e32 v73, v73
	s_waitcnt lgkmcnt(6)
	v_mfma_f32_32x32x16_bf16 v[18:33], v[146:149], v[102:105], v[18:33]
	v_exp_f32_e32 v74, v74
	v_exp_f32_e32 v75, v75
	v_exp_f32_e32 v76, v76
	v_exp_f32_e32 v77, v77
	s_waitcnt lgkmcnt(4)
	v_mfma_f32_32x32x16_bf16 v[34:49], v[146:149], v[106:109], v[34:49]
	v_exp_f32_e32 v78, v78
	v_exp_f32_e32 v79, v79
	v_exp_f32_e32 v80, v80
	v_exp_f32_e32 v81, v81
	s_add_i32 s48, s20, 0x2000
	s_cmpk_lg_i32 s20, 0x4000
	s_mov_b32 s87, s85
	s_cselect_b32 s85, s48, 0
	s_add_i32 s84, s84, 2
	s_add_u32 s12, s12, s92
	s_addc_u32 s13, s13, s93
	s_mov_b32 s86, s20
	s_cmp_gt_u32 s84, 56
	s_waitcnt vmcnt(2) lgkmcnt(0)
	s_barrier
	s_cbranch_scc0 .LBB0_461
; #define WAIT_BAR(N) asm volatile("s_waitcnt vmcnt(" #N ") lgkmcnt(0)\n\ts_barrier":::"memory")
;   #define RESC() do{ if(!FIXREF&&resc){ asm volatile("s_waitcnt lgkmcnt(0)":::"memory"); \
;       _Pragma("unroll") for(int d_=0;d_<2;++d_) _Pragma("unroll") for(int r=0;r<16;++r)o[d_][r]*=wsf[crow(r,hi)]; } }while(0)
;   #define ROT() do{sl_prev=sl_cur;sl_cur=sl_next;sl_next=(sl_next==(NSLOT-1)*SLOTB)?0:sl_next+SLOTB;}while(0)
;   #define ENDW(tt) do{ if((tt)+3<NT){WAIT_BAR(2);} else if((tt)+2<NT){WAIT_BAR(1);} else {WAIT_BAR(0);} }while(0)
; template<int THRL,bool FIXREF,bool HALFK> __device__ __forceinline__ void attn_unit(float mref,long rowbase,int q0,const bf16*Qh,int PQ,const bf16*__restrict__ Kh_,int PK,const bf16*__restrict__ Vh_,int PV,bf16*Oh,int PO,const bf16*Gh,int PG,u32x4(&okeep)[4],int omode,float lam,float oml,const float ...
;     ...
;   int t=1;
;     ...
;   for(;t+5<NT;t+=2){
;     STEP(pB0,pB1,pA0,pA1,t,true,true,true);     WAIT_BAR(2); RESC(); ROT();
;     STEP(pA0,pA1,pB0,pB1,t+1,true,true,true);   WAIT_BAR(2); RESC(); ROT();
;   }
;     ...
;   for(;t+1<NT;t+=2){
;     STEP(pB0,pB1,pA0,pA1,t,(t+3<NT),(t+1<NT),(t+1<NT));       ENDW(t);   RESC(); ROT();
;     STEP(pA0,pA1,pB0,pB1,t+1,(t+4<NT),(t+2<NT),(t+2<NT));     ENDW(t+1); RESC(); ROT();
;   }
	s_and_b32 s20, s83, 0x3fffffc0
	s_lshl_b32 s20, s20, 2
	s_add_i32 s20, s20, 0
	s_cmp_lg_u32 0, -1
	s_cselect_b32 s50, 0, 0
	s_add_i32 s48, s50, 0x6000
	v_add_u32_e32 v0, s48, v216
	v_add3_u32 v0, v0, v215, v217
	ds_read_b64_tr_b16 v[142:143], v213 offset:32768
	ds_read_b64_tr_b16 v[144:145], v213 offset:33280
	v_add_f32_e32 v102, v82, v83
	v_add_f32_e32 v102, v84, v102
	v_add_f32_e32 v102, v85, v102
	v_add_f32_e32 v102, v86, v102
	v_add_f32_e32 v102, v87, v102
	v_cvt_pk_bf16_f32 v158, v82, v83
	v_cvt_pk_bf16_f32 v159, v84, v85
	s_waitcnt lgkmcnt(5)
	v_mfma_f32_32x32x16_bf16 v[114:129], v[98:101], v[166:169], v[50:65]
	ds_read_b64_tr_b16 v[82:83], v213 offset:36864
	ds_read_b64_tr_b16 v[84:85], v213 offset:37376
	v_add_f32_e32 v98, v88, v102
	v_add_f32_e32 v98, v89, v98
	v_add_f32_e32 v98, v90, v98
	v_add_f32_e32 v146, v91, v98
	v_cvt_pk_bf16_f32 v160, v86, v87
	v_cvt_pk_bf16_f32 v161, v88, v89
	s_waitcnt lgkmcnt(6)
	v_mfma_f32_32x32x16_bf16 v[98:113], v[134:137], v[166:169], v[50:65]
	ds_read_b64_tr_b16 v[86:87], v213 offset:33792
	ds_read_b64_tr_b16 v[88:89], v213 offset:34304
	v_add_f32_e32 v134, v92, v146
	v_add_f32_e32 v134, v93, v134
	v_add_f32_e32 v134, v94, v134
	v_add_f32_e32 v134, v95, v134
	v_cvt_pk_bf16_f32 v154, v90, v91
	v_cvt_pk_bf16_f32 v155, v92, v93
	s_waitcnt lgkmcnt(7)
	v_mfma_f32_32x32x16_bf16 v[114:129], v[138:141], v[162:165], v[114:129]
	ds_read_b64_tr_b16 v[90:91], v213 offset:37888
	ds_read_b64_tr_b16 v[92:93], v213 offset:38400
	s_waitcnt lgkmcnt(8)
	v_mfma_f32_32x32x16_bf16 v[98:113], v[130:133], v[162:165], v[98:113]
	v_add_f32_e32 v130, v96, v134
	v_add_f32_e32 v130, v97, v130
	v_add_f32_e32 v130, v66, v130
	v_add_f32_e32 v130, v67, v130
	v_cvt_pk_bf16_f32 v156, v94, v95
	v_cvt_pk_bf16_f32 v157, v96, v97
	ds_read_b64_tr_b16 v[94:95], v213 offset:34816
	ds_read_b64_tr_b16 v[96:97], v213 offset:35328
	v_add_f32_e32 v130, v68, v130
	v_add_f32_e32 v130, v69, v130
	v_add_f32_e32 v130, v70, v130
	v_add_f32_e32 v130, v71, v130
	v_cvt_pk_bf16_f32 v150, v66, v67
	v_cvt_pk_bf16_f32 v151, v68, v69
	ds_read_b64_tr_b16 v[66:67], v213 offset:38912
	ds_read_b64_tr_b16 v[68:69], v213 offset:39424
	v_add_f32_e32 v130, v72, v130
	v_add_f32_e32 v130, v73, v130
	v_add_f32_e32 v130, v74, v130
	v_add_f32_e32 v130, v75, v130
	v_cvt_pk_bf16_f32 v152, v70, v71
	v_cvt_pk_bf16_f32 v153, v72, v73
	ds_read_b64_tr_b16 v[70:71], v213 offset:35840
	ds_read_b64_tr_b16 v[72:73], v213 offset:36352
	v_add_f32_e32 v130, v76, v130
	v_add_f32_e32 v130, v77, v130
	v_add_f32_e32 v130, v78, v130
	v_add_f32_e32 v130, v79, v130
	v_cvt_pk_bf16_f32 v146, v74, v75
	v_cvt_pk_bf16_f32 v147, v76, v77
	ds_read_b64_tr_b16 v[74:75], v213 offset:39936
	ds_read_b64_tr_b16 v[76:77], v213 offset:40448
	v_add_f32_e32 v130, v80, v130
	v_add_f32_e32 v130, v81, v130
	v_add_f32_e32 v130, 0, v130
	v_cvt_pk_bf16_f32 v148, v78, v79
	v_cvt_pk_bf16_f32 v149, v80, v81
	s_mov_b64 s[48:49], 0x1f0000
	v_lshl_add_u64 v[78:79], v[174:175], 0, s[48:49]
	s_add_i32 s48, s50, s82
	s_add_i32 s49, s48, 0x4000
	s_mov_b32 s50, m0
	s_mov_b32 m0, s49
	s_nop 0
	global_load_lds_dwordx4 v[78:79], off
	s_mov_b32 m0, s50
	v_lshl_add_u64 v[78:79], v[172:173], 0, s[18:19]
	s_mov_b32 s49, m0
	s_mov_b32 m0, s80
	s_nop 0
	global_load_lds_dwordx4 v[78:79], off
	s_mov_b32 m0, s49
	v_add_f32_e32 v215, v227, v130
	s_waitcnt lgkmcnt(14)
	v_mfma_f32_32x32x16_bf16 v[18:33], v[158:161], v[142:145], v[18:33]
	v_exp_f32_e32 v114, v114
	v_exp_f32_e32 v115, v115
	v_exp_f32_e32 v116, v116
	v_exp_f32_e32 v117, v117
	s_waitcnt lgkmcnt(12)
	v_mfma_f32_32x32x16_bf16 v[34:49], v[158:161], v[82:85], v[34:49]
	v_exp_f32_e32 v118, v118
	v_exp_f32_e32 v119, v119
	v_exp_f32_e32 v120, v120
	v_exp_f32_e32 v121, v121
	ds_read_b128 v[78:81], v214
	ds_read_b128 v[82:85], v214 offset:512
	s_waitcnt lgkmcnt(12)
	v_mfma_f32_32x32x16_bf16 v[18:33], v[154:157], v[86:89], v[18:33]
	v_exp_f32_e32 v122, v122
	v_exp_f32_e32 v123, v123
	v_exp_f32_e32 v124, v124
	v_exp_f32_e32 v125, v125
	ds_read_b128 v[86:89], v214 offset:2048
	ds_read_b128 v[228:231], v214 offset:2560
	s_waitcnt lgkmcnt(12)
	v_mfma_f32_32x32x16_bf16 v[34:49], v[154:157], v[90:93], v[34:49]
	v_exp_f32_e32 v126, v126
	v_exp_f32_e32 v127, v127
	v_exp_f32_e32 v128, v128
	v_exp_f32_e32 v129, v129
	s_waitcnt lgkmcnt(10)
	v_mfma_f32_32x32x16_bf16 v[18:33], v[150:153], v[94:97], v[18:33]
	v_exp_f32_e32 v98, v98
	v_exp_f32_e32 v99, v99
	v_exp_f32_e32 v100, v100
	v_exp_f32_e32 v101, v101
	s_waitcnt lgkmcnt(8)
	v_mfma_f32_32x32x16_bf16 v[34:49], v[150:153], v[66:69], v[34:49]
	v_exp_f32_e32 v102, v102
	v_exp_f32_e32 v103, v103
	v_exp_f32_e32 v104, v104
	v_exp_f32_e32 v105, v105
	s_waitcnt lgkmcnt(6)
	v_mfma_f32_32x32x16_bf16 v[18:33], v[146:149], v[70:73], v[18:33]
	v_exp_f32_e32 v106, v106
	v_exp_f32_e32 v107, v107
	v_exp_f32_e32 v108, v108
	v_exp_f32_e32 v109, v109
	s_waitcnt lgkmcnt(4)
	v_mfma_f32_32x32x16_bf16 v[34:49], v[146:149], v[74:77], v[34:49]
	v_exp_f32_e32 v110, v110
	v_exp_f32_e32 v111, v111
	v_exp_f32_e32 v112, v112
	v_exp_f32_e32 v113, v113
	s_waitcnt vmcnt(2) lgkmcnt(0)
	s_barrier
; #define WAIT_BAR(N) asm volatile("s_waitcnt vmcnt(" #N ") lgkmcnt(0)\n\ts_barrier":::"memory")
;   #define RESC() do{ if(!FIXREF&&resc){ asm volatile("s_waitcnt lgkmcnt(0)":::"memory"); \
;       _Pragma("unroll") for(int d_=0;d_<2;++d_) _Pragma("unroll") for(int r=0;r<16;++r)o[d_][r]*=wsf[crow(r,hi)]; } }while(0)
;   #define ROT() do{sl_prev=sl_cur;sl_cur=sl_next;sl_next=(sl_next==(NSLOT-1)*SLOTB)?0:sl_next+SLOTB;}while(0)
;   #define ENDW(tt) do{ if((tt)+3<NT){WAIT_BAR(2);} else if((tt)+2<NT){WAIT_BAR(1);} else {WAIT_BAR(0);} }while(0)
; template<int THRL,bool FIXREF,bool HALFK> __device__ __forceinline__ void attn_unit(float mref,long rowbase,int q0,const bf16*Qh,int PQ,const bf16*__restrict__ Kh_,int PK,const bf16*__restrict__ Vh_,int PV,bf16*Oh,int PO,const bf16*Gh,int PG,u32x4(&okeep)[4],int omode,float lam,float oml,const float ...
;     ...
;   int t=1;
;     ...
;   for(;t+5<NT;t+=2){
;     STEP(pB0,pB1,pA0,pA1,t,true,true,true);     WAIT_BAR(2); RESC(); ROT();
;     STEP(pA0,pA1,pB0,pB1,t+1,true,true,true);   WAIT_BAR(2); RESC(); ROT();
;   }
;     ...
;   for(;t+1<NT;t+=2){
;     STEP(pB0,pB1,pA0,pA1,t,(t+3<NT),(t+1<NT),(t+1<NT));       ENDW(t);   RESC(); ROT();
;     STEP(pA0,pA1,pB0,pB1,t+1,(t+4<NT),(t+2<NT),(t+2<NT));     ENDW(t+1); RESC(); ROT();
;   }
	ds_read_b64_tr_b16 v[90:91], v213 offset:40960
	ds_read_b64_tr_b16 v[92:93], v213 offset:41472
	v_add_f32_e32 v66, v114, v115
	v_add_f32_e32 v66, v116, v66
	v_add_f32_e32 v66, v117, v66
	v_add_f32_e32 v66, v118, v66
	v_add_f32_e32 v66, v119, v66
	v_cvt_pk_bf16_f32 v158, v114, v115
	v_cvt_pk_bf16_f32 v159, v116, v117
	s_waitcnt lgkmcnt(5)
	v_mfma_f32_32x32x16_bf16 v[130:145], v[78:81], v[166:169], v[50:65]
	ds_read_b64_tr_b16 v[94:95], v213 offset:45056
	ds_read_b64_tr_b16 v[96:97], v213 offset:45568
	v_add_f32_e32 v66, v120, v66
	v_add_f32_e32 v66, v121, v66
	v_add_f32_e32 v66, v122, v66
	v_add_f32_e32 v114, v123, v66
	s_waitcnt lgkmcnt(6)
	v_mfma_f32_32x32x16_bf16 v[66:81], v[82:85], v[166:169], v[50:65]
	v_cvt_pk_bf16_f32 v160, v118, v119
	v_cvt_pk_bf16_f32 v161, v120, v121
	ds_read_b64_tr_b16 v[82:83], v213 offset:41984
	ds_read_b64_tr_b16 v[84:85], v213 offset:42496
	s_waitcnt lgkmcnt(7)
	v_mfma_f32_32x32x16_bf16 v[130:145], v[86:89], v[162:165], v[130:145]
	v_add_f32_e32 v86, v124, v114
	v_add_f32_e32 v86, v125, v86
	v_add_f32_e32 v86, v126, v86
	v_add_f32_e32 v114, v127, v86
	v_cvt_pk_bf16_f32 v154, v122, v123
	v_cvt_pk_bf16_f32 v155, v124, v125
	ds_read_b64_tr_b16 v[86:87], v213 offset:46080
	ds_read_b64_tr_b16 v[88:89], v213 offset:46592
	s_waitcnt lgkmcnt(8)
	v_mfma_f32_32x32x16_bf16 v[66:81], v[228:231], v[162:165], v[66:81]
	v_add_f32_e32 v114, v128, v114
	v_add_f32_e32 v114, v129, v114
	v_add_f32_e32 v114, v98, v114
	v_add_f32_e32 v118, v99, v114
	v_cvt_pk_bf16_f32 v156, v126, v127
	v_cvt_pk_bf16_f32 v157, v128, v129
	ds_read_b64_tr_b16 v[114:115], v213 offset:43008
	ds_read_b64_tr_b16 v[116:117], v213 offset:43520
	v_add_f32_e32 v118, v100, v118
	v_add_f32_e32 v118, v101, v118
	v_add_f32_e32 v118, v102, v118
	v_add_f32_e32 v118, v103, v118
	v_cvt_pk_bf16_f32 v150, v98, v99
	v_cvt_pk_bf16_f32 v151, v100, v101
	ds_read_b64_tr_b16 v[98:99], v213 offset:47104
	ds_read_b64_tr_b16 v[100:101], v213 offset:47616
	v_add_f32_e32 v118, v104, v118
	v_add_f32_e32 v118, v105, v118
	v_add_f32_e32 v118, v106, v118
	v_add_f32_e32 v118, v107, v118
	v_cvt_pk_bf16_f32 v152, v102, v103
	v_cvt_pk_bf16_f32 v153, v104, v105
	ds_read_b64_tr_b16 v[102:103], v213 offset:44032
	ds_read_b64_tr_b16 v[104:105], v213 offset:44544
	v_add_f32_e32 v118, v108, v118
	v_add_f32_e32 v118, v109, v118
	v_add_f32_e32 v118, v110, v118
	v_add_f32_e32 v118, v111, v118
	v_cvt_pk_bf16_f32 v146, v106, v107
	v_cvt_pk_bf16_f32 v147, v108, v109
	ds_read_b64_tr_b16 v[106:107], v213 offset:48128
	ds_read_b64_tr_b16 v[108:109], v213 offset:48640
	v_add_f32_e32 v118, v112, v118
	v_add_f32_e32 v118, v113, v118
	v_add_f32_e32 v118, 0, v118
	v_cvt_pk_bf16_f32 v148, v110, v111
	v_cvt_pk_bf16_f32 v149, v112, v113
	s_mov_b64 s[50:51], 0x1f8000
	v_lshl_add_u64 v[110:111], v[174:175], 0, s[50:51]
	s_mov_b32 s49, m0
	s_mov_b32 m0, s81
	s_nop 0
	global_load_lds_dwordx4 v[110:111], off
	s_mov_b32 m0, s49
	v_lshl_add_u64 v[110:111], v[172:173], 0, s[6:7]
	s_add_i32 s49, s48, 0x8000
	s_mov_b32 s50, m0
	s_mov_b32 m0, s49
	s_nop 0
	global_load_lds_dwordx4 v[110:111], off
	s_mov_b32 m0, s50
	v_add_f32_e32 v215, v215, v118
	s_waitcnt lgkmcnt(14)
	v_mfma_f32_32x32x16_bf16 v[18:33], v[158:161], v[90:93], v[18:33]
	v_exp_f32_e32 v130, v130
	v_exp_f32_e32 v131, v131
	v_exp_f32_e32 v132, v132
	v_exp_f32_e32 v133, v133
	s_waitcnt lgkmcnt(12)
	v_mfma_f32_32x32x16_bf16 v[34:49], v[158:161], v[94:97], v[34:49]
	v_exp_f32_e32 v134, v134
	v_exp_f32_e32 v135, v135
	v_exp_f32_e32 v136, v136
	v_exp_f32_e32 v137, v137
	ds_read_b128 v[90:93], v214 offset:8192
	ds_read_b128 v[110:113], v214 offset:8704
	s_waitcnt lgkmcnt(12)
	v_mfma_f32_32x32x16_bf16 v[18:33], v[154:157], v[82:85], v[18:33]
	v_exp_f32_e32 v138, v138
	v_exp_f32_e32 v139, v139
	v_exp_f32_e32 v140, v140
	v_exp_f32_e32 v141, v141
	ds_read_b128 v[228:231], v214 offset:10240
	ds_read_b128 v[232:235], v214 offset:10752
	s_waitcnt lgkmcnt(12)
	v_mfma_f32_32x32x16_bf16 v[34:49], v[154:157], v[86:89], v[34:49]
	v_exp_f32_e32 v142, v142
	v_exp_f32_e32 v143, v143
	v_exp_f32_e32 v144, v144
	v_exp_f32_e32 v145, v145
	s_waitcnt lgkmcnt(10)
	v_mfma_f32_32x32x16_bf16 v[18:33], v[150:153], v[114:117], v[18:33]
	v_exp_f32_e32 v66, v66
	v_exp_f32_e32 v67, v67
	v_exp_f32_e32 v68, v68
	v_exp_f32_e32 v69, v69
	s_waitcnt lgkmcnt(8)
	v_mfma_f32_32x32x16_bf16 v[34:49], v[150:153], v[98:101], v[34:49]
	v_exp_f32_e32 v70, v70
	v_exp_f32_e32 v71, v71
	v_exp_f32_e32 v72, v72
	v_exp_f32_e32 v73, v73
	s_waitcnt lgkmcnt(6)
	v_mfma_f32_32x32x16_bf16 v[18:33], v[146:149], v[102:105], v[18:33]
	v_exp_f32_e32 v74, v74
	v_exp_f32_e32 v75, v75
	v_exp_f32_e32 v76, v76
	v_exp_f32_e32 v77, v77
	s_waitcnt lgkmcnt(4)
	v_mfma_f32_32x32x16_bf16 v[34:49], v[146:149], v[106:109], v[34:49]
	v_exp_f32_e32 v78, v78
	v_exp_f32_e32 v79, v79
	v_exp_f32_e32 v80, v80
	v_exp_f32_e32 v81, v81
	s_waitcnt vmcnt(2) lgkmcnt(0)
	s_barrier
; #define WAIT_BAR(N) asm volatile("s_waitcnt vmcnt(" #N ") lgkmcnt(0)\n\ts_barrier":::"memory")
;   #define RESC() do{ if(!FIXREF&&resc){ asm volatile("s_waitcnt lgkmcnt(0)":::"memory"); \
;       _Pragma("unroll") for(int d_=0;d_<2;++d_) _Pragma("unroll") for(int r=0;r<16;++r)o[d_][r]*=wsf[crow(r,hi)]; } }while(0)
;   #define ROT() do{sl_prev=sl_cur;sl_cur=sl_next;sl_next=(sl_next==(NSLOT-1)*SLOTB)?0:sl_next+SLOTB;}while(0)
;   #define ENDW(tt) do{ if((tt)+3<NT){WAIT_BAR(2);} else if((tt)+2<NT){WAIT_BAR(1);} else {WAIT_BAR(0);} }while(0)
; template<int THRL,bool FIXREF,bool HALFK> __device__ __forceinline__ void attn_unit(float mref,long rowbase,int q0,const bf16*Qh,int PQ,const bf16*__restrict__ Kh_,int PK,const bf16*__restrict__ Vh_,int PV,bf16*Oh,int PO,const bf16*Gh,int PG,u32x4(&okeep)[4],int omode,float lam,float oml,const float ...
;     ...
;   int t=1;
;     ...
;   for(;t+5<NT;t+=2){
;     STEP(pB0,pB1,pA0,pA1,t,true,true,true);     WAIT_BAR(2); RESC(); ROT();
;     STEP(pA0,pA1,pB0,pB1,t+1,true,true,true);   WAIT_BAR(2); RESC(); ROT();
;   }
;     ...
;   for(;t+1<NT;t+=2){
;     STEP(pB0,pB1,pA0,pA1,t,(t+3<NT),(t+1<NT),(t+1<NT));       ENDW(t);   RESC(); ROT();
;     STEP(pA0,pA1,pB0,pB1,t+1,(t+4<NT),(t+2<NT),(t+2<NT));     ENDW(t+1); RESC(); ROT();
;   }
	ds_read_b64_tr_b16 v[98:99], v213 offset:24576
	ds_read_b64_tr_b16 v[100:101], v213 offset:25088
	v_add_f32_e32 v82, v130, v131
	v_add_f32_e32 v82, v132, v82
	v_add_f32_e32 v82, v133, v82
	v_add_f32_e32 v82, v134, v82
	v_add_f32_e32 v82, v135, v82
	v_cvt_pk_bf16_f32 v158, v130, v131
	v_cvt_pk_bf16_f32 v159, v132, v133
	s_waitcnt lgkmcnt(5)
	v_mfma_f32_32x32x16_bf16 v[114:129], v[90:93], v[166:169], v[50:65]
	ds_read_b64_tr_b16 v[102:103], v213 offset:28672
	ds_read_b64_tr_b16 v[104:105], v213 offset:29184
	v_add_f32_e32 v82, v136, v82
	v_add_f32_e32 v82, v137, v82
	v_add_f32_e32 v82, v138, v82
	v_add_f32_e32 v130, v139, v82
	v_cvt_pk_bf16_f32 v160, v134, v135
	v_cvt_pk_bf16_f32 v161, v136, v137
	s_waitcnt lgkmcnt(6)
	v_mfma_f32_32x32x16_bf16 v[82:97], v[110:113], v[166:169], v[50:65]
	ds_read_b64_tr_b16 v[106:107], v213 offset:25600
	ds_read_b64_tr_b16 v[108:109], v213 offset:26112
	v_add_f32_e32 v110, v140, v130
	v_add_f32_e32 v110, v141, v110
	v_add_f32_e32 v110, v142, v110
	v_add_f32_e32 v130, v143, v110
	v_cvt_pk_bf16_f32 v154, v138, v139
	v_cvt_pk_bf16_f32 v155, v140, v141
	s_waitcnt lgkmcnt(7)
	v_mfma_f32_32x32x16_bf16 v[114:129], v[228:231], v[162:165], v[114:129]
	ds_read_b64_tr_b16 v[110:111], v213 offset:29696
	ds_read_b64_tr_b16 v[112:113], v213 offset:30208
	v_add_f32_e32 v130, v144, v130
	v_add_f32_e32 v130, v145, v130
	v_add_f32_e32 v130, v66, v130
	v_add_f32_e32 v134, v67, v130
	v_cvt_pk_bf16_f32 v156, v142, v143
	v_cvt_pk_bf16_f32 v157, v144, v145
	s_waitcnt lgkmcnt(8)
	v_mfma_f32_32x32x16_bf16 v[82:97], v[232:235], v[162:165], v[82:97]
	ds_read_b64_tr_b16 v[130:131], v213 offset:26624
	ds_read_b64_tr_b16 v[132:133], v213 offset:27136
	v_add_f32_e32 v134, v68, v134
	v_add_f32_e32 v134, v69, v134
	v_add_f32_e32 v134, v70, v134
	v_add_f32_e32 v134, v71, v134
	v_cvt_pk_bf16_f32 v150, v66, v67
	v_cvt_pk_bf16_f32 v151, v68, v69
	ds_read_b64_tr_b16 v[66:67], v213 offset:30720
	ds_read_b64_tr_b16 v[68:69], v213 offset:31232
	v_add_f32_e32 v134, v72, v134
	v_add_f32_e32 v134, v73, v134
	v_add_f32_e32 v134, v74, v134
	v_add_f32_e32 v134, v75, v134
	v_cvt_pk_bf16_f32 v152, v70, v71
	v_cvt_pk_bf16_f32 v153, v72, v73
	ds_read_b64_tr_b16 v[70:71], v213 offset:27648
	ds_read_b64_tr_b16 v[72:73], v213 offset:28160
	v_add_f32_e32 v134, v76, v134
	v_add_f32_e32 v134, v77, v134
	v_add_f32_e32 v134, v78, v134
	v_add_f32_e32 v134, v79, v134
	v_cvt_pk_bf16_f32 v146, v74, v75
	v_cvt_pk_bf16_f32 v147, v76, v77
	ds_read_b64_tr_b16 v[74:75], v213 offset:31744
	ds_read_b64_tr_b16 v[76:77], v213 offset:32256
	v_add_f32_e32 v134, v80, v134
	v_add_f32_e32 v134, v81, v134
	v_add_f32_e32 v134, 0, v134
	v_cvt_pk_bf16_f32 v148, v78, v79
	v_cvt_pk_bf16_f32 v149, v80, v81
	v_lshl_add_u64 v[78:79], v[172:173], 0, s[94:95]
	s_add_i32 s48, s48, 0xa000
	s_mov_b32 s49, m0
	s_mov_b32 m0, s48
	s_nop 0
	global_load_lds_dwordx4 v[78:79], off
	s_mov_b32 m0, s49
	v_add_f32_e32 v174, v215, v134
	s_waitcnt lgkmcnt(14)
	v_mfma_f32_32x32x16_bf16 v[18:33], v[158:161], v[98:101], v[18:33]
	v_exp_f32_e32 v114, v114
	v_exp_f32_e32 v115, v115
	v_exp_f32_e32 v116, v116
	v_exp_f32_e32 v117, v117
	s_waitcnt lgkmcnt(12)
	v_mfma_f32_32x32x16_bf16 v[34:49], v[158:161], v[102:105], v[34:49]
	v_exp_f32_e32 v118, v118
	v_exp_f32_e32 v119, v119
	v_exp_f32_e32 v120, v120
	v_exp_f32_e32 v121, v121
	ds_read_b128 v[78:81], v214 offset:16384
	ds_read_b128 v[134:137], v214 offset:16896
	s_waitcnt lgkmcnt(12)
	v_mfma_f32_32x32x16_bf16 v[18:33], v[154:157], v[106:109], v[18:33]
	v_exp_f32_e32 v122, v122
	v_exp_f32_e32 v123, v123
	v_exp_f32_e32 v124, v124
	v_exp_f32_e32 v125, v125
	ds_read_b128 v[138:141], v214 offset:18432
	ds_read_b128 v[142:145], v214 offset:18944
	s_waitcnt lgkmcnt(12)
	v_mfma_f32_32x32x16_bf16 v[34:49], v[154:157], v[110:113], v[34:49]
	v_exp_f32_e32 v126, v126
	v_exp_f32_e32 v127, v127
	v_exp_f32_e32 v128, v128
	v_exp_f32_e32 v129, v129
	s_waitcnt lgkmcnt(10)
	v_mfma_f32_32x32x16_bf16 v[18:33], v[150:153], v[130:133], v[18:33]
	v_exp_f32_e32 v82, v82
	v_exp_f32_e32 v83, v83
	v_exp_f32_e32 v84, v84
	v_exp_f32_e32 v85, v85
	s_waitcnt lgkmcnt(8)
	v_mfma_f32_32x32x16_bf16 v[34:49], v[150:153], v[66:69], v[34:49]
	v_exp_f32_e32 v86, v86
	v_exp_f32_e32 v87, v87
	v_exp_f32_e32 v88, v88
	v_exp_f32_e32 v89, v89
	s_waitcnt lgkmcnt(6)
	v_mfma_f32_32x32x16_bf16 v[18:33], v[146:149], v[70:73], v[18:33]
	v_exp_f32_e32 v90, v90
	v_exp_f32_e32 v91, v91
	v_exp_f32_e32 v92, v92
	v_exp_f32_e32 v93, v93
	s_waitcnt lgkmcnt(4)
	v_mfma_f32_32x32x16_bf16 v[34:49], v[146:149], v[74:77], v[34:49]
	v_exp_f32_e32 v94, v94
	v_exp_f32_e32 v95, v95
	v_exp_f32_e32 v96, v96
	v_exp_f32_e32 v97, v97
	s_waitcnt vmcnt(1) lgkmcnt(0)
	s_barrier
; #define WAIT_BAR(N) asm volatile("s_waitcnt vmcnt(" #N ") lgkmcnt(0)\n\ts_barrier":::"memory")
;   #define RESC() do{ if(!FIXREF&&resc){ asm volatile("s_waitcnt lgkmcnt(0)":::"memory"); \
;       _Pragma("unroll") for(int d_=0;d_<2;++d_) _Pragma("unroll") for(int r=0;r<16;++r)o[d_][r]*=wsf[crow(r,hi)]; } }while(0)
;   #define ROT() do{sl_prev=sl_cur;sl_cur=sl_next;sl_next=(sl_next==(NSLOT-1)*SLOTB)?0:sl_next+SLOTB;}while(0)
;   #define ENDW(tt) do{ if((tt)+3<NT){WAIT_BAR(2);} else if((tt)+2<NT){WAIT_BAR(1);} else {WAIT_BAR(0);} }while(0)
; template<int THRL,bool FIXREF,bool HALFK> __device__ __forceinline__ void attn_unit(float mref,long rowbase,int q0,const bf16*Qh,int PQ,const bf16*__restrict__ Kh_,int PK,const bf16*__restrict__ Vh_,int PV,bf16*Oh,int PO,const bf16*Gh,int PG,u32x4(&okeep)[4],int omode,float lam,float oml,const float ...
;     ...
;   int t=1;
;     ...
;   for(;t+5<NT;t+=2){
;     STEP(pB0,pB1,pA0,pA1,t,true,true,true);     WAIT_BAR(2); RESC(); ROT();
;     STEP(pA0,pA1,pB0,pB1,t+1,true,true,true);   WAIT_BAR(2); RESC(); ROT();
;   }
;     ...
;   for(;t+1<NT;t+=2){
;     STEP(pB0,pB1,pA0,pA1,t,(t+3<NT),(t+1<NT),(t+1<NT));       ENDW(t);   RESC(); ROT();
;     STEP(pA0,pA1,pB0,pB1,t+1,(t+4<NT),(t+2<NT),(t+2<NT));     ENDW(t+1); RESC(); ROT();
;   }
;   STEP(pB0,pB1,pA0,pA1,NT-1,false,false,false); RESC();
	ds_read_b64_tr_b16 v[130:131], v213 offset:32768
	ds_read_b64_tr_b16 v[132:133], v213 offset:33280
	v_add_f32_e32 v66, v114, v115
	v_add_f32_e32 v66, v116, v66
	v_add_f32_e32 v66, v117, v66
	v_add_f32_e32 v66, v118, v66
	v_add_f32_e32 v66, v119, v66
	v_cvt_pk_bf16_f32 v158, v114, v115
	v_cvt_pk_bf16_f32 v159, v116, v117
	s_waitcnt lgkmcnt(5)
	v_mfma_f32_32x32x16_bf16 v[98:113], v[78:81], v[166:169], v[50:65]
	ds_read_b64_tr_b16 v[114:115], v213 offset:36864
	ds_read_b64_tr_b16 v[116:117], v213 offset:37376
	v_add_f32_e32 v66, v120, v66
	v_add_f32_e32 v66, v121, v66
	v_add_f32_e32 v66, v122, v66
	v_add_f32_e32 v146, v123, v66
	s_waitcnt lgkmcnt(6)
	v_mfma_f32_32x32x16_bf16 v[66:81], v[134:137], v[166:169], v[50:65]
	v_cvt_pk_bf16_f32 v160, v118, v119
	v_cvt_pk_bf16_f32 v161, v120, v121
	ds_read_b64_tr_b16 v[118:119], v213 offset:33792
	ds_read_b64_tr_b16 v[120:121], v213 offset:34304
	v_add_f32_e32 v134, v124, v146
	v_add_f32_e32 v134, v125, v134
	v_add_f32_e32 v134, v126, v134
	s_waitcnt lgkmcnt(7)
	v_mfma_f32_32x32x16_bf16 v[98:113], v[138:141], v[162:165], v[98:113]
	v_add_f32_e32 v138, v127, v134
	v_cvt_pk_bf16_f32 v154, v122, v123
	v_cvt_pk_bf16_f32 v155, v124, v125
	ds_read_b64_tr_b16 v[134:135], v213 offset:37888
	ds_read_b64_tr_b16 v[136:137], v213 offset:38400
	s_waitcnt lgkmcnt(8)
	v_mfma_f32_32x32x16_bf16 v[66:81], v[142:145], v[162:165], v[66:81]
	v_add_f32_e32 v122, v128, v138
	v_add_f32_e32 v122, v129, v122
	v_add_f32_e32 v122, v82, v122
	v_add_f32_e32 v122, v83, v122
	v_cvt_pk_bf16_f32 v156, v126, v127
	v_cvt_pk_bf16_f32 v157, v128, v129
	ds_read_b64_tr_b16 v[124:125], v213 offset:34816
	ds_read_b64_tr_b16 v[126:127], v213 offset:35328
	v_add_f32_e32 v122, v84, v122
	v_add_f32_e32 v122, v85, v122
	v_add_f32_e32 v122, v86, v122
	v_add_f32_e32 v122, v87, v122
	v_cvt_pk_bf16_f32 v150, v82, v83
	v_cvt_pk_bf16_f32 v151, v84, v85
	ds_read_b64_tr_b16 v[82:83], v213 offset:38912
	ds_read_b64_tr_b16 v[84:85], v213 offset:39424
	v_add_f32_e32 v122, v88, v122
	v_add_f32_e32 v122, v89, v122
	v_add_f32_e32 v122, v90, v122
	v_add_f32_e32 v122, v91, v122
	v_cvt_pk_bf16_f32 v152, v86, v87
	v_cvt_pk_bf16_f32 v153, v88, v89
	ds_read_b64_tr_b16 v[86:87], v213 offset:35840
	ds_read_b64_tr_b16 v[88:89], v213 offset:36352
	v_add_f32_e32 v122, v92, v122
	v_add_f32_e32 v122, v93, v122
	v_add_f32_e32 v122, v94, v122
	v_add_f32_e32 v122, v95, v122
	v_cvt_pk_bf16_f32 v146, v90, v91
	v_cvt_pk_bf16_f32 v147, v92, v93
	ds_read_b64_tr_b16 v[90:91], v213 offset:39936
	ds_read_b64_tr_b16 v[92:93], v213 offset:40448
	v_add_f32_e32 v122, v96, v122
	v_add_f32_e32 v122, v97, v122
	v_add_f32_e32 v122, 0, v122
	v_cvt_pk_bf16_f32 v148, v94, v95
	v_cvt_pk_bf16_f32 v149, v96, v97
	v_lshl_add_u64 v[94:95], v[172:173], 0, s[26:27]
	s_mov_b32 s48, m0
	s_mov_b32 m0, s80
	s_nop 0
	global_load_lds_dwordx4 v[94:95], off
	s_mov_b32 m0, s48
	v_add_f32_e32 v122, v174, v122
	s_waitcnt lgkmcnt(14)
	v_mfma_f32_32x32x16_bf16 v[18:33], v[158:161], v[130:133], v[18:33]
	v_exp_f32_e32 v98, v98
	v_exp_f32_e32 v99, v99
	v_exp_f32_e32 v100, v100
	v_exp_f32_e32 v101, v101
	s_waitcnt lgkmcnt(12)
	v_mfma_f32_32x32x16_bf16 v[34:49], v[158:161], v[114:117], v[34:49]
	v_exp_f32_e32 v102, v102
	v_exp_f32_e32 v103, v103
	v_exp_f32_e32 v104, v104
	v_exp_f32_e32 v105, v105
	ds_read_b128 v[128:131], v214
	ds_read_b128 v[138:141], v214 offset:512
	s_waitcnt lgkmcnt(12)
	v_mfma_f32_32x32x16_bf16 v[18:33], v[154:157], v[118:121], v[18:33]
	v_exp_f32_e32 v106, v106
	v_exp_f32_e32 v107, v107
	v_exp_f32_e32 v108, v108
	v_exp_f32_e32 v109, v109
	ds_read_b128 v[142:145], v214 offset:2048
	ds_read_b128 v[172:175], v214 offset:2560
	s_waitcnt lgkmcnt(12)
	v_mfma_f32_32x32x16_bf16 v[34:49], v[154:157], v[134:137], v[34:49]
	v_exp_f32_e32 v110, v110
	v_exp_f32_e32 v111, v111
	v_exp_f32_e32 v112, v112
	v_exp_f32_e32 v113, v113
	s_waitcnt lgkmcnt(10)
	v_mfma_f32_32x32x16_bf16 v[18:33], v[150:153], v[124:127], v[18:33]
	v_exp_f32_e32 v66, v66
	v_exp_f32_e32 v67, v67
	v_exp_f32_e32 v68, v68
	v_exp_f32_e32 v69, v69
	s_waitcnt lgkmcnt(8)
	v_mfma_f32_32x32x16_bf16 v[34:49], v[150:153], v[82:85], v[34:49]
	v_exp_f32_e32 v70, v70
	v_exp_f32_e32 v71, v71
	v_exp_f32_e32 v72, v72
	v_exp_f32_e32 v73, v73
	s_waitcnt lgkmcnt(6)
	v_mfma_f32_32x32x16_bf16 v[18:33], v[146:149], v[86:89], v[18:33]
	v_exp_f32_e32 v74, v74
	v_exp_f32_e32 v75, v75
	v_exp_f32_e32 v76, v76
	v_exp_f32_e32 v77, v77
	s_waitcnt lgkmcnt(4)
	v_mfma_f32_32x32x16_bf16 v[34:49], v[146:149], v[90:93], v[34:49]
	v_exp_f32_e32 v78, v78
	v_exp_f32_e32 v79, v79
	v_exp_f32_e32 v80, v80
	v_exp_f32_e32 v81, v81
	s_waitcnt vmcnt(0) lgkmcnt(0)
	s_barrier
; #define SBAR() __builtin_amdgcn_sched_barrier(0)
;   #define RESC() do{ if(!FIXREF&&resc){ asm volatile("s_waitcnt lgkmcnt(0)":::"memory"); \
;       _Pragma("unroll") for(int d_=0;d_<2;++d_) _Pragma("unroll") for(int r=0;r<16;++r)o[d_][r]*=wsf[crow(r,hi)]; } }while(0)
;   #define PKW(P,B) cvtpk_s(P[B],P[B+1])
; template<int THRL,bool FIXREF,bool HALFK> __device__ __forceinline__ void attn_unit(float mref,long rowbase,int q0,const bf16*Qh,int PQ,const bf16*__restrict__ Kh_,int PK,const bf16*__restrict__ Vh_,int PV,bf16*Oh,int PO,const bf16*Gh,int PG,u32x4(&okeep)[4],int omode,float lam,float oml,const float ...
;     ...
;   STEP(pB0,pB1,pA0,pA1,NT-1,false,false,false); RESC();
;   { float sacc=pB0[0]+pB0[1]; _Pragma("unroll") for(int r=2;r<16;++r)sacc+=pB0[r]; _Pragma("unroll") for(int r=0;r<16;++r)sacc+=pB1[r]; l_reg+=sacc;
;     pw0=(u32x4){PKW(pB0,0),PKW(pB0,2),PKW(pB0,4),PKW(pB0,6)};pw1=(u32x4){PKW(pB0,8),PKW(pB0,10),PKW(pB0,12),PKW(pB0,14)};pw2=(u32x4){PKW(pB1,0),PKW(pB1,2),PKW(pB1,4),PKW(pB1,6)};pw3=(u32x4){PKW(pB1,8),PKW(pB1,10),PKW(pB1,12),PKW(pB1,14)};
;     SBAR(); pv(o,vb0+sl_cur,PAF(0),PAF(1),PAF(2),PAF(3)); }
	ds_read_b64_tr_b16 v[114:115], v213 offset:40960
	ds_read_b64_tr_b16 v[116:117], v213 offset:41472
	v_add_f32_e32 v82, v98, v99
	v_add_f32_e32 v82, v100, v82
	v_add_f32_e32 v82, v101, v82
	v_add_f32_e32 v82, v102, v82
	v_add_f32_e32 v118, v103, v82
	v_cvt_pk_bf16_f32 v158, v98, v99
	v_cvt_pk_bf16_f32 v159, v100, v101
	s_waitcnt lgkmcnt(5)
	v_mfma_f32_32x32x16_bf16 v[82:97], v[128:131], v[166:169], v[50:65]
	ds_read_b64_tr_b16 v[98:99], v213 offset:45056
	ds_read_b64_tr_b16 v[100:101], v213 offset:45568
	v_add_f32_e32 v118, v104, v118
	v_add_f32_e32 v118, v105, v118
	v_add_f32_e32 v118, v106, v118
	v_add_f32_e32 v123, v107, v118
	v_cvt_pk_bf16_f32 v160, v102, v103
	v_cvt_pk_bf16_f32 v161, v104, v105
	s_waitcnt lgkmcnt(6)
	v_mfma_f32_32x32x16_bf16 v[50:65], v[138:141], v[166:169], v[50:65]
	ds_read_b64_tr_b16 v[118:119], v213 offset:41984
	ds_read_b64_tr_b16 v[120:121], v213 offset:42496
	v_add_f32_e32 v102, v108, v123
	v_add_f32_e32 v102, v109, v102
	v_add_f32_e32 v102, v110, v102
	v_add_f32_e32 v123, v111, v102
	v_cvt_pk_bf16_f32 v154, v106, v107
	v_cvt_pk_bf16_f32 v155, v108, v109
	s_waitcnt lgkmcnt(7)
	v_mfma_f32_32x32x16_bf16 v[82:97], v[142:145], v[162:165], v[82:97]
	ds_read_b64_tr_b16 v[102:103], v213 offset:46080
	ds_read_b64_tr_b16 v[104:105], v213 offset:46592
	v_add_f32_e32 v106, v112, v123
	v_add_f32_e32 v106, v113, v106
	v_add_f32_e32 v106, v66, v106
	v_add_f32_e32 v123, v67, v106
	v_cvt_pk_bf16_f32 v156, v110, v111
	v_cvt_pk_bf16_f32 v157, v112, v113
	s_waitcnt lgkmcnt(8)
	v_mfma_f32_32x32x16_bf16 v[50:65], v[172:175], v[162:165], v[50:65]
	ds_read_b64_tr_b16 v[106:107], v213 offset:43008
	ds_read_b64_tr_b16 v[108:109], v213 offset:43520
	v_add_f32_e32 v110, v68, v123
	v_add_f32_e32 v110, v69, v110
	v_add_f32_e32 v110, v70, v110
	v_add_f32_e32 v110, v71, v110
	v_cvt_pk_bf16_f32 v150, v66, v67
	v_cvt_pk_bf16_f32 v151, v68, v69
	ds_read_b64_tr_b16 v[66:67], v213 offset:47104
	ds_read_b64_tr_b16 v[68:69], v213 offset:47616
	v_add_f32_e32 v110, v72, v110
	v_add_f32_e32 v110, v73, v110
	v_add_f32_e32 v110, v74, v110
	v_add_f32_e32 v123, v75, v110
	v_cvt_pk_bf16_f32 v152, v70, v71
	v_cvt_pk_bf16_f32 v153, v72, v73
	ds_read_b64_tr_b16 v[110:111], v213 offset:44032
	ds_read_b64_tr_b16 v[112:113], v213 offset:44544
	v_add_f32_e32 v70, v76, v123
	v_add_f32_e32 v70, v77, v70
	v_add_f32_e32 v70, v78, v70
	v_add_f32_e32 v123, v79, v70
	v_cvt_pk_bf16_f32 v146, v74, v75
	v_cvt_pk_bf16_f32 v147, v76, v77
	ds_read_b64_tr_b16 v[70:71], v213 offset:48128
	ds_read_b64_tr_b16 v[72:73], v213 offset:48640
	v_add_f32_e32 v74, v80, v123
	v_add_f32_e32 v74, v81, v74
	v_add_f32_e32 v74, 0, v74
	v_cvt_pk_bf16_f32 v148, v78, v79
	v_cvt_pk_bf16_f32 v149, v80, v81
	v_exp_f32_e32 v82, v82
	v_exp_f32_e32 v83, v83
	v_exp_f32_e32 v84, v84
	v_exp_f32_e32 v85, v85
	s_nop 0
	v_exp_f32_e32 v86, v86
	v_exp_f32_e32 v87, v87
	v_exp_f32_e32 v88, v88
	v_exp_f32_e32 v89, v89
	s_nop 0
	v_exp_f32_e32 v90, v90
	v_exp_f32_e32 v91, v91
	v_exp_f32_e32 v92, v92
	v_exp_f32_e32 v93, v93
	s_nop 0
	v_exp_f32_e32 v94, v94
	v_exp_f32_e32 v95, v95
	v_exp_f32_e32 v96, v96
	v_exp_f32_e32 v97, v97
	v_exp_f32_e32 v50, v50
	v_exp_f32_e32 v51, v51
	v_exp_f32_e32 v52, v52
	v_exp_f32_e32 v53, v53
	s_nop 0
	v_exp_f32_e32 v54, v54
	v_exp_f32_e32 v55, v55
	v_exp_f32_e32 v56, v56
	v_exp_f32_e32 v57, v57
	s_nop 0
	v_exp_f32_e32 v58, v58
	v_exp_f32_e32 v59, v59
	v_exp_f32_e32 v60, v60
	v_exp_f32_e32 v61, v61
	s_nop 0
	v_exp_f32_e32 v62, v62
	v_exp_f32_e32 v63, v63
	v_exp_f32_e32 v64, v64
	v_exp_f32_e32 v65, v65
	s_waitcnt lgkmcnt(14)
	v_mfma_f32_32x32x16_bf16 v[18:33], v[158:161], v[114:117], v[18:33]
	v_add_f32_e32 v75, v82, v83
	v_add_f32_e32 v75, v84, v75
	v_add_f32_e32 v75, v85, v75
	v_add_f32_e32 v75, v86, v75
	v_add_f32_e32 v75, v87, v75
	v_add_f32_e32 v75, v88, v75
	v_add_f32_e32 v75, v89, v75
	s_waitcnt lgkmcnt(12)
	v_mfma_f32_32x32x16_bf16 v[34:49], v[158:161], v[98:101], v[34:49]
	v_add_f32_e32 v75, v90, v75
	v_add_f32_e32 v75, v91, v75
	v_add_f32_e32 v75, v92, v75
	v_add_f32_e32 v75, v93, v75
	v_add_f32_e32 v75, v94, v75
	v_add_f32_e32 v75, v95, v75
	v_add_f32_e32 v75, v96, v75
	s_waitcnt lgkmcnt(10)
	v_mfma_f32_32x32x16_bf16 v[18:33], v[154:157], v[118:121], v[18:33]
	v_add_f32_e32 v75, v97, v75
	v_add_f32_e32 v75, v50, v75
	v_add_f32_e32 v75, v51, v75
	v_add_f32_e32 v75, v52, v75
	v_add_f32_e32 v75, v53, v75
	v_add_f32_e32 v75, v54, v75
	v_add_f32_e32 v75, v55, v75
	s_waitcnt lgkmcnt(8)
	v_mfma_f32_32x32x16_bf16 v[34:49], v[154:157], v[102:105], v[34:49]
	v_add_f32_e32 v75, v56, v75
	v_add_f32_e32 v75, v57, v75
	v_add_f32_e32 v75, v58, v75
	v_add_f32_e32 v75, v59, v75
	v_add_f32_e32 v75, v60, v75
	v_add_f32_e32 v75, v61, v75
	v_add_f32_e32 v75, v62, v75
	s_waitcnt lgkmcnt(6)
	v_mfma_f32_32x32x16_bf16 v[18:33], v[150:153], v[106:109], v[18:33]
	v_add_f32_e32 v75, v63, v75
	v_add_f32_e32 v75, v64, v75
	v_add_f32_e32 v75, v65, v75
	v_add_f32_e32 v74, v122, v74
	v_add_f32_e32 v74, v74, v75
	v_cvt_pk_bf16_f32 v76, v82, v83
	v_cvt_pk_bf16_f32 v77, v84, v85
	s_waitcnt lgkmcnt(4)
	v_mfma_f32_32x32x16_bf16 v[34:49], v[150:153], v[66:69], v[34:49]
	v_cvt_pk_bf16_f32 v78, v86, v87
	v_cvt_pk_bf16_f32 v79, v88, v89
	v_cvt_pk_bf16_f32 v80, v90, v91
	v_cvt_pk_bf16_f32 v81, v92, v93
	v_cvt_pk_bf16_f32 v82, v94, v95
	v_cvt_pk_bf16_f32 v83, v96, v97
	v_cvt_pk_bf16_f32 v50, v50, v51
	s_waitcnt lgkmcnt(2)
	v_mfma_f32_32x32x16_bf16 v[18:33], v[146:149], v[110:113], v[18:33]
	v_cvt_pk_bf16_f32 v51, v52, v53
	v_cvt_pk_bf16_f32 v52, v54, v55
	v_cvt_pk_bf16_f32 v53, v56, v57
	v_cvt_pk_bf16_f32 v54, v58, v59
	v_cvt_pk_bf16_f32 v55, v60, v61
	v_cvt_pk_bf16_f32 v56, v62, v63
	v_cvt_pk_bf16_f32 v57, v64, v65
	s_waitcnt lgkmcnt(0)
; __device__ __forceinline__ int crow(int r,int hi){return (r&3)+8*(r>>2)+4*hi;}
; #define SBAR() __builtin_amdgcn_sched_barrier(0)
; template<int THRL,bool FIXREF,bool HALFK> __device__ __forceinline__ void attn_unit(float mref,long rowbase,int q0,const bf16*Qh,int PQ,const bf16*__restrict__ Kh_,int PK,const bf16*__restrict__ Vh_,int PV,bf16*Oh,int PO,const bf16*Gh,int PG,u32x4(&okeep)[4],int omode,float lam,float oml,const float ...
;     ...
;     SBAR(); pv(o,vb0+sl_cur,PAF(0),PAF(1),PAF(2),PAF(3)); }
;     ...
;   {auto rr=__builtin_amdgcn_permlane32_swap(__float_as_uint(l_reg),__float_as_uint(l_reg),false,false);l_reg=__uint_as_float(rr[0])+__uint_as_float(rr[1]);}
;   if(hi==0)wsf[32+r32]=l_reg;asm volatile("s_waitcnt lgkmcnt(0)":::"memory");
;   float rli[16];
;   #pragma unroll
;   for(int r=0;r<16;++r)rli[r]=__builtin_amdgcn_rcpf(wsf[32+crow(r,hi)]);
;   bf16*Ow=Oh+(rowbase+q0+wid*QBLK)*PO;
;   { bf16*stg=(bf16*)(shm+LDS_OST)+wid*2048;
;     #pragma unroll
;     for(int r=0;r<16;++r){const int orow=crow(r,hi);
;       #pragma unroll
;       for(int d0=0;d0<2;++d0)stg[orow*64+d0*32+r32]=__float2bfloat16(o[d0][r]*rli[r]);}
;     asm volatile("s_waitcnt lgkmcnt(0)":::"memory");
;     if(omode==2){
	v_mfma_f32_32x32x16_bf16 v[34:49], v[146:149], v[70:73], v[34:49]
	ds_read_b64_tr_b16 v[58:59],v0 offset:0
	ds_read_b64_tr_b16 v[60:61],v0 offset:512
	ds_read_b64_tr_b16 v[62:63],v0 offset:1024
	ds_read_b64_tr_b16 v[64:65],v0 offset:1536
	ds_read_b64_tr_b16 v[66:67],v0 offset:2048
	ds_read_b64_tr_b16 v[68:69],v0 offset:2560
	ds_read_b64_tr_b16 v[70:71],v0 offset:3072
	ds_read_b64_tr_b16 v[72:73],v0 offset:3584
	s_waitcnt lgkmcnt(0)
	s_nop 0
	v_mfma_f32_32x32x16_bf16 v[18:33], v[76:79], v[58:61], v[18:33]
	ds_read_b64_tr_b16 v[58:59],v0 offset:4096
	ds_read_b64_tr_b16 v[60:61],v0 offset:4608
	v_mfma_f32_32x32x16_bf16 v[18:33], v[80:83], v[62:65], v[18:33]
	ds_read_b64_tr_b16 v[62:63],v0 offset:5120
	ds_read_b64_tr_b16 v[64:65],v0 offset:5632
	v_mfma_f32_32x32x16_bf16 v[18:33], v[50:53], v[66:69], v[18:33]
	ds_read_b64_tr_b16 v[66:67],v0 offset:6144
	ds_read_b64_tr_b16 v[68:69],v0 offset:6656
	v_mfma_f32_32x32x16_bf16 v[18:33], v[54:57], v[70:73], v[18:33]
	ds_read_b64_tr_b16 v[70:71],v0 offset:7168
	ds_read_b64_tr_b16 v[72:73],v0 offset:7680
	s_waitcnt lgkmcnt(0)
	v_mfma_f32_32x32x16_bf16 v[34:49], v[76:79], v[58:61], v[34:49]
	v_mov_b32_e32 v0, v74
	s_nop 1
	v_permlane32_swap_b32_e32 v74, v0
	v_cmp_gt_u32_e32 vcc, 32, v209
	v_mfma_f32_32x32x16_bf16 v[34:49], v[80:83], v[62:65], v[34:49]
	v_mfma_f32_32x32x16_bf16 v[34:49], v[50:53], v[66:69], v[34:49]
	v_mfma_f32_32x32x16_bf16 v[34:49], v[54:57], v[70:73], v[34:49]
	s_and_saveexec_b64 s[48:49], vcc
	v_lshl_add_u32 v50, v171, 2, s20
	v_add_f32_e32 v0, v74, v0
	ds_write_b32 v50, v0 offset:49280
	s_or_b64 exec, exec, s[48:49]
	s_waitcnt lgkmcnt(0)
	v_lshl_add_u32 v0, v212, 4, s20
	ds_read_b128 v[50:53], v0 offset:49280
	ds_read_b128 v[54:57], v0 offset:49312
	s_lshl_b32 s20, s79, 12
	s_add_i32 s20, s20, 0
	v_lshlrev_b32_e32 v66, 1, v171
	s_waitcnt lgkmcnt(1)
	v_rcp_f32_e32 v58, v50
	v_rcp_f32_e32 v59, v51
	v_rcp_f32_e32 v60, v52
	v_rcp_f32_e32 v61, v53
	s_waitcnt lgkmcnt(0)
	v_rcp_f32_e32 v62, v54
	ds_read_b128 v[50:53], v0 offset:49344
	v_rcp_f32_e32 v63, v55
	v_rcp_f32_e32 v64, v56
	v_rcp_f32_e32 v65, v57
	ds_read_b128 v[54:57], v0 offset:49376
	s_waitcnt lgkmcnt(1)
	v_rcp_f32_e32 v0, v50
	v_rcp_f32_e32 v50, v51
	v_rcp_f32_e32 v51, v52
	v_rcp_f32_e32 v52, v53
	s_waitcnt lgkmcnt(0)
	v_rcp_f32_e32 v53, v54
	v_rcp_f32_e32 v54, v55
	v_rcp_f32_e32 v55, v56
	v_rcp_f32_e32 v56, v57
	v_lshlrev_b32_e32 v57, 9, v212
	v_mul_f32_e32 v18, v18, v58
	v_add3_u32 v57, s20, v57, v66
	v_cvt_pk_bf16_f32 v18, v18, s0
	ds_write_b16 v57, v18 offset:51200
	v_mul_f32_e32 v18, v34, v58
	v_cvt_pk_bf16_f32 v18, v18, s0
	ds_write_b16 v57, v18 offset:51264
	v_mul_f32_e32 v18, v19, v59
	v_cvt_pk_bf16_f32 v18, v18, s0
	ds_write_b16 v57, v18 offset:51328
	v_mul_f32_e32 v18, v35, v59
	v_cvt_pk_bf16_f32 v18, v18, s0
	ds_write_b16 v57, v18 offset:51392
	v_mul_f32_e32 v18, v20, v60
	v_cvt_pk_bf16_f32 v18, v18, s0
	ds_write_b16 v57, v18 offset:51456
	v_mul_f32_e32 v18, v36, v60
	v_cvt_pk_bf16_f32 v18, v18, s0
	ds_write_b16 v57, v18 offset:51520
	v_mul_f32_e32 v18, v21, v61
	v_cvt_pk_bf16_f32 v18, v18, s0
	ds_write_b16 v57, v18 offset:51584
	v_mul_f32_e32 v18, v37, v61
	v_cvt_pk_bf16_f32 v18, v18, s0
	ds_write_b16 v57, v18 offset:51648
	v_mul_f32_e32 v18, v22, v62
	v_cvt_pk_bf16_f32 v18, v18, s0
	ds_write_b16 v57, v18 offset:52224
	v_mul_f32_e32 v18, v38, v62
	v_cvt_pk_bf16_f32 v18, v18, s0
	ds_write_b16 v57, v18 offset:52288
	v_mul_f32_e32 v18, v23, v63
	v_cvt_pk_bf16_f32 v18, v18, s0
	ds_write_b16 v57, v18 offset:52352
	v_mul_f32_e32 v18, v39, v63
	v_cvt_pk_bf16_f32 v18, v18, s0
	ds_write_b16 v57, v18 offset:52416
	v_mul_f32_e32 v18, v24, v64
	v_cvt_pk_bf16_f32 v18, v18, s0
	ds_write_b16 v57, v18 offset:52480
	v_mul_f32_e32 v18, v40, v64
	v_cvt_pk_bf16_f32 v18, v18, s0
	ds_write_b16 v57, v18 offset:52544
	v_mul_f32_e32 v18, v25, v65
	v_cvt_pk_bf16_f32 v18, v18, s0
	ds_write_b16 v57, v18 offset:52608
	v_mul_f32_e32 v18, v41, v65
	v_cvt_pk_bf16_f32 v18, v18, s0
	ds_write_b16 v57, v18 offset:52672
	v_mul_f32_e32 v18, v26, v0
	v_mul_f32_e32 v0, v42, v0
	v_cvt_pk_bf16_f32 v0, v0, s0
	ds_write_b16 v57, v0 offset:53312
	v_mul_f32_e32 v0, v27, v50
	v_cvt_pk_bf16_f32 v0, v0, s0
	ds_write_b16 v57, v0 offset:53376
	v_mul_f32_e32 v0, v43, v50
	v_cvt_pk_bf16_f32 v0, v0, s0
	ds_write_b16 v57, v0 offset:53440
	v_mul_f32_e32 v0, v28, v51
	v_cvt_pk_bf16_f32 v0, v0, s0
	ds_write_b16 v57, v0 offset:53504
	v_mul_f32_e32 v0, v44, v51
	v_cvt_pk_bf16_f32 v0, v0, s0
	ds_write_b16 v57, v0 offset:53568
	v_mul_f32_e32 v0, v29, v52
	v_cvt_pk_bf16_f32 v0, v0, s0
	ds_write_b16 v57, v0 offset:53632
	v_mul_f32_e32 v0, v45, v52
	v_cvt_pk_bf16_f32 v0, v0, s0
	ds_write_b16 v57, v0 offset:53696
	v_mul_f32_e32 v0, v30, v53
	v_cvt_pk_bf16_f32 v0, v0, s0
	ds_write_b16 v57, v0 offset:54272
	v_mul_f32_e32 v0, v46, v53
	v_cvt_pk_bf16_f32 v0, v0, s0
	ds_write_b16 v57, v0 offset:54336
	v_mul_f32_e32 v0, v31, v54
	v_cvt_pk_bf16_f32 v0, v0, s0
	ds_write_b16 v57, v0 offset:54400
	v_mul_f32_e32 v0, v47, v54
	v_cvt_pk_bf16_f32 v0, v0, s0
	ds_write_b16 v57, v0 offset:54464
	v_mul_f32_e32 v0, v32, v55
	v_cvt_pk_bf16_f32 v0, v0, s0
	ds_write_b16 v57, v0 offset:54528
	v_mul_f32_e32 v0, v48, v55
	v_cvt_pk_bf16_f32 v0, v0, s0
	ds_write_b16 v57, v0 offset:54592
	v_mul_f32_e32 v0, v33, v56
	v_cvt_pk_bf16_f32 v0, v0, s0
	ds_write_b16 v57, v0 offset:54656
	v_mul_f32_e32 v0, v49, v56
	v_cvt_pk_bf16_f32 v18, v18, s0
	v_cvt_pk_bf16_f32 v0, v0, s0
	ds_write_b16 v57, v18 offset:53248
	ds_write_b16 v57, v0 offset:54720
	s_lshl_b64 s[46:47], s[46:47], 11
	s_waitcnt lgkmcnt(0)
	s_add_u32 s46, s69, s46
	s_addc_u32 s47, s70, s47
	s_mov_b64 s[48:49], -1
	s_and_b64 vcc, exec, s[42:43]
	s_cbranch_vccz .LBB0_470
; __device__ __forceinline__ unsigned cvtpk_s(float lo,float hi){f32x2_t v={lo,hi};bf16x2_t b=__builtin_convertvector(v,bf16x2_t);return __builtin_bit_cast(unsigned,b);}
; template<int THRL,bool FIXREF,bool HALFK> __device__ __forceinline__ void attn_unit(float mref,long rowbase,int q0,const bf16*Qh,int PQ,const bf16*__restrict__ Kh_,int PK,const bf16*__restrict__ Vh_,int PV,bf16*Oh,int PO,const bf16*Gh,int PG,u32x4(&okeep)[4],int omode,float lam,float oml,const float ...
;     ...
;     else if(Gh){
;       u32x4 gv[4]; const char*gst=shm+LDS_GST+wid*4096+lane*16;
;       #pragma unroll
;       for(int i=0;i<4;++i) gv[i]=*(const u32x4*)(gst+i*1024);
;       #pragma unroll
;       for(int i=0;i<4;++i){const int row=i*8+(lane>>3),ch=lane&7; u32x4 v=*(const u32x4*)(stg+row*64+ch*8);
;         #pragma unroll
;         for(int k=0;k<4;++k){ const float g0=__uint_as_float(gv[i][k]<<16),g1=__uint_as_float(gv[i][k]&0xffff0000u),o0=__uint_as_float(v[k]<<16),o1=__uint_as_float(v[k]&0xffff0000u);
;           v[k]=cvtpk_s(o0*g0*__builtin_amdgcn_rcpf(1.f+__builtin_amdgcn_exp2f(-1.4426950408889634f*g0)),o1*g1*__builtin_amdgcn_rcpf(1.f+__builtin_amdgcn_exp2f(-1.4426950408889634f*g1))); }
;         ATTN_STORE16(Ow+(long)row*PO+ch*8,v);} }
	s_mov_b64 s[42:43], -1
	s_and_b64 vcc, exec, s[40:41]
	s_cbranch_vccz .LBB0_467
	v_lshl_add_u32 v0, v209, 4, s20
	v_add_u32_e32 v0, 0x14800, v0
	ds_read_b128 v[30:33], v0
	ds_read_b128 v[26:29], v0 offset:1024
	ds_read_b128 v[22:25], v0 offset:2048
	ds_read_b128 v[18:21], v0 offset:3072
	v_lshlrev_b32_e32 v0, 1, v211
	v_and_b32_e32 v0, 0x70, v0
	v_add_u32_e32 v36, s20, v0
	v_lshl_add_u64 v[34:35], s[46:47], 0, v[0:1]
	v_lshl_add_u32 v0, v208, 7, v36
	s_waitcnt lgkmcnt(3)
	v_lshlrev_b32_e32 v44, 16, v30
	ds_read_b128 v[38:41], v0 offset:51200
	v_mul_f32_e32 v0, 0xbfb8aa3b, v44
	v_exp_f32_e32 v0, v0
	v_and_b32_e32 v43, 0xffff0000, v30
	s_mov_b64 s[42:43], 0
	s_waitcnt lgkmcnt(0)
	v_lshlrev_b32_e32 v42, 16, v38
	v_add_f32_e32 v0, 1.0, v0
	v_rcp_f32_e32 v46, v0
	v_mul_f32_e32 v0, 0xbfb8aa3b, v43
	v_exp_f32_e32 v0, v0
	v_and_b32_e32 v45, 0xffff0000, v38
	v_lshlrev_b32_e32 v38, 16, v31
	v_pk_mul_f32 v[44:45], v[42:43], v[44:45]
	v_add_f32_e32 v0, 1.0, v0
	v_rcp_f32_e32 v47, v0
	v_mul_f32_e32 v0, 0xbfb8aa3b, v38
	v_exp_f32_e32 v0, v0
	v_pk_mul_f32 v[42:43], v[46:47], v[44:45]
	s_nop 0
	v_cvt_pk_bf16_f32 v30, v42, v43
	v_and_b32_e32 v43, 0xffff0000, v31
	v_add_f32_e32 v0, 1.0, v0
	v_rcp_f32_e32 v44, v0
	v_mul_f32_e32 v0, 0xbfb8aa3b, v43
	v_exp_f32_e32 v0, v0
	v_lshlrev_b32_e32 v42, 16, v39
	v_and_b32_e32 v39, 0xffff0000, v39
	v_pk_mul_f32 v[38:39], v[42:43], v[38:39]
	v_add_f32_e32 v0, 1.0, v0
	v_lshlrev_b32_e32 v42, 16, v32
	v_rcp_f32_e32 v45, v0
	v_mul_f32_e32 v0, 0xbfb8aa3b, v42
	v_exp_f32_e32 v0, v0
	v_and_b32_e32 v43, 0xffff0000, v40
	v_pk_mul_f32 v[38:39], v[44:45], v[38:39]
	v_add_f32_e32 v0, 1.0, v0
	v_cvt_pk_bf16_f32 v31, v38, v39
	v_and_b32_e32 v39, 0xffff0000, v32
	v_rcp_f32_e32 v44, v0
	v_mul_f32_e32 v0, 0xbfb8aa3b, v39
	v_exp_f32_e32 v0, v0
	v_lshlrev_b32_e32 v38, 16, v40
	v_lshlrev_b32_e32 v40, 16, v33
	v_pk_mul_f32 v[42:43], v[38:39], v[42:43]
	v_add_f32_e32 v0, 1.0, v0
	v_rcp_f32_e32 v45, v0
	v_mul_f32_e32 v0, 0xbfb8aa3b, v40
	v_exp_f32_e32 v0, v0
	v_pk_mul_f32 v[38:39], v[44:45], v[42:43]
	s_nop 0
	v_cvt_pk_bf16_f32 v32, v38, v39
	v_and_b32_e32 v39, 0xffff0000, v33
	v_add_f32_e32 v0, 1.0, v0
	v_rcp_f32_e32 v42, v0
	v_mul_f32_e32 v0, 0xbfb8aa3b, v39
	v_exp_f32_e32 v0, v0
	v_lshlrev_b32_e32 v38, 16, v41
	v_and_b32_e32 v41, 0xffff0000, v41
	v_pk_mul_f32 v[40:41], v[38:39], v[40:41]
	v_add_f32_e32 v0, 1.0, v0
	v_rcp_f32_e32 v43, v0
	v_lshlrev_b32_e32 v0, 11, v208
	v_pk_mul_f32 v[38:39], v[42:43], v[40:41]
	s_nop 0
	v_cvt_pk_bf16_f32 v33, v38, v39
	v_lshl_add_u64 v[38:39], v[34:35], 0, v[0:1]
	v_lshlrev_b32_e32 v40, 16, v26
	global_store_dwordx4 v[38:39], v[30:33], off
	v_and_b32_e32 v39, 0xffff0000, v26
	v_mul_f32_e32 v26, 0xbfb8aa3b, v40
	v_exp_f32_e32 v26, v26
	v_or_b32_e32 v0, 8, v208
	v_lshl_add_u32 v30, v0, 7, v36
	ds_read_b128 v[30:33], v30 offset:51200
	v_add_f32_e32 v26, 1.0, v26
	v_rcp_f32_e32 v42, v26
	v_mul_f32_e32 v26, 0xbfb8aa3b, v39
	v_exp_f32_e32 v26, v26
	s_waitcnt lgkmcnt(0)
	v_lshlrev_b32_e32 v38, 16, v30
	v_and_b32_e32 v41, 0xffff0000, v30
	v_pk_mul_f32 v[40:41], v[38:39], v[40:41]
	v_add_f32_e32 v26, 1.0, v26
	v_rcp_f32_e32 v43, v26
	v_lshlrev_b32_e32 v30, 16, v27
	v_lshlrev_b32_e32 v0, 11, v0
	v_pk_mul_f32 v[38:39], v[42:43], v[40:41]
	s_nop 0
	v_cvt_pk_bf16_f32 v26, v38, v39
	v_and_b32_e32 v39, 0xffff0000, v27
	v_mul_f32_e32 v27, 0xbfb8aa3b, v30
	v_exp_f32_e32 v27, v27
	v_lshlrev_b32_e32 v38, 16, v31
	v_and_b32_e32 v31, 0xffff0000, v31
	v_pk_mul_f32 v[30:31], v[38:39], v[30:31]
	v_add_f32_e32 v27, 1.0, v27
	v_rcp_f32_e32 v40, v27
	v_mul_f32_e32 v27, 0xbfb8aa3b, v39
	v_exp_f32_e32 v27, v27
	v_lshlrev_b32_e32 v38, 16, v28
	v_and_b32_e32 v39, 0xffff0000, v32
	v_add_f32_e32 v27, 1.0, v27
	v_rcp_f32_e32 v41, v27
	s_nop 0
	v_pk_mul_f32 v[30:31], v[40:41], v[30:31]
	s_nop 0
	v_cvt_pk_bf16_f32 v27, v30, v31
	v_and_b32_e32 v31, 0xffff0000, v28
	v_mul_f32_e32 v28, 0xbfb8aa3b, v38
	v_exp_f32_e32 v28, v28
	v_lshlrev_b32_e32 v30, 16, v32
	v_pk_mul_f32 v[38:39], v[30:31], v[38:39]
	v_lshlrev_b32_e32 v32, 16, v29
	v_add_f32_e32 v28, 1.0, v28
	v_rcp_f32_e32 v40, v28
	v_mul_f32_e32 v28, 0xbfb8aa3b, v31
	v_exp_f32_e32 v28, v28
	s_nop 0
	v_add_f32_e32 v28, 1.0, v28
	v_rcp_f32_e32 v41, v28
	s_nop 0
	v_pk_mul_f32 v[30:31], v[40:41], v[38:39]
	s_nop 0
	v_cvt_pk_bf16_f32 v28, v30, v31
	v_and_b32_e32 v31, 0xffff0000, v29
	v_mul_f32_e32 v29, 0xbfb8aa3b, v32
	v_exp_f32_e32 v29, v29
	v_lshlrev_b32_e32 v30, 16, v33
	v_and_b32_e32 v33, 0xffff0000, v33
	v_pk_mul_f32 v[32:33], v[30:31], v[32:33]
	v_add_f32_e32 v29, 1.0, v29
	v_rcp_f32_e32 v38, v29
	v_mul_f32_e32 v29, 0xbfb8aa3b, v31
	v_exp_f32_e32 v29, v29
	s_nop 0
	v_add_f32_e32 v29, 1.0, v29
	v_rcp_f32_e32 v39, v29
	s_nop 0
	v_pk_mul_f32 v[30:31], v[38:39], v[32:33]
	s_nop 0
	v_cvt_pk_bf16_f32 v29, v30, v31
	v_lshl_add_u64 v[30:31], v[34:35], 0, v[0:1]
	v_lshlrev_b32_e32 v32, 16, v22
	global_store_dwordx4 v[30:31], v[26:29], off
	v_and_b32_e32 v31, 0xffff0000, v22
	v_mul_f32_e32 v22, 0xbfb8aa3b, v32
	v_exp_f32_e32 v22, v22
	v_or_b32_e32 v0, 16, v208
	v_lshl_add_u32 v26, v0, 7, v36
	ds_read_b128 v[26:29], v26 offset:51200
	v_add_f32_e32 v22, 1.0, v22
	v_rcp_f32_e32 v38, v22
	v_mul_f32_e32 v22, 0xbfb8aa3b, v31
	v_exp_f32_e32 v22, v22
	s_waitcnt lgkmcnt(0)
; __device__ __forceinline__ unsigned cvtpk_s(float lo,float hi){f32x2_t v={lo,hi};bf16x2_t b=__builtin_convertvector(v,bf16x2_t);return __builtin_bit_cast(unsigned,b);}
; template<int THRL,bool FIXREF,bool HALFK> __device__ __forceinline__ void attn_unit(float mref,long rowbase,int q0,const bf16*Qh,int PQ,const bf16*__restrict__ Kh_,int PK,const bf16*__restrict__ Vh_,int PV,bf16*Oh,int PO,const bf16*Gh,int PG,u32x4(&okeep)[4],int omode,float lam,float oml,const float ...
;     ...
;     else if(Gh){
;       u32x4 gv[4]; const char*gst=shm+LDS_GST+wid*4096+lane*16;
;       #pragma unroll
;       for(int i=0;i<4;++i) gv[i]=*(const u32x4*)(gst+i*1024);
;       #pragma unroll
;       for(int i=0;i<4;++i){const int row=i*8+(lane>>3),ch=lane&7; u32x4 v=*(const u32x4*)(stg+row*64+ch*8);
;         #pragma unroll
;         for(int k=0;k<4;++k){ const float g0=__uint_as_float(gv[i][k]<<16),g1=__uint_as_float(gv[i][k]&0xffff0000u),o0=__uint_as_float(v[k]<<16),o1=__uint_as_float(v[k]&0xffff0000u);
;           v[k]=cvtpk_s(o0*g0*__builtin_amdgcn_rcpf(1.f+__builtin_amdgcn_exp2f(-1.4426950408889634f*g0)),o1*g1*__builtin_amdgcn_rcpf(1.f+__builtin_amdgcn_exp2f(-1.4426950408889634f*g1))); }
;         ATTN_STORE16(Ow+(long)row*PO+ch*8,v);} }
	v_lshlrev_b32_e32 v30, 16, v26
	v_and_b32_e32 v33, 0xffff0000, v26
	v_pk_mul_f32 v[32:33], v[30:31], v[32:33]
	v_add_f32_e32 v22, 1.0, v22
	v_rcp_f32_e32 v39, v22
	v_lshlrev_b32_e32 v26, 16, v23
	v_lshlrev_b32_e32 v0, 11, v0
	v_pk_mul_f32 v[30:31], v[38:39], v[32:33]
	s_nop 0
	v_cvt_pk_bf16_f32 v22, v30, v31
	v_and_b32_e32 v31, 0xffff0000, v23
	v_mul_f32_e32 v23, 0xbfb8aa3b, v26
	v_exp_f32_e32 v23, v23
	v_lshlrev_b32_e32 v30, 16, v27
	v_and_b32_e32 v27, 0xffff0000, v27
	v_pk_mul_f32 v[26:27], v[30:31], v[26:27]
	v_add_f32_e32 v23, 1.0, v23
	v_rcp_f32_e32 v32, v23
	v_mul_f32_e32 v23, 0xbfb8aa3b, v31
	v_exp_f32_e32 v23, v23
	v_lshlrev_b32_e32 v30, 16, v24
	v_and_b32_e32 v31, 0xffff0000, v28
	v_add_f32_e32 v23, 1.0, v23
	v_rcp_f32_e32 v33, v23
	s_nop 0
	v_pk_mul_f32 v[26:27], v[32:33], v[26:27]
	s_nop 0
	v_cvt_pk_bf16_f32 v23, v26, v27
	v_and_b32_e32 v27, 0xffff0000, v24
	v_mul_f32_e32 v24, 0xbfb8aa3b, v30
	v_exp_f32_e32 v24, v24
	v_lshlrev_b32_e32 v26, 16, v28
	v_pk_mul_f32 v[30:31], v[26:27], v[30:31]
	v_lshlrev_b32_e32 v28, 16, v25
	v_add_f32_e32 v24, 1.0, v24
	v_rcp_f32_e32 v32, v24
	v_mul_f32_e32 v24, 0xbfb8aa3b, v27
	v_exp_f32_e32 v24, v24
	s_nop 0
	v_add_f32_e32 v24, 1.0, v24
	v_rcp_f32_e32 v33, v24
	s_nop 0
	v_pk_mul_f32 v[26:27], v[32:33], v[30:31]
	s_nop 0
	v_cvt_pk_bf16_f32 v24, v26, v27
	v_and_b32_e32 v27, 0xffff0000, v25
	v_mul_f32_e32 v25, 0xbfb8aa3b, v28
	v_exp_f32_e32 v25, v25
	v_lshlrev_b32_e32 v26, 16, v29
	v_and_b32_e32 v29, 0xffff0000, v29
	v_pk_mul_f32 v[28:29], v[26:27], v[28:29]
	v_add_f32_e32 v25, 1.0, v25
	v_rcp_f32_e32 v30, v25
	v_mul_f32_e32 v25, 0xbfb8aa3b, v27
	v_exp_f32_e32 v25, v25
	s_nop 0
	v_add_f32_e32 v25, 1.0, v25
	v_rcp_f32_e32 v31, v25
	s_nop 0
	v_pk_mul_f32 v[26:27], v[30:31], v[28:29]
	s_nop 0
	v_cvt_pk_bf16_f32 v25, v26, v27
	v_lshl_add_u64 v[26:27], v[34:35], 0, v[0:1]
	v_lshlrev_b32_e32 v28, 16, v18
	global_store_dwordx4 v[26:27], v[22:25], off
	v_and_b32_e32 v27, 0xffff0000, v18
	v_mul_f32_e32 v18, 0xbfb8aa3b, v28
	v_exp_f32_e32 v18, v18
	v_or_b32_e32 v0, 24, v208
	v_lshl_add_u32 v22, v0, 7, v36
	ds_read_b128 v[22:25], v22 offset:51200
	v_add_f32_e32 v18, 1.0, v18
	v_rcp_f32_e32 v30, v18
	v_mul_f32_e32 v18, 0xbfb8aa3b, v27
	v_exp_f32_e32 v18, v18
	s_waitcnt lgkmcnt(0)
	v_lshlrev_b32_e32 v26, 16, v22
	v_and_b32_e32 v29, 0xffff0000, v22
	v_pk_mul_f32 v[28:29], v[26:27], v[28:29]
	v_add_f32_e32 v18, 1.0, v18
	v_rcp_f32_e32 v31, v18
	v_lshlrev_b32_e32 v22, 16, v19
	v_lshlrev_b32_e32 v0, 11, v0
	v_pk_mul_f32 v[26:27], v[30:31], v[28:29]
	s_nop 0
	v_cvt_pk_bf16_f32 v18, v26, v27
	v_and_b32_e32 v27, 0xffff0000, v19
	v_mul_f32_e32 v19, 0xbfb8aa3b, v22
	v_exp_f32_e32 v19, v19
	v_lshlrev_b32_e32 v26, 16, v23
	v_and_b32_e32 v23, 0xffff0000, v23
	v_pk_mul_f32 v[22:23], v[26:27], v[22:23]
	v_add_f32_e32 v19, 1.0, v19
	v_rcp_f32_e32 v28, v19
	v_mul_f32_e32 v19, 0xbfb8aa3b, v27
	v_exp_f32_e32 v19, v19
	v_lshlrev_b32_e32 v26, 16, v20
	v_and_b32_e32 v27, 0xffff0000, v24
	v_add_f32_e32 v19, 1.0, v19
	v_rcp_f32_e32 v29, v19
	s_nop 0
	v_pk_mul_f32 v[22:23], v[28:29], v[22:23]
	s_nop 0
	v_cvt_pk_bf16_f32 v19, v22, v23
	v_and_b32_e32 v23, 0xffff0000, v20
	v_mul_f32_e32 v20, 0xbfb8aa3b, v26
	v_exp_f32_e32 v20, v20
	v_lshlrev_b32_e32 v22, 16, v24
	v_pk_mul_f32 v[26:27], v[22:23], v[26:27]
	v_lshlrev_b32_e32 v24, 16, v21
	v_add_f32_e32 v20, 1.0, v20
	v_rcp_f32_e32 v28, v20
	v_mul_f32_e32 v20, 0xbfb8aa3b, v23
	v_exp_f32_e32 v20, v20
	s_nop 0
	v_add_f32_e32 v20, 1.0, v20
	v_rcp_f32_e32 v29, v20
	s_nop 0
	v_pk_mul_f32 v[22:23], v[28:29], v[26:27]
	s_nop 0
	v_cvt_pk_bf16_f32 v20, v22, v23
	v_and_b32_e32 v23, 0xffff0000, v21
	v_mul_f32_e32 v21, 0xbfb8aa3b, v24
	v_exp_f32_e32 v21, v21
	v_lshlrev_b32_e32 v22, 16, v25
	v_and_b32_e32 v25, 0xffff0000, v25
	v_pk_mul_f32 v[24:25], v[22:23], v[24:25]
	v_add_f32_e32 v21, 1.0, v21
	v_rcp_f32_e32 v26, v21
	v_mul_f32_e32 v21, 0xbfb8aa3b, v23
	v_exp_f32_e32 v21, v21
	s_nop 0
	v_add_f32_e32 v21, 1.0, v21
	v_rcp_f32_e32 v27, v21
	s_nop 0
	v_pk_mul_f32 v[22:23], v[26:27], v[24:25]
	s_nop 0
	v_cvt_pk_bf16_f32 v21, v22, v23
	v_lshl_add_u64 v[22:23], v[34:35], 0, v[0:1]
	global_store_dwordx4 v[22:23], v[18:21], off

; __device__ __forceinline__ void phase_attn(int l, char* lds_generic, int vcu, int G) {
;     ...
;         for (int du = vcu; du < 32 * 16; du += G)
;             for (int mp = 0; mp < 2; ++mp) { ATTN_C_ARGS
;                 attn_body::attn_unit<8, false, true>(0.f, (long)b * SEQ, qb * 256, Q, 256, K, 256, V, DIN, O, DMODEL, Gt, DIN, okeep, 1 + mp, lam, oml, subln, lds_generic); }
.LBB0_472:
	s_mov_b64 s[12:13], 0xc000
	s_mov_b64 s[38:39], 0x80
	v_readlane_b32 s84, v248, 1
	v_readlane_b32 s88, v247, 53
	v_readlane_b32 s46, v247, 57
	v_readlane_b32 s48, v247, 59
	v_readlane_b32 s76, v246, 1
	v_readlane_b32 s85, v248, 2
	v_readlane_b32 s86, v247, 50
	v_readlane_b32 s73, v247, 52
	v_readlane_b32 s89, v247, 54
	v_readlane_b32 s47, v247, 58
	v_readlane_b32 s49, v247, 60
	s_movk_i32 s75, 0x1000
	v_readlane_b32 s77, v246, 2
	v_readlane_b32 s87, v247, 51
